# v8 + pipelined w_o epilogue + P0 row prefetch + GEMM LDS-DMA saddr form (stacked neutral edits)
# baseline (speedup 1.0000x reference)
; __device__ __forceinline__ unsigned pk2(float a, float b) { f32x2_t v = {a, b}; bf16x2v_t r = __builtin_convertvector(v, bf16x2v_t); return __builtin_bit_cast(unsigned, r); }
; __device__ __forceinline__ void phase0(const Args& a, LAS unsigned char* lds, int gw_, int NGW, int wave, int lane_) {
;     ...
;     { bf16_t* XN = (bf16_t*)(ws + WS_XN);
;       f32x4 g[4];
; #pragma unroll
;       for (int j = 0; j < 4; ++j) g[j] = *(const f32x4*)(a.g_in + 4 * lane + 256 * j);
;       for (int m = gw; m < T; m += NGW) { const float* xr = a.x + (size_t)m * DM + 4 * lane; f32x4 v[4]; float s = 0.f;
; #pragma unroll
;           for (int j = 0; j < 4; ++j) { v[j] = *(const f32x4*)(xr + 256 * j); s += (v[j][0] * v[j][0] + v[j][1] * v[j][1]) + (v[j][2] * v[j][2] + v[j][3] * v[j][3]); }
;           const float rstd = rsqrtf(wave_sum(s) * (1.f / DM) + EPS);
; #pragma unroll
;           for (int j = 0; j < 4; ++j) { const f32x4 o = v[j] * rstd * g[j]; u32x2 w; w.x = pk2(o[0], o[1]); w.y = pk2(o[2], o[3]); *(u32x2*)(XN + (size_t)m * DM + 4 * lane + 256 * j) = w; } } }
.LBB0_91:
	s_or_b64 exec, exec, s[0:1]
	s_cmpk_lt_i32 s84, 0x4000
	s_cselect_b64 s[12:13], -1, 0
	s_and_b64 vcc, exec, s[12:13]
	s_cbranch_vccz .LBB0_94
	v_readlane_b32 s16, v255, 0
	v_lshlrev_b32_e32 v16, 2, v51
	v_readlane_b32 s20, v255, 4
	v_readlane_b32 s21, v255, 5
	v_ashrrev_i32_e32 v17, 31, v16
	v_readlane_b32 s22, v255, 6
	v_readlane_b32 s23, v255, 7
	s_mov_b64 s[8:9], s[20:21]
	v_lshlrev_b64 v[18:19], 2, v[16:17]
	s_mov_b64 s[10:11], s[22:23]
	v_lshl_add_u64 v[20:21], s[10:11], 0, v[18:19]
	global_load_dwordx4 v[0:3], v[20:21], off
	global_load_dwordx4 v[4:7], v[20:21], off offset:1024
	global_load_dwordx4 v[8:11], v[20:21], off offset:2048
	global_load_dwordx4 v[12:15], v[20:21], off offset:3072
	v_mbcnt_lo_u32_b32 v20, -1, 0
	v_mbcnt_hi_u32_b32 v25, -1, v20
	v_and_b32_e32 v20, 64, v25
	s_ashr_i32 s85, s84, 31
	v_add_u32_e32 v26, 64, v20
	v_xor_b32_e32 v20, 1, v25
	s_lshl_b64 s[0:1], s[84:85], 11
	v_cmp_lt_i32_e32 vcc, v20, v26
	v_xor_b32_e32 v21, 2, v25
	s_add_u32 s0, s82, s0
	v_cndmask_b32_e32 v20, v25, v20, vcc
	v_cmp_lt_i32_e32 vcc, v21, v26
	v_xor_b32_e32 v22, 4, v25
	s_addc_u32 s1, s83, s1
	v_readlane_b32 s17, v255, 1
	v_cndmask_b32_e32 v21, v25, v21, vcc
	v_cmp_lt_i32_e32 vcc, v22, v26
	v_xor_b32_e32 v23, 8, v25
	v_lshl_add_u64 v[16:17], v[16:17], 1, s[0:1]
	s_mov_b64 s[0:1], 0x1000000
	s_ashr_i32 s87, s86, 31
	s_mov_b64 s[4:5], s[16:17]
	v_cndmask_b32_e32 v22, v25, v22, vcc
	v_cmp_lt_i32_e32 vcc, v23, v26
	v_xor_b32_e32 v24, 16, v25
	v_lshl_add_u64 v[16:17], v[16:17], 0, s[0:1]
	s_lshl_b64 s[0:1], s[86:87], 11
	s_lshl_b64 s[2:3], s[84:85], 12
	v_cndmask_b32_e32 v23, v25, v23, vcc
	v_cmp_lt_i32_e32 vcc, v24, v26
	v_xor_b32_e32 v27, 32, v25
	s_add_u32 s2, s4, s2
	v_cndmask_b32_e32 v24, v25, v24, vcc
	v_cmp_lt_i32_e32 vcc, v27, v26
	s_addc_u32 s3, s5, s3
	v_lshl_add_u64 v[18:19], s[2:3], 0, v[18:19]
	v_cndmask_b32_e32 v25, v25, v27, vcc
	s_mov_b64 s[2:3], 0xc00
	v_lshlrev_b32_e32 v20, 2, v20
	v_lshlrev_b32_e32 v21, 2, v21
	v_lshlrev_b32_e32 v22, 2, v22
	v_lshlrev_b32_e32 v23, 2, v23
	v_lshlrev_b32_e32 v24, 2, v24
	v_lshlrev_b32_e32 v25, 2, v25
	v_lshl_add_u64 v[18:19], v[18:19], 0, s[2:3]
	s_lshl_b64 s[4:5], s[86:87], 12
	v_mov_b32_e32 v26, 0x358637bd
	s_mov_b32 s2, 0x800000
	s_mov_b32 s3, s84
	v_readlane_b32 s18, v255, 2
	v_readlane_b32 s19, v255, 3
	v_readlane_b32 s24, v255, 8
	v_readlane_b32 s25, v255, 9
	v_readlane_b32 s26, v255, 10
	v_readlane_b32 s27, v255, 11
	v_readlane_b32 s28, v255, 12
	v_readlane_b32 s29, v255, 13
	v_readlane_b32 s30, v255, 14
	v_readlane_b32 s31, v255, 15
	global_load_dwordx4 v[108:111], v[18:19], off offset:-3072 nt
	global_load_dwordx4 v[112:115], v[18:19], off offset:-2048 nt
	global_load_dwordx4 v[116:119], v[18:19], off offset:-1024 nt
	global_load_dwordx4 v[120:123], v[18:19], off nt
	s_waitcnt vmcnt(0)
	s_branch .Lxn_body
.LBB0_93:
	s_waitcnt vmcnt(4)
.Lxn_body:
	v_mov_b32_e32 v28, v108
	v_mov_b32_e32 v29, v109
	v_mov_b32_e32 v30, v110
	v_mov_b32_e32 v31, v111
	v_mov_b32_e32 v32, v112
	v_mov_b32_e32 v33, v113
	v_mov_b32_e32 v34, v114
	v_mov_b32_e32 v35, v115
	v_mov_b32_e32 v36, v116
	v_mov_b32_e32 v37, v117
	v_mov_b32_e32 v38, v118
	v_mov_b32_e32 v39, v119
	v_mov_b32_e32 v40, v120
	v_mov_b32_e32 v41, v121
	v_mov_b32_e32 v42, v122
	v_mov_b32_e32 v43, v123
	s_add_i32 s3, s3, s86
	v_lshl_add_u64 v[18:19], v[18:19], 0, s[4:5]
	s_cmpk_lt_i32 s3, 0x4000
	s_cbranch_scc0 .Lxn_nopref
	global_load_dwordx4 v[108:111], v[18:19], off offset:-3072 nt
	global_load_dwordx4 v[112:115], v[18:19], off offset:-2048 nt
	global_load_dwordx4 v[116:119], v[18:19], off offset:-1024 nt
	global_load_dwordx4 v[120:123], v[18:19], off nt
.Lxn_nopref:
	v_pk_mul_f32 v[44:45], v[30:31], v[30:31]
	v_pk_mul_f32 v[46:47], v[28:29], v[28:29]
	v_pk_mul_f32 v[48:49], v[34:35], v[34:35]
	v_pk_mul_f32 v[50:51], v[32:33], v[32:33]
	v_pk_mov_b32 v[56:57], v[46:47], v[44:45] op_sel:[1,0]
	v_mov_b32_e32 v47, v45
	v_pk_mov_b32 v[44:45], v[50:51], v[48:49] op_sel:[1,0]
	v_mov_b32_e32 v51, v49
	v_mul_f32_e32 v55, v41, v41
	v_mul_f32_e32 v52, v37, v37
	v_mul_f32_e32 v54, v39, v39
	v_pk_add_f32 v[46:47], v[56:57], v[46:47]
	v_pk_add_f32 v[44:45], v[44:45], v[50:51]
	v_mul_f32_e32 v27, v40, v40
	v_mul_f32_e32 v58, v42, v42
	v_mul_f32_e32 v59, v43, v43
	v_pk_fma_f32 v[48:49], v[36:37], v[36:37], v[52:53] op_sel_hi:[1,1,0]
	v_pk_fma_f32 v[52:53], v[38:39], v[38:39], v[54:55] op_sel_hi:[1,1,0]
	v_pk_add_f32 v[46:47], v[46:47], v[46:47] op_sel:[0,1] op_sel_hi:[1,0]
	v_pk_add_f32 v[44:45], v[44:45], v[44:45] op_sel:[0,1] op_sel_hi:[1,0]
	v_mov_b32_e32 v49, v58
	v_mov_b32_e32 v53, v59
	v_mov_b32_e32 v47, v27
	v_mov_b32_e32 v45, v55
	v_pk_add_f32 v[48:49], v[48:49], v[52:53]
	v_pk_add_f32 v[44:45], v[46:47], v[44:45]
	s_nop 0
	v_pk_add_f32 v[44:45], v[44:45], v[48:49]
	s_nop 0
	v_add_f32_e32 v27, v44, v45
	ds_bpermute_b32 v44, v20, v27
	s_waitcnt lgkmcnt(0)
	v_add_f32_e32 v27, v27, v44
	ds_bpermute_b32 v44, v21, v27
	s_waitcnt lgkmcnt(0)
	v_add_f32_e32 v27, v27, v44
	ds_bpermute_b32 v44, v22, v27
	s_waitcnt lgkmcnt(0)
	v_add_f32_e32 v27, v27, v44
	ds_bpermute_b32 v44, v23, v27
	s_waitcnt lgkmcnt(0)
	v_add_f32_e32 v27, v27, v44
	ds_bpermute_b32 v44, v24, v27
	s_waitcnt lgkmcnt(0)
	v_add_f32_e32 v27, v27, v44
	ds_bpermute_b32 v44, v25, v27
	s_waitcnt lgkmcnt(0)
	v_add_f32_e32 v27, v27, v44
	v_fmamk_f32 v27, v27, 0x3a800000, v26
	v_mul_f32_e32 v44, 0x4b800000, v27
	v_cmp_gt_f32_e32 vcc, s2, v27
	s_nop 1
	v_cndmask_b32_e32 v27, v27, v44, vcc
	v_rsq_f32_e32 v27, v27
	s_nop 0
	v_mul_f32_e32 v44, 0x45800000, v27
	v_cndmask_b32_e32 v44, v27, v44, vcc
	v_pk_mul_f32 v[28:29], v[28:29], v[44:45] op_sel_hi:[1,0]
	v_pk_mul_f32 v[30:31], v[30:31], v[44:45] op_sel_hi:[1,0]
	v_pk_mul_f32 v[32:33], v[32:33], v[44:45] op_sel_hi:[1,0]
	v_pk_mul_f32 v[34:35], v[34:35], v[44:45] op_sel_hi:[1,0]
	v_pk_mul_f32 v[36:37], v[36:37], v[44:45] op_sel_hi:[1,0]
	v_pk_mul_f32 v[38:39], v[38:39], v[44:45] op_sel_hi:[1,0]
	v_pk_mul_f32 v[40:41], v[40:41], v[44:45] op_sel_hi:[1,0]
	v_pk_mul_f32 v[42:43], v[42:43], v[44:45] op_sel_hi:[1,0]
	v_pk_mul_f32 v[30:31], v[2:3], v[30:31]
	v_pk_mul_f32 v[28:29], v[0:1], v[28:29]
	v_pk_mul_f32 v[34:35], v[6:7], v[34:35]
	v_pk_mul_f32 v[32:33], v[4:5], v[32:33]
	v_pk_mul_f32 v[38:39], v[10:11], v[38:39]
	v_pk_mul_f32 v[36:37], v[8:9], v[36:37]
	v_pk_mul_f32 v[42:43], v[14:15], v[42:43]
	v_pk_mul_f32 v[40:41], v[12:13], v[40:41]
	v_cvt_pk_bf16_f32 v28, v28, v29
	v_cvt_pk_bf16_f32 v29, v30, v31
	v_cvt_pk_bf16_f32 v30, v32, v33
	v_cvt_pk_bf16_f32 v31, v34, v35
	v_cvt_pk_bf16_f32 v32, v36, v37
	v_cvt_pk_bf16_f32 v33, v38, v39
	v_cvt_pk_bf16_f32 v34, v40, v41
	v_cvt_pk_bf16_f32 v35, v42, v43
	global_store_dwordx2 v[16:17], v[28:29], off
	global_store_dwordx2 v[16:17], v[30:31], off offset:512
	global_store_dwordx2 v[16:17], v[32:33], off offset:1024
	global_store_dwordx2 v[16:17], v[34:35], off offset:1536
	v_lshl_add_u64 v[16:17], v[16:17], 0, s[0:1]
	s_cbranch_scc1 .LBB0_93

; #define PG8_STAGE(bufoff, gbase, voff) do { _Pragma("unroll") for (int _i = 0; _i < 2; ++_i) \
;         __builtin_amdgcn_global_load_lds((const unsigned*)((const char*)(gbase) + (voff)[_i]), (PG8_LAS unsigned*)(lds + (bufoff) + ldsw + _i * 8192), 16, 0, 0); } while (0)
; #define PG8_WAIT_V(n) asm volatile("s_waitcnt vmcnt(" #n ")" ::: "memory")
; #define PG8_BAR __builtin_amdgcn_s_barrier()
; template <class Epi, class Sched, bool ALIGN_EPI = false, bool SP2 = false>
; __device__ __forceinline__ void gemm_phase(PG8_LAS unsigned char* lds, const Gemm g, const Sched& S, const Epi& E) {
;     ...
;         PG8_STAGE(PG8_SB(0, 0), cB, voffB); PG8_STAGE(PG8_SB(0, 1), cB + hstepB, voffB); PG8_STAGE(PG8_SA(0, 0), cA, voffA); PG8_STAGE(PG8_SA(0, 1), cA + hstepA, voffA);
;         if (wr == 1) PG8_BAR;
;         PG8_WAIT_V(2); PG8_BAR;
;         PG8_STAGE(PG8_SB(1, 0), cB + kstep, voffB); PG8_STAGE(PG8_SA(1, 0), cA + kstep, voffA); PG8_STAGE(PG8_SB(1, 1), cB + hstepB + kstep, voffB);
;         PG8_WAIT_V(6); PG8_BAR;
.LBB0_154:
	s_add_u32 s14, s82, 0x7800000
	s_addc_u32 s15, s83, 0
	s_lshl_b32 s16, s16, 5
	s_and_b32 s52, s16, 0x60
	s_mov_b64 s[16:17], 0x80
	s_add_i32 m0, s9, 0x18000
	v_lshl_add_u64 v[6:7], v[6:7], 0, s[16:17]
	s_lshl_b32 s43, s1, 6
	s_lshl_b32 s1, s1, 13
	s_lshl_b32 s19, s52, 7
	s_waitcnt vmcnt(2)
	s_barrier
	global_load_lds_dwordx4 v[6:7], off
	v_lshl_add_u64 v[4:5], v[4:5], 0, s[16:17]
	s_add_i32 m0, s9, 0x1a000
	s_add_i32 s53, s9, 0x8000
	s_add_i32 s56, s9, 0xa000
	global_load_lds_dwordx4 v[4:5], off
	v_lshl_add_u64 v[0:1], v[0:1], 0, s[16:17]
	s_mov_b32 m0, s53
	s_add_u32 s22, s40, 0x10080
	global_load_lds_dwordx4 v[0:1], off
	v_lshl_add_u64 v[0:1], v[2:3], 0, s[16:17]
	s_mov_b32 m0, s56
	s_addc_u32 s23, s41, 0
	global_load_lds_dwordx4 v[0:1], off
	s_add_i32 m0, s9, 0x1c000
	s_nop 0
	global_load_lds_dwordx4 v130, s[22:23]
	v_lshl_add_u64 v[0:1], s[22:23], 0, v[134:135]
	s_add_i32 m0, s9, 0x1e000
	v_bfe_u32 v141, v8, 4, 2
	global_load_lds_dwordx4 v[0:1], off
	v_and_b32_e32 v140, 15, v8
	v_lshlrev_b32_e32 v0, 4, v141
	v_lshlrev_b32_e32 v1, 2, v8
	v_lshl_or_b32 v0, v140, 6, v0
	v_and_b32_e32 v1, 32, v1
	s_cmpk_lt_u32 s18, 0x100
	v_bitop3_b32 v142, v0, s19, v1 bitop3:0xde
	s_cselect_b64 s[18:19], -1, 0
	s_ashr_i32 s57, s88, 31
	s_waitcnt vmcnt(6)
	s_add_u32 s20, s69, s88
	v_bitop3_b32 v2, v0, s1, v1 bitop3:0xde
	s_addc_u32 s21, s21, s57
	s_add_i32 s59, 0, 0x10000
	s_add_i32 s60, 0, 0x14000
	s_sext_i32_i8 s62, s0
	s_mov_b32 s58, s88
	s_mov_b64 s[22:23], 0x100
	v_mov_b64_e32 v[136:137], 0x100
	v_mov_b64_e32 v[138:139], 0xff
	v_add_u32_e32 v143, s59, v142
	v_add_u32_e32 v144, s60, v142
	v_add_u32_e32 v145, 0, v2
	s_mov_b64 s[24:25], 0x180
	s_mov_b32 s61, 0x58000
	s_barrier
	s_branch .LBB0_157

; #define PG8_STAGE(bufoff, gbase, voff) do { _Pragma("unroll") for (int _i = 0; _i < 2; ++_i) \
;         __builtin_amdgcn_global_load_lds((const unsigned*)((const char*)(gbase) + (voff)[_i]), (PG8_LAS unsigned*)(lds + (bufoff) + ldsw + _i * 8192), 16, 0, 0); } while (0)
; #define PG8_LDA(dst, b, h) do { _Pragma("unroll") for (int m = 0; m < 4; ++m) _Pragma("unroll") for (int k = 0; k < 2; ++k) dst[m][k] = *(const PG8_LAS bf16x8*)(lds + PG8_SA(b, h) + aoff + m * 2048 + k * 1024); } while (0)
; #define PG8_LDB(dst, b, h) do { _Pragma("unroll") for (int n = 0; n < 2; ++n) _Pragma("unroll") for (int k = 0; k < 2; ++k) dst[n][k] = *(const PG8_LAS bf16x8*)(lds + PG8_SB(b, h) + boff + n * 2048 + k * 1024); } while (0)
; #define PG8_MMA(ai, bj, At, Bt) do { __builtin_amdgcn_s_setprio(1); _Pragma("unroll") for (int m = 0; m < 4; ++m) _Pragma("unroll") for (int n = 0; n < 2; ++n) _Pragma("unroll") for (int k = 0; k < 2; ++k) \
;         acc[ai][bj][m][n] = __builtin_amdgcn_mfma_f32_16x16x32_bf16(Bt[n][k], At[m][k], acc[ai][bj][m][n], 0, 0, 0); __builtin_amdgcn_s_setprio(0); } while (0)
; #define PG8_WAIT_V(n) asm volatile("s_waitcnt vmcnt(" #n ")" ::: "memory")
; #define PG8_WAIT_L(n) asm volatile("s_waitcnt lgkmcnt(" #n ")" ::: "memory")
; #define PG8_BAR __builtin_amdgcn_s_barrier()
; #define PG8_SCHED __builtin_amdgcn_sched_barrier(0)
; template <class Epi, class Sched, bool ALIGN_EPI = false, bool SP2 = false>
; __device__ __forceinline__ void gemm_phase(PG8_LAS unsigned char* lds, const Gemm g, const Sched& S, const Epi& E) {
;     ...
;             PG8_LDB(B0, 0, 0); PG8_LDB(B1, 0, 1); PG8_SCHED; PG8_LDA(At, 0, 0); PG8_STAGE(PG8_SA(1, 1), a1 + hstepA, voffA);
;             PG8_WAIT_V(8); PG8_WAIT_L(0); PG8_BAR; PG8_MMA(0, 0, At, B0); PG8_MMA(0, 1, At, B1); PG8_BAR; PG8_SCHED;
;             PG8_LDA(At, 0, 1); PG8_STAGE(PG8_SB(0, 0), b2, voffB); PG8_STAGE(PG8_SB(0, 1), b2 + hstepB, voffB); PG8_STAGE(PG8_SA(0, 0), a2, voffA);
;             PG8_WAIT_V(8); PG8_WAIT_L(0); PG8_BAR; PG8_MMA(1, 0, At, B0); PG8_MMA(1, 1, At, B1); PG8_BAR; PG8_SCHED;
.LBB0_163:
	ds_read_b128 v[0:3], v143
	ds_read_b128 v[4:7], v143 offset:1024
	ds_read_b128 v[8:11], v143 offset:2048
	ds_read_b128 v[12:15], v143 offset:3072
	ds_read_b128 v[16:19], v144
	ds_read_b128 v[20:23], v144 offset:1024
	ds_read_b128 v[24:27], v144 offset:2048
	ds_read_b128 v[28:31], v144 offset:3072
	s_ashr_i32 s31, s30, 31
	s_lshl_b64 s[34:35], s[30:31], 17
	s_add_u32 s34, s54, s34
	s_addc_u32 s35, s55, s35
	s_and_b64 s[36:37], s[0:1], exec
	s_cselect_b32 s51, s35, s39
	s_cselect_b32 s50, s34, s38
	s_ashr_i32 s29, s28, 31
	s_lshl_b64 s[36:37], s[28:29], 17
	s_add_u32 s36, s2, s36
	s_addc_u32 s37, s3, s37
	s_and_b64 s[44:45], s[0:1], exec
	s_cselect_b32 s47, s37, s41
	s_cselect_b32 s46, s36, s40
	s_add_u32 s44, s38, 0x10080
	s_addc_u32 s45, s39, 0
	s_add_i32 s63, s9, 0xc000
	s_mov_b32 m0, s63
	s_add_i32 s29, s9, 0xe000
	ds_read_b128 v[32:35], v145
	ds_read_b128 v[36:39], v145 offset:1024
	ds_read_b128 v[40:43], v145 offset:2048
	ds_read_b128 v[44:47], v145 offset:3072
	ds_read_b128 v[48:51], v145 offset:4096
	ds_read_b128 v[52:55], v145 offset:5120
	ds_read_b128 v[56:59], v145 offset:6144
	ds_read_b128 v[60:63], v145 offset:7168
	global_load_lds_dwordx4 v128, s[44:45]
	s_mov_b32 m0, s29
	s_nop 0
	global_load_lds_dwordx4 v132, s[44:45]
	s_waitcnt vmcnt(8)
	s_waitcnt lgkmcnt(0)
	s_barrier
	s_setprio 1
	s_waitcnt lgkmcnt(0)
	v_mfma_f32_16x16x32_bf16 v[64:67], v[0:3], v[32:35], 0
	v_mfma_f32_16x16x32_bf16 v[68:71], v[8:11], v[32:35], 0
	v_mfma_f32_16x16x32_bf16 v[72:75], v[0:3], v[40:43], 0
	v_mfma_f32_16x16x32_bf16 v[76:79], v[8:11], v[40:43], 0
	v_mfma_f32_16x16x32_bf16 v[80:83], v[0:3], v[48:51], 0
	v_mfma_f32_16x16x32_bf16 v[84:87], v[8:11], v[48:51], 0
	v_mfma_f32_16x16x32_bf16 v[88:91], v[0:3], v[56:59], 0
	v_mfma_f32_16x16x32_bf16 v[92:95], v[8:11], v[56:59], 0
	v_mfma_f32_16x16x32_bf16 v[64:67], v[4:7], v[36:39], v[64:67]
	v_mfma_f32_16x16x32_bf16 v[68:71], v[12:15], v[36:39], v[68:71]
	v_mfma_f32_16x16x32_bf16 v[72:75], v[4:7], v[44:47], v[72:75]
	v_mfma_f32_16x16x32_bf16 v[76:79], v[12:15], v[44:47], v[76:79]
	v_mfma_f32_16x16x32_bf16 v[80:83], v[4:7], v[52:55], v[80:83]
	v_mfma_f32_16x16x32_bf16 v[84:87], v[12:15], v[52:55], v[84:87]
	v_mfma_f32_16x16x32_bf16 v[88:91], v[4:7], v[60:63], v[88:91]
	v_mfma_f32_16x16x32_bf16 v[92:95], v[12:15], v[60:63], v[92:95]
	s_setprio 0
	s_setprio 1
	v_mfma_f32_16x16x32_bf16 v[96:99], v[16:19], v[32:35], 0
	v_mfma_f32_16x16x32_bf16 v[32:35], v[24:27], v[32:35], 0
	v_mfma_f32_16x16x32_bf16 v[96:99], v[20:23], v[36:39], v[96:99]
	v_mfma_f32_16x16x32_bf16 v[32:35], v[28:31], v[36:39], v[32:35]
	v_mfma_f32_16x16x32_bf16 v[36:39], v[16:19], v[40:43], 0
	v_mfma_f32_16x16x32_bf16 v[40:43], v[24:27], v[40:43], 0
	v_mfma_f32_16x16x32_bf16 v[36:39], v[20:23], v[44:47], v[36:39]
	v_mfma_f32_16x16x32_bf16 v[40:43], v[28:31], v[44:47], v[40:43]
	v_mfma_f32_16x16x32_bf16 v[44:47], v[16:19], v[48:51], 0
	v_mfma_f32_16x16x32_bf16 v[48:51], v[24:27], v[48:51], 0
	v_mfma_f32_16x16x32_bf16 v[44:47], v[20:23], v[52:55], v[44:47]
	v_mfma_f32_16x16x32_bf16 v[48:51], v[28:31], v[52:55], v[48:51]
	v_mfma_f32_16x16x32_bf16 v[52:55], v[16:19], v[56:59], 0
	v_mfma_f32_16x16x32_bf16 v[56:59], v[24:27], v[56:59], 0
	v_mfma_f32_16x16x32_bf16 v[52:55], v[20:23], v[60:63], v[52:55]
	v_mfma_f32_16x16x32_bf16 v[56:59], v[28:31], v[60:63], v[56:59]
	s_setprio 0
	s_barrier
	s_add_i32 s48, s59, s8
	v_lshl_add_u64 v[190:191], s[40:41], 0, v[130:131]
	s_add_i32 s31, s48, 0x2000
	v_lshl_add_u64 v[146:147], v[190:191], 0, s[22:23]
	s_mov_b32 m0, s48
	v_lshl_add_u64 v[216:217], s[40:41], 0, v[134:135]
	s_add_u32 s64, s40, 0x10100
	ds_read_b128 v[60:63], v145 offset:16384
	ds_read_b128 v[100:103], v145 offset:17408
	ds_read_b128 v[104:107], v145 offset:18432
	ds_read_b128 v[108:111], v145 offset:19456
	ds_read_b128 v[112:115], v145 offset:20480
	ds_read_b128 v[116:119], v145 offset:21504
	ds_read_b128 v[120:123], v145 offset:22528
	ds_read_b128 v[124:127], v145 offset:23552
	global_load_lds_dwordx4 v[146:147], off
	v_lshl_add_u64 v[146:147], v[216:217], 0, s[22:23]
	s_mov_b32 m0, s31
	s_addc_u32 s65, s41, 0
	s_add_i32 s44, s60, s8
	global_load_lds_dwordx4 v[146:147], off
	s_mov_b32 m0, s44
	s_add_i32 s45, s44, 0x2000
	global_load_lds_dwordx4 v130, s[64:65]
	s_mov_b32 m0, s45
	v_lshl_add_u64 v[218:219], s[38:39], 0, v[128:129]
	global_load_lds_dwordx4 v134, s[64:65]
	v_lshl_add_u64 v[146:147], v[218:219], 0, s[22:23]
	s_mov_b32 m0, s9
	v_lshl_add_u64 v[220:221], s[38:39], 0, v[132:133]
	global_load_lds_dwordx4 v[146:147], off
	v_lshl_add_u64 v[146:147], v[220:221], 0, s[22:23]
	s_mov_b32 m0, s27
	s_nop 0
	global_load_lds_dwordx4 v[146:147], off
	s_waitcnt vmcnt(8)
	s_waitcnt lgkmcnt(0)
	s_barrier
; #define PG8_STAGE(bufoff, gbase, voff) do { _Pragma("unroll") for (int _i = 0; _i < 2; ++_i) \
;         __builtin_amdgcn_global_load_lds((const unsigned*)((const char*)(gbase) + (voff)[_i]), (PG8_LAS unsigned*)(lds + (bufoff) + ldsw + _i * 8192), 16, 0, 0); } while (0)
; #define PG8_LDA(dst, b, h) do { _Pragma("unroll") for (int m = 0; m < 4; ++m) _Pragma("unroll") for (int k = 0; k < 2; ++k) dst[m][k] = *(const PG8_LAS bf16x8*)(lds + PG8_SA(b, h) + aoff + m * 2048 + k * 1024); } while (0)
; #define PG8_LDB(dst, b, h) do { _Pragma("unroll") for (int n = 0; n < 2; ++n) _Pragma("unroll") for (int k = 0; k < 2; ++k) dst[n][k] = *(const PG8_LAS bf16x8*)(lds + PG8_SB(b, h) + boff + n * 2048 + k * 1024); } while (0)
; #define PG8_MMA(ai, bj, At, Bt) do { __builtin_amdgcn_s_setprio(1); _Pragma("unroll") for (int m = 0; m < 4; ++m) _Pragma("unroll") for (int n = 0; n < 2; ++n) _Pragma("unroll") for (int k = 0; k < 2; ++k) \
;         acc[ai][bj][m][n] = __builtin_amdgcn_mfma_f32_16x16x32_bf16(Bt[n][k], At[m][k], acc[ai][bj][m][n], 0, 0, 0); __builtin_amdgcn_s_setprio(0); } while (0)
; #define PG8_WAIT_V(n) asm volatile("s_waitcnt vmcnt(" #n ")" ::: "memory")
; #define PG8_WAIT_L(n) asm volatile("s_waitcnt lgkmcnt(" #n ")" ::: "memory")
; #define PG8_BAR __builtin_amdgcn_s_barrier()
; #define PG8_SCHED __builtin_amdgcn_sched_barrier(0)
; template <class Epi, class Sched, bool ALIGN_EPI = false, bool SP2 = false>
; __device__ __forceinline__ void gemm_phase(PG8_LAS unsigned char* lds, const Gemm g, const Sched& S, const Epi& E) {
;     ...
;             PG8_WAIT_V(8); PG8_WAIT_L(0); PG8_BAR; PG8_MMA(1, 0, At, B0); PG8_MMA(1, 1, At, B1); PG8_BAR; PG8_SCHED;
;             PG8_LDB(B0, 1, 0); PG8_LDB(B1, 1, 1); PG8_SCHED; PG8_LDA(At, 1, 0); PG8_STAGE(PG8_SA(0, 1), a2 + hstepA, voffA);
;             PG8_WAIT_V(8); PG8_WAIT_L(0); PG8_BAR; PG8_MMA(0, 0, At, B0); PG8_MMA(0, 1, At, B1); PG8_BAR; PG8_SCHED;
	s_setprio 1
	s_waitcnt lgkmcnt(0)
	v_mfma_f32_16x16x32_bf16 v[146:149], v[0:3], v[60:63], 0
	v_mfma_f32_16x16x32_bf16 v[154:157], v[0:3], v[104:107], 0
	v_mfma_f32_16x16x32_bf16 v[162:165], v[0:3], v[112:115], 0
	v_mfma_f32_16x16x32_bf16 v[0:3], v[0:3], v[120:123], 0
	v_mfma_f32_16x16x32_bf16 v[146:149], v[4:7], v[100:103], v[146:149]
	v_mfma_f32_16x16x32_bf16 v[154:157], v[4:7], v[108:111], v[154:157]
	v_mfma_f32_16x16x32_bf16 v[162:165], v[4:7], v[116:119], v[162:165]
	v_mfma_f32_16x16x32_bf16 v[0:3], v[4:7], v[124:127], v[0:3]
	v_mfma_f32_16x16x32_bf16 v[4:7], v[8:11], v[120:123], 0
	v_mfma_f32_16x16x32_bf16 v[150:153], v[8:11], v[60:63], 0
	v_mfma_f32_16x16x32_bf16 v[158:161], v[8:11], v[104:107], 0
	v_mfma_f32_16x16x32_bf16 v[166:169], v[8:11], v[112:115], 0
	v_mfma_f32_16x16x32_bf16 v[4:7], v[12:15], v[124:127], v[4:7]
	v_mfma_f32_16x16x32_bf16 v[150:153], v[12:15], v[100:103], v[150:153]
	v_mfma_f32_16x16x32_bf16 v[158:161], v[12:15], v[108:111], v[158:161]
	v_mfma_f32_16x16x32_bf16 v[166:169], v[12:15], v[116:119], v[166:169]
	s_setprio 0
	s_setprio 1
	v_mfma_f32_16x16x32_bf16 v[8:11], v[16:19], v[60:63], 0
	v_mfma_f32_16x16x32_bf16 v[12:15], v[24:27], v[60:63], 0
	v_mfma_f32_16x16x32_bf16 v[8:11], v[20:23], v[100:103], v[8:11]
	v_mfma_f32_16x16x32_bf16 v[12:15], v[28:31], v[100:103], v[12:15]
	v_mfma_f32_16x16x32_bf16 v[60:63], v[16:19], v[104:107], 0
	v_mfma_f32_16x16x32_bf16 v[100:103], v[24:27], v[104:107], 0
	v_mfma_f32_16x16x32_bf16 v[104:107], v[16:19], v[112:115], 0
	v_mfma_f32_16x16x32_bf16 v[16:19], v[16:19], v[120:123], 0
	v_mfma_f32_16x16x32_bf16 v[60:63], v[20:23], v[108:111], v[60:63]
	v_mfma_f32_16x16x32_bf16 v[100:103], v[28:31], v[108:111], v[100:103]
	v_mfma_f32_16x16x32_bf16 v[104:107], v[20:23], v[116:119], v[104:107]
	v_mfma_f32_16x16x32_bf16 v[108:111], v[24:27], v[112:115], 0
	v_mfma_f32_16x16x32_bf16 v[16:19], v[20:23], v[124:127], v[16:19]
	v_mfma_f32_16x16x32_bf16 v[20:23], v[24:27], v[120:123], 0
	v_mfma_f32_16x16x32_bf16 v[108:111], v[28:31], v[116:119], v[108:111]
	v_mfma_f32_16x16x32_bf16 v[20:23], v[28:31], v[124:127], v[20:23]
	s_setprio 0
	s_barrier
	s_add_i32 s49, 0, 0x18000
	s_add_i32 s68, 0, 0x1c000
	v_add_u32_e32 v224, s49, v142
	v_add_u32_e32 v228, s68, v142
	ds_read_b128 v[24:27], v224
	ds_read_b128 v[28:31], v224 offset:1024
	ds_read_b128 v[112:115], v224 offset:2048
	ds_read_b128 v[116:119], v224 offset:3072
	ds_read_b128 v[120:123], v228
	ds_read_b128 v[124:127], v228 offset:1024
	ds_read_b128 v[170:173], v228 offset:2048
	ds_read_b128 v[174:177], v228 offset:3072
	s_add_u32 s64, s38, 0x10100
	s_addc_u32 s65, s39, 0
	s_mov_b32 m0, s33
	ds_read_b128 v[178:181], v145 offset:32768
	ds_read_b128 v[182:185], v145 offset:33792
	ds_read_b128 v[186:189], v145 offset:34816
	ds_read_b128 v[196:199], v145 offset:35840
	ds_read_b128 v[200:203], v145 offset:36864
	ds_read_b128 v[204:207], v145 offset:37888
	ds_read_b128 v[208:211], v145 offset:38912
	ds_read_b128 v[212:215], v145 offset:39936
	global_load_lds_dwordx4 v128, s[64:65]
	s_mov_b32 m0, s42
	s_nop 0
	global_load_lds_dwordx4 v132, s[64:65]
	s_waitcnt vmcnt(8)
	s_waitcnt lgkmcnt(0)
	s_barrier
	s_setprio 1
	s_waitcnt lgkmcnt(0)
	v_mfma_f32_16x16x32_bf16 v[64:67], v[24:27], v[178:181], v[64:67]
	v_mfma_f32_16x16x32_bf16 v[68:71], v[112:115], v[178:181], v[68:71]
	v_mfma_f32_16x16x32_bf16 v[72:75], v[24:27], v[186:189], v[72:75]
	v_mfma_f32_16x16x32_bf16 v[76:79], v[112:115], v[186:189], v[76:79]
	v_mfma_f32_16x16x32_bf16 v[80:83], v[24:27], v[200:203], v[80:83]
	v_mfma_f32_16x16x32_bf16 v[84:87], v[112:115], v[200:203], v[84:87]
	v_mfma_f32_16x16x32_bf16 v[88:91], v[24:27], v[208:211], v[88:91]
	v_mfma_f32_16x16x32_bf16 v[92:95], v[112:115], v[208:211], v[92:95]
	v_mfma_f32_16x16x32_bf16 v[64:67], v[28:31], v[182:185], v[64:67]
	v_mfma_f32_16x16x32_bf16 v[68:71], v[116:119], v[182:185], v[68:71]
	v_mfma_f32_16x16x32_bf16 v[72:75], v[28:31], v[196:199], v[72:75]
	v_mfma_f32_16x16x32_bf16 v[76:79], v[116:119], v[196:199], v[76:79]
	v_mfma_f32_16x16x32_bf16 v[80:83], v[28:31], v[204:207], v[80:83]
	v_mfma_f32_16x16x32_bf16 v[84:87], v[116:119], v[204:207], v[84:87]
	v_mfma_f32_16x16x32_bf16 v[88:91], v[28:31], v[212:215], v[88:91]
	v_mfma_f32_16x16x32_bf16 v[92:95], v[116:119], v[212:215], v[92:95]
	s_setprio 0
	s_setprio 1
	v_mfma_f32_16x16x32_bf16 v[96:99], v[120:123], v[178:181], v[96:99]
	v_mfma_f32_16x16x32_bf16 v[32:35], v[170:173], v[178:181], v[32:35]
	v_mfma_f32_16x16x32_bf16 v[36:39], v[120:123], v[186:189], v[36:39]
	v_mfma_f32_16x16x32_bf16 v[40:43], v[170:173], v[186:189], v[40:43]
	v_mfma_f32_16x16x32_bf16 v[44:47], v[120:123], v[200:203], v[44:47]
	v_mfma_f32_16x16x32_bf16 v[48:51], v[170:173], v[200:203], v[48:51]
	v_mfma_f32_16x16x32_bf16 v[52:55], v[120:123], v[208:211], v[52:55]
	v_mfma_f32_16x16x32_bf16 v[56:59], v[170:173], v[208:211], v[56:59]
	v_mfma_f32_16x16x32_bf16 v[96:99], v[124:127], v[182:185], v[96:99]
	v_mfma_f32_16x16x32_bf16 v[32:35], v[174:177], v[182:185], v[32:35]
	v_mfma_f32_16x16x32_bf16 v[36:39], v[124:127], v[196:199], v[36:39]
	v_mfma_f32_16x16x32_bf16 v[40:43], v[174:177], v[196:199], v[40:43]
	v_mfma_f32_16x16x32_bf16 v[44:47], v[124:127], v[204:207], v[44:47]
	v_mfma_f32_16x16x32_bf16 v[48:51], v[174:177], v[204:207], v[48:51]
	v_mfma_f32_16x16x32_bf16 v[52:55], v[124:127], v[212:215], v[52:55]
	v_mfma_f32_16x16x32_bf16 v[56:59], v[174:177], v[212:215], v[56:59]
	s_setprio 0
	s_barrier
; #define PG8_STAGE(bufoff, gbase, voff) do { _Pragma("unroll") for (int _i = 0; _i < 2; ++_i) \
;         __builtin_amdgcn_global_load_lds((const unsigned*)((const char*)(gbase) + (voff)[_i]), (PG8_LAS unsigned*)(lds + (bufoff) + ldsw + _i * 8192), 16, 0, 0); } while (0)
; #define PG8_LDA(dst, b, h) do { _Pragma("unroll") for (int m = 0; m < 4; ++m) _Pragma("unroll") for (int k = 0; k < 2; ++k) dst[m][k] = *(const PG8_LAS bf16x8*)(lds + PG8_SA(b, h) + aoff + m * 2048 + k * 1024); } while (0)
; #define PG8_LDB(dst, b, h) do { _Pragma("unroll") for (int n = 0; n < 2; ++n) _Pragma("unroll") for (int k = 0; k < 2; ++k) dst[n][k] = *(const PG8_LAS bf16x8*)(lds + PG8_SB(b, h) + boff + n * 2048 + k * 1024); } while (0)
; #define PG8_MMA(ai, bj, At, Bt) do { __builtin_amdgcn_s_setprio(1); _Pragma("unroll") for (int m = 0; m < 4; ++m) _Pragma("unroll") for (int n = 0; n < 2; ++n) _Pragma("unroll") for (int k = 0; k < 2; ++k) \
;         acc[ai][bj][m][n] = __builtin_amdgcn_mfma_f32_16x16x32_bf16(Bt[n][k], At[m][k], acc[ai][bj][m][n], 0, 0, 0); __builtin_amdgcn_s_setprio(0); } while (0)
; #define PG8_WAIT_V(n) asm volatile("s_waitcnt vmcnt(" #n ")" ::: "memory")
; #define PG8_WAIT_L(n) asm volatile("s_waitcnt lgkmcnt(" #n ")" ::: "memory")
; #define PG8_BAR __builtin_amdgcn_s_barrier()
; #define PG8_SCHED __builtin_amdgcn_sched_barrier(0)
; template <class Epi, class Sched, bool ALIGN_EPI = false, bool SP2 = false>
; __device__ __forceinline__ void gemm_phase(PG8_LAS unsigned char* lds, const Gemm g, const Sched& S, const Epi& E) {
;     ...
;             PG8_WAIT_V(8); PG8_WAIT_L(0); PG8_BAR; PG8_MMA(0, 0, At, B0); PG8_MMA(0, 1, At, B1); PG8_BAR; PG8_SCHED;
;             PG8_LDA(At, 1, 1); PG8_STAGE(PG8_SB(1, 0), b3, voffB); PG8_STAGE(PG8_SB(1, 1), b3 + hstepB, voffB); PG8_STAGE(PG8_SA(1, 0), a3, voffA);
;             PG8_WAIT_V(8); PG8_WAIT_L(0); PG8_BAR; PG8_MMA(1, 0, At, B0); PG8_MMA(1, 1, At, B1); PG8_BAR; PG8_SCHED;
;             } else {
;             PG8_LDB(B0, 0, 0); PG8_SCHED; PG8_LDA(At, 0, 0); PG8_STAGE(PG8_SA(1, 1), a1 + hstepA, voffA);
	s_add_i32 s64, s49, s8
	s_add_i32 s49, s64, 0x2000
	v_lshl_add_u64 v[190:191], v[190:191], 0, s[24:25]
	s_mov_b32 m0, s64
	s_add_u32 s66, s40, 0x10180
	ds_read_b128 v[178:181], v145 offset:49152
	ds_read_b128 v[182:185], v145 offset:50176
	ds_read_b128 v[186:189], v145 offset:51200
	ds_read_b128 v[196:199], v145 offset:52224
	ds_read_b128 v[200:203], v145 offset:53248
	ds_read_b128 v[204:207], v145 offset:54272
	ds_read_b128 v[208:211], v145 offset:55296
	ds_read_b128 v[212:215], v145 offset:56320
	global_load_lds_dwordx4 v[190:191], off
	v_lshl_add_u64 v[190:191], v[216:217], 0, s[24:25]
	s_mov_b32 m0, s49
	s_addc_u32 s67, s41, 0
	s_add_i32 s40, s68, s8
	global_load_lds_dwordx4 v[190:191], off
	s_mov_b32 m0, s40
	s_add_i32 s41, s40, 0x2000
	global_load_lds_dwordx4 v130, s[66:67]
	s_mov_b32 m0, s41
	s_nop 0
	global_load_lds_dwordx4 v134, s[66:67]
	v_lshl_add_u64 v[190:191], v[218:219], 0, s[24:25]
	s_mov_b32 m0, s53
	s_nop 0
	global_load_lds_dwordx4 v[190:191], off
	v_lshl_add_u64 v[190:191], v[220:221], 0, s[24:25]
	s_mov_b32 m0, s56
	s_nop 0
	global_load_lds_dwordx4 v[190:191], off
	s_waitcnt vmcnt(8)
	s_waitcnt lgkmcnt(0)
	s_barrier
	s_setprio 1
	s_waitcnt lgkmcnt(0)
	v_mfma_f32_16x16x32_bf16 v[0:3], v[24:27], v[208:211], v[0:3]
	v_mfma_f32_16x16x32_bf16 v[4:7], v[112:115], v[208:211], v[4:7]
	v_mfma_f32_16x16x32_bf16 v[146:149], v[24:27], v[178:181], v[146:149]
	v_mfma_f32_16x16x32_bf16 v[150:153], v[112:115], v[178:181], v[150:153]
	v_mfma_f32_16x16x32_bf16 v[154:157], v[24:27], v[186:189], v[154:157]
	v_mfma_f32_16x16x32_bf16 v[158:161], v[112:115], v[186:189], v[158:161]
	v_mfma_f32_16x16x32_bf16 v[162:165], v[24:27], v[200:203], v[162:165]
	v_mfma_f32_16x16x32_bf16 v[166:169], v[112:115], v[200:203], v[166:169]
	v_mfma_f32_16x16x32_bf16 v[0:3], v[28:31], v[212:215], v[0:3]
	v_mfma_f32_16x16x32_bf16 v[4:7], v[116:119], v[212:215], v[4:7]
	v_mfma_f32_16x16x32_bf16 v[146:149], v[28:31], v[182:185], v[146:149]
	v_mfma_f32_16x16x32_bf16 v[150:153], v[116:119], v[182:185], v[150:153]
	v_mfma_f32_16x16x32_bf16 v[154:157], v[28:31], v[196:199], v[154:157]
	v_mfma_f32_16x16x32_bf16 v[158:161], v[116:119], v[196:199], v[158:161]
	v_mfma_f32_16x16x32_bf16 v[162:165], v[28:31], v[204:207], v[162:165]
	v_mfma_f32_16x16x32_bf16 v[166:169], v[116:119], v[204:207], v[166:169]
	s_setprio 0
	s_setprio 1
	v_mfma_f32_16x16x32_bf16 v[8:11], v[120:123], v[178:181], v[8:11]
	v_mfma_f32_16x16x32_bf16 v[12:15], v[170:173], v[178:181], v[12:15]
	v_mfma_f32_16x16x32_bf16 v[24:27], v[120:123], v[186:189], v[60:63]
	v_mfma_f32_16x16x32_bf16 v[28:31], v[170:173], v[186:189], v[100:103]
	v_mfma_f32_16x16x32_bf16 v[60:63], v[120:123], v[200:203], v[104:107]
	v_mfma_f32_16x16x32_bf16 v[100:103], v[170:173], v[200:203], v[108:111]
	v_mfma_f32_16x16x32_bf16 v[16:19], v[120:123], v[208:211], v[16:19]
	v_mfma_f32_16x16x32_bf16 v[20:23], v[170:173], v[208:211], v[20:23]
	v_mfma_f32_16x16x32_bf16 v[8:11], v[124:127], v[182:185], v[8:11]
	v_mfma_f32_16x16x32_bf16 v[12:15], v[174:177], v[182:185], v[12:15]
	v_mfma_f32_16x16x32_bf16 v[24:27], v[124:127], v[196:199], v[24:27]
	v_mfma_f32_16x16x32_bf16 v[28:31], v[174:177], v[196:199], v[28:31]
	v_mfma_f32_16x16x32_bf16 v[60:63], v[124:127], v[204:207], v[60:63]
	v_mfma_f32_16x16x32_bf16 v[100:103], v[174:177], v[204:207], v[100:103]
	v_mfma_f32_16x16x32_bf16 v[16:19], v[124:127], v[212:215], v[16:19]
	v_mfma_f32_16x16x32_bf16 v[20:23], v[174:177], v[212:215], v[20:23]
	s_setprio 0
	s_barrier
	ds_read_b128 v[104:107], v143
	ds_read_b128 v[108:111], v143 offset:1024
	ds_read_b128 v[112:115], v143 offset:2048
	ds_read_b128 v[116:119], v143 offset:3072
	ds_read_b128 v[120:123], v144
	ds_read_b128 v[124:127], v144 offset:1024
	ds_read_b128 v[170:173], v144 offset:2048
	ds_read_b128 v[174:177], v144 offset:3072
	s_add_u32 s38, s38, 0x10180
	s_addc_u32 s39, s39, 0
	s_mov_b32 m0, s63
	ds_read_b128 v[178:181], v145
	ds_read_b128 v[182:185], v145 offset:1024
	ds_read_b128 v[186:189], v145 offset:2048
	ds_read_b128 v[196:199], v145 offset:3072
	ds_read_b128 v[200:203], v145 offset:4096
	ds_read_b128 v[204:207], v145 offset:5120
	ds_read_b128 v[208:211], v145 offset:6144
	ds_read_b128 v[212:215], v145 offset:7168
	global_load_lds_dwordx4 v128, s[38:39]
	s_mov_b32 m0, s29
	s_nop 0
	global_load_lds_dwordx4 v132, s[38:39]
	s_waitcnt vmcnt(8)
	s_waitcnt lgkmcnt(0)
	s_barrier
	s_setprio 1
	s_waitcnt lgkmcnt(0)
	v_mfma_f32_16x16x32_bf16 v[64:67], v[104:107], v[178:181], v[64:67]
	v_mfma_f32_16x16x32_bf16 v[68:71], v[112:115], v[178:181], v[68:71]
	v_mfma_f32_16x16x32_bf16 v[72:75], v[104:107], v[186:189], v[72:75]
	v_mfma_f32_16x16x32_bf16 v[76:79], v[112:115], v[186:189], v[76:79]
	v_mfma_f32_16x16x32_bf16 v[80:83], v[104:107], v[200:203], v[80:83]
	v_mfma_f32_16x16x32_bf16 v[84:87], v[112:115], v[200:203], v[84:87]
	v_mfma_f32_16x16x32_bf16 v[88:91], v[104:107], v[208:211], v[88:91]
	v_mfma_f32_16x16x32_bf16 v[92:95], v[112:115], v[208:211], v[92:95]
	v_mfma_f32_16x16x32_bf16 v[64:67], v[108:111], v[182:185], v[64:67]
	v_mfma_f32_16x16x32_bf16 v[68:71], v[116:119], v[182:185], v[68:71]
	v_mfma_f32_16x16x32_bf16 v[72:75], v[108:111], v[196:199], v[72:75]
	v_mfma_f32_16x16x32_bf16 v[76:79], v[116:119], v[196:199], v[76:79]
	v_mfma_f32_16x16x32_bf16 v[80:83], v[108:111], v[204:207], v[80:83]
	v_mfma_f32_16x16x32_bf16 v[84:87], v[116:119], v[204:207], v[84:87]
	v_mfma_f32_16x16x32_bf16 v[88:91], v[108:111], v[212:215], v[88:91]
	v_mfma_f32_16x16x32_bf16 v[92:95], v[116:119], v[212:215], v[92:95]
	s_setprio 0
	s_setprio 1
	v_mfma_f32_16x16x32_bf16 v[32:35], v[170:173], v[178:181], v[32:35]
	v_mfma_f32_16x16x32_bf16 v[96:99], v[120:123], v[178:181], v[96:99]
	v_mfma_f32_16x16x32_bf16 v[178:181], v[174:177], v[182:185], v[32:35]
	v_mfma_f32_16x16x32_bf16 v[32:35], v[120:123], v[186:189], v[36:39]
	v_mfma_f32_16x16x32_bf16 v[216:219], v[124:127], v[182:185], v[96:99]
	v_mfma_f32_16x16x32_bf16 v[182:185], v[124:127], v[196:199], v[32:35]
	v_mfma_f32_16x16x32_bf16 v[32:35], v[170:173], v[186:189], v[40:43]
	v_mfma_f32_16x16x32_bf16 v[40:43], v[174:177], v[196:199], v[32:35]
	v_mfma_f32_16x16x32_bf16 v[32:35], v[120:123], v[200:203], v[44:47]
	v_mfma_f32_16x16x32_bf16 v[44:47], v[124:127], v[204:207], v[32:35]
	v_mfma_f32_16x16x32_bf16 v[32:35], v[170:173], v[200:203], v[48:51]
	v_mfma_f32_16x16x32_bf16 v[48:51], v[174:177], v[204:207], v[32:35]
	v_mfma_f32_16x16x32_bf16 v[32:35], v[120:123], v[208:211], v[52:55]
	v_mfma_f32_16x16x32_bf16 v[52:55], v[124:127], v[212:215], v[32:35]
	v_mfma_f32_16x16x32_bf16 v[32:35], v[170:173], v[208:211], v[56:59]
	v_mfma_f32_16x16x32_bf16 v[56:59], v[174:177], v[212:215], v[32:35]
	s_setprio 0
	s_barrier
; #define PG8_STAGE(bufoff, gbase, voff) do { _Pragma("unroll") for (int _i = 0; _i < 2; ++_i) \
;         __builtin_amdgcn_global_load_lds((const unsigned*)((const char*)(gbase) + (voff)[_i]), (PG8_LAS unsigned*)(lds + (bufoff) + ldsw + _i * 8192), 16, 0, 0); } while (0)
; #define PG8_LDA(dst, b, h) do { _Pragma("unroll") for (int m = 0; m < 4; ++m) _Pragma("unroll") for (int k = 0; k < 2; ++k) dst[m][k] = *(const PG8_LAS bf16x8*)(lds + PG8_SA(b, h) + aoff + m * 2048 + k * 1024); } while (0)
; #define PG8_LDB(dst, b, h) do { _Pragma("unroll") for (int n = 0; n < 2; ++n) _Pragma("unroll") for (int k = 0; k < 2; ++k) dst[n][k] = *(const PG8_LAS bf16x8*)(lds + PG8_SB(b, h) + boff + n * 2048 + k * 1024); } while (0)
; #define PG8_MMA(ai, bj, At, Bt) do { __builtin_amdgcn_s_setprio(1); _Pragma("unroll") for (int m = 0; m < 4; ++m) _Pragma("unroll") for (int n = 0; n < 2; ++n) _Pragma("unroll") for (int k = 0; k < 2; ++k) \
;         acc[ai][bj][m][n] = __builtin_amdgcn_mfma_f32_16x16x32_bf16(Bt[n][k], At[m][k], acc[ai][bj][m][n], 0, 0, 0); __builtin_amdgcn_s_setprio(0); } while (0)
; #define PG8_WAIT_V(n) asm volatile("s_waitcnt vmcnt(" #n ")" ::: "memory")
; #define PG8_WAIT_L(n) asm volatile("s_waitcnt lgkmcnt(" #n ")" ::: "memory")
; #define PG8_BAR __builtin_amdgcn_s_barrier()
; #define PG8_SCHED __builtin_amdgcn_sched_barrier(0)
; template <class Epi, class Sched, bool ALIGN_EPI = false, bool SP2 = false>
; __device__ __forceinline__ void gemm_phase(PG8_LAS unsigned char* lds, const Gemm g, const Sched& S, const Epi& E) {
;     ...
;             PG8_LDB(B0, 0, 0); PG8_LDB(B1, 0, 1); PG8_SCHED; PG8_LDA(At, 0, 0); PG8_STAGE(PG8_SA(1, 1), a1 + hstepA, voffA);
;             PG8_WAIT_V(8); PG8_WAIT_L(0); PG8_BAR; PG8_MMA(0, 0, At, B0); PG8_MMA(0, 1, At, B1); PG8_BAR; PG8_SCHED;
;             PG8_LDA(At, 0, 1); PG8_STAGE(PG8_SB(0, 0), b2, voffB); PG8_STAGE(PG8_SB(0, 1), b2 + hstepB, voffB); PG8_STAGE(PG8_SA(0, 0), a2, voffA);
;             PG8_WAIT_V(8); PG8_WAIT_L(0); PG8_BAR; PG8_MMA(1, 0, At, B0); PG8_MMA(1, 1, At, B1); PG8_BAR; PG8_SCHED;
;             PG8_LDB(B0, 1, 0); PG8_LDB(B1, 1, 1); PG8_SCHED; PG8_LDA(At, 1, 0); PG8_STAGE(PG8_SA(0, 1), a2 + hstepA, voffA);
	s_mov_b32 m0, s48
	v_lshl_add_u64 v[190:191], s[46:47], 0, v[130:131]
	s_add_u32 s38, s46, 0x10000
	s_nop 1
	ds_read_b128 v[32:35], v145 offset:16384
	ds_read_b128 v[36:39], v145 offset:17408
	ds_read_b128 v[96:99], v145 offset:18432
	ds_read_b128 v[186:189], v145 offset:19456
	ds_read_b128 v[196:199], v145 offset:20480
	ds_read_b128 v[200:203], v145 offset:21504
	ds_read_b128 v[204:207], v145 offset:22528
	ds_read_b128 v[208:211], v145 offset:23552
	global_load_lds_dwordx4 v[190:191], off
	v_lshl_add_u64 v[252:253], s[46:47], 0, v[134:135]
	s_mov_b32 m0, s31
	s_addc_u32 s39, s47, 0
	global_load_lds_dwordx4 v[252:253], off
	s_mov_b32 m0, s44
	v_lshl_add_u64 v[194:195], s[50:51], 0, v[128:129]
	global_load_lds_dwordx4 v130, s[38:39]
	s_mov_b32 m0, s45
	v_lshl_add_u64 v[192:193], s[50:51], 0, v[132:133]
	global_load_lds_dwordx4 v134, s[38:39]
	s_mov_b32 m0, s9
	s_nop 0
	global_load_lds_dwordx4 v[194:195], off
	s_mov_b32 m0, s27
	s_nop 0
	global_load_lds_dwordx4 v[192:193], off
	s_waitcnt vmcnt(8)
	s_waitcnt lgkmcnt(0)
	s_barrier
	s_setprio 1
	s_waitcnt lgkmcnt(0)
	v_mfma_f32_16x16x32_bf16 v[0:3], v[104:107], v[204:207], v[0:3]
	v_mfma_f32_16x16x32_bf16 v[4:7], v[112:115], v[204:207], v[4:7]
	v_mfma_f32_16x16x32_bf16 v[146:149], v[104:107], v[32:35], v[146:149]
	v_mfma_f32_16x16x32_bf16 v[150:153], v[112:115], v[32:35], v[150:153]
	v_mfma_f32_16x16x32_bf16 v[154:157], v[104:107], v[96:99], v[154:157]
	v_mfma_f32_16x16x32_bf16 v[158:161], v[112:115], v[96:99], v[158:161]
	v_mfma_f32_16x16x32_bf16 v[162:165], v[104:107], v[196:199], v[162:165]
	v_mfma_f32_16x16x32_bf16 v[166:169], v[112:115], v[196:199], v[166:169]
	v_mfma_f32_16x16x32_bf16 v[0:3], v[108:111], v[208:211], v[0:3]
	v_mfma_f32_16x16x32_bf16 v[4:7], v[116:119], v[208:211], v[4:7]
	v_mfma_f32_16x16x32_bf16 v[146:149], v[108:111], v[36:39], v[146:149]
	v_mfma_f32_16x16x32_bf16 v[150:153], v[116:119], v[36:39], v[150:153]
	v_mfma_f32_16x16x32_bf16 v[154:157], v[108:111], v[186:189], v[154:157]
	v_mfma_f32_16x16x32_bf16 v[158:161], v[116:119], v[186:189], v[158:161]
	v_mfma_f32_16x16x32_bf16 v[162:165], v[108:111], v[200:203], v[162:165]
	v_mfma_f32_16x16x32_bf16 v[166:169], v[116:119], v[200:203], v[166:169]
	s_setprio 0
	s_setprio 1
	v_mfma_f32_16x16x32_bf16 v[8:11], v[120:123], v[32:35], v[8:11]
	v_mfma_f32_16x16x32_bf16 v[12:15], v[170:173], v[32:35], v[12:15]
	v_mfma_f32_16x16x32_bf16 v[24:27], v[120:123], v[96:99], v[24:27]
	v_mfma_f32_16x16x32_bf16 v[28:31], v[170:173], v[96:99], v[28:31]
	v_mfma_f32_16x16x32_bf16 v[32:35], v[120:123], v[196:199], v[60:63]
	v_mfma_f32_16x16x32_bf16 v[24:27], v[124:127], v[186:189], v[24:27]
	v_mfma_f32_16x16x32_bf16 v[28:31], v[174:177], v[186:189], v[28:31]
	v_mfma_f32_16x16x32_bf16 v[186:189], v[124:127], v[200:203], v[32:35]
	v_mfma_f32_16x16x32_bf16 v[32:35], v[170:173], v[196:199], v[100:103]
	v_mfma_f32_16x16x32_bf16 v[16:19], v[120:123], v[204:207], v[16:19]
	v_mfma_f32_16x16x32_bf16 v[8:11], v[124:127], v[36:39], v[8:11]
	v_mfma_f32_16x16x32_bf16 v[12:15], v[174:177], v[36:39], v[12:15]
	v_mfma_f32_16x16x32_bf16 v[196:199], v[174:177], v[200:203], v[32:35]
	v_mfma_f32_16x16x32_bf16 v[200:203], v[124:127], v[208:211], v[16:19]
	v_mfma_f32_16x16x32_bf16 v[16:19], v[170:173], v[204:207], v[20:23]
	v_mfma_f32_16x16x32_bf16 v[170:173], v[174:177], v[208:211], v[16:19]
	s_setprio 0
	s_barrier
	ds_read_b128 v[60:63], v224
	ds_read_b128 v[174:177], v224 offset:1024
	ds_read_b128 v[204:207], v224 offset:2048
	ds_read_b128 v[208:211], v224 offset:3072
	ds_read_b128 v[212:215], v228
	ds_read_b128 v[220:223], v228 offset:1024
	ds_read_b128 v[224:227], v228 offset:2048
	ds_read_b128 v[228:231], v228 offset:3072
	s_add_u32 s38, s50, 0x10000
	s_addc_u32 s39, s51, 0
	s_mov_b32 m0, s33
	ds_read_b128 v[16:19], v145 offset:32768
	ds_read_b128 v[20:23], v145 offset:33792
	ds_read_b128 v[108:111], v145 offset:34816
	ds_read_b128 v[232:235], v145 offset:35840
	ds_read_b128 v[236:239], v145 offset:36864
	ds_read_b128 v[240:243], v145 offset:37888
	ds_read_b128 v[244:247], v145 offset:38912
	ds_read_b128 v[248:251], v145 offset:39936
	global_load_lds_dwordx4 v128, s[38:39]
	s_mov_b32 m0, s42
	s_nop 0
	global_load_lds_dwordx4 v132, s[38:39]
	s_waitcnt vmcnt(8)
	s_waitcnt lgkmcnt(0)
	s_barrier
; #define PG8_STAGE(bufoff, gbase, voff) do { _Pragma("unroll") for (int _i = 0; _i < 2; ++_i) \
;         __builtin_amdgcn_global_load_lds((const unsigned*)((const char*)(gbase) + (voff)[_i]), (PG8_LAS unsigned*)(lds + (bufoff) + ldsw + _i * 8192), 16, 0, 0); } while (0)
; #define PG8_LDA(dst, b, h) do { _Pragma("unroll") for (int m = 0; m < 4; ++m) _Pragma("unroll") for (int k = 0; k < 2; ++k) dst[m][k] = *(const PG8_LAS bf16x8*)(lds + PG8_SA(b, h) + aoff + m * 2048 + k * 1024); } while (0)
; #define PG8_MMA(ai, bj, At, Bt) do { __builtin_amdgcn_s_setprio(1); _Pragma("unroll") for (int m = 0; m < 4; ++m) _Pragma("unroll") for (int n = 0; n < 2; ++n) _Pragma("unroll") for (int k = 0; k < 2; ++k) \
;         acc[ai][bj][m][n] = __builtin_amdgcn_mfma_f32_16x16x32_bf16(Bt[n][k], At[m][k], acc[ai][bj][m][n], 0, 0, 0); __builtin_amdgcn_s_setprio(0); } while (0)
; #define PG8_WAIT_V(n) asm volatile("s_waitcnt vmcnt(" #n ")" ::: "memory")
; #define PG8_WAIT_L(n) asm volatile("s_waitcnt lgkmcnt(" #n ")" ::: "memory")
; #define PG8_BAR __builtin_amdgcn_s_barrier()
; #define PG8_SCHED __builtin_amdgcn_sched_barrier(0)
; template <class Epi, class Sched, bool ALIGN_EPI = false, bool SP2 = false>
; __device__ __forceinline__ void gemm_phase(PG8_LAS unsigned char* lds, const Gemm g, const Sched& S, const Epi& E) {
;     ...
;             PG8_WAIT_V(8); PG8_WAIT_L(0); PG8_BAR; PG8_MMA(0, 0, At, B0); PG8_MMA(0, 1, At, B1); PG8_BAR; PG8_SCHED;
;             PG8_LDA(At, 1, 1); PG8_STAGE(PG8_SB(1, 0), b3, voffB); PG8_STAGE(PG8_SB(1, 1), b3 + hstepB, voffB); PG8_STAGE(PG8_SA(1, 0), a3, voffA);
;             PG8_WAIT_V(8); PG8_WAIT_L(0); PG8_BAR; PG8_MMA(1, 0, At, B0); PG8_MMA(1, 1, At, B1); PG8_BAR; PG8_SCHED;
	s_setprio 1
	s_waitcnt lgkmcnt(0)
	v_mfma_f32_16x16x32_bf16 v[32:35], v[60:63], v[16:19], v[64:67]
	v_mfma_f32_16x16x32_bf16 v[112:115], v[174:177], v[20:23], v[32:35]
	v_mfma_f32_16x16x32_bf16 v[32:35], v[204:207], v[16:19], v[68:71]
	v_mfma_f32_16x16x32_bf16 v[116:119], v[208:211], v[20:23], v[32:35]
	v_mfma_f32_16x16x32_bf16 v[32:35], v[60:63], v[108:111], v[72:75]
	v_mfma_f32_16x16x32_bf16 v[96:99], v[174:177], v[232:235], v[32:35]
	v_mfma_f32_16x16x32_bf16 v[32:35], v[204:207], v[108:111], v[76:79]
	v_mfma_f32_16x16x32_bf16 v[100:103], v[208:211], v[232:235], v[32:35]
	v_mfma_f32_16x16x32_bf16 v[32:35], v[60:63], v[236:239], v[80:83]
	v_mfma_f32_16x16x32_bf16 v[64:67], v[174:177], v[240:243], v[32:35]
	v_mfma_f32_16x16x32_bf16 v[32:35], v[204:207], v[236:239], v[84:87]
	v_mfma_f32_16x16x32_bf16 v[68:71], v[208:211], v[240:243], v[32:35]
	v_mfma_f32_16x16x32_bf16 v[32:35], v[60:63], v[244:247], v[88:91]
	v_mfma_f32_16x16x32_bf16 v[36:39], v[204:207], v[244:247], v[92:95]
	v_mfma_f32_16x16x32_bf16 v[32:35], v[174:177], v[248:251], v[32:35]
	v_mfma_f32_16x16x32_bf16 v[36:39], v[208:211], v[248:251], v[36:39]
	s_setprio 0
	s_setprio 1
	v_mfma_f32_16x16x32_bf16 v[72:75], v[212:215], v[16:19], v[216:219]
	v_mfma_f32_16x16x32_bf16 v[16:19], v[224:227], v[16:19], v[178:181]
	v_mfma_f32_16x16x32_bf16 v[124:127], v[228:231], v[20:23], v[16:19]
	v_mfma_f32_16x16x32_bf16 v[16:19], v[212:215], v[108:111], v[182:185]
	v_mfma_f32_16x16x32_bf16 v[104:107], v[220:223], v[232:235], v[16:19]
	v_mfma_f32_16x16x32_bf16 v[16:19], v[224:227], v[108:111], v[40:43]
	v_mfma_f32_16x16x32_bf16 v[108:111], v[228:231], v[232:235], v[16:19]
	v_mfma_f32_16x16x32_bf16 v[16:19], v[212:215], v[236:239], v[44:47]
	v_mfma_f32_16x16x32_bf16 v[120:123], v[220:223], v[20:23], v[72:75]
	v_mfma_f32_16x16x32_bf16 v[72:75], v[220:223], v[240:243], v[16:19]
	v_mfma_f32_16x16x32_bf16 v[16:19], v[224:227], v[236:239], v[48:51]
	v_mfma_f32_16x16x32_bf16 v[76:79], v[228:231], v[240:243], v[16:19]
	v_mfma_f32_16x16x32_bf16 v[16:19], v[212:215], v[244:247], v[52:55]
	v_mfma_f32_16x16x32_bf16 v[40:43], v[220:223], v[248:251], v[16:19]
	v_mfma_f32_16x16x32_bf16 v[16:19], v[224:227], v[244:247], v[56:59]
	v_mfma_f32_16x16x32_bf16 v[44:47], v[228:231], v[248:251], v[16:19]
	s_setprio 0
	s_barrier
	s_mov_b32 m0, s64
	s_nop 3
	v_lshl_add_u64 v[16:17], v[190:191], 0, s[16:17]
	s_add_u32 s38, s46, 0x10080
	ds_read_b128 v[56:59], v145 offset:49152
	ds_read_b128 v[92:95], v145 offset:50176
	ds_read_b128 v[178:181], v145 offset:51200
	ds_read_b128 v[182:185], v145 offset:52224
	ds_read_b128 v[216:219], v145 offset:53248
	ds_read_b128 v[232:235], v145 offset:54272
	ds_read_b128 v[236:239], v145 offset:55296
	ds_read_b128 v[240:243], v145 offset:56320
	global_load_lds_dwordx4 v[16:17], off
	v_lshl_add_u64 v[16:17], v[252:253], 0, s[16:17]
	s_mov_b32 m0, s49
	s_addc_u32 s39, s47, 0
	global_load_lds_dwordx4 v[16:17], off
	s_mov_b32 m0, s40
	s_nop 0
	global_load_lds_dwordx4 v130, s[38:39]
	s_mov_b32 m0, s41
	s_nop 0
	global_load_lds_dwordx4 v134, s[38:39]
	v_lshl_add_u64 v[16:17], v[194:195], 0, s[16:17]
	s_mov_b32 m0, s53
	s_nop 0
	global_load_lds_dwordx4 v[16:17], off
	v_lshl_add_u64 v[16:17], v[192:193], 0, s[16:17]
	s_mov_b32 m0, s56
	s_nop 0
	global_load_lds_dwordx4 v[16:17], off
	s_waitcnt vmcnt(8)
	s_waitcnt lgkmcnt(0)
	s_barrier
	s_setprio 1
	s_waitcnt lgkmcnt(0)
	v_mfma_f32_16x16x32_bf16 v[16:19], v[60:63], v[56:59], v[146:149]
	v_mfma_f32_16x16x32_bf16 v[80:83], v[174:177], v[92:95], v[16:19]
	v_mfma_f32_16x16x32_bf16 v[16:19], v[204:207], v[56:59], v[150:153]
	v_mfma_f32_16x16x32_bf16 v[84:87], v[208:211], v[92:95], v[16:19]
	v_mfma_f32_16x16x32_bf16 v[16:19], v[60:63], v[178:181], v[154:157]
	v_mfma_f32_16x16x32_bf16 v[48:51], v[174:177], v[182:185], v[16:19]
	v_mfma_f32_16x16x32_bf16 v[16:19], v[204:207], v[178:181], v[158:161]
	v_mfma_f32_16x16x32_bf16 v[52:55], v[208:211], v[182:185], v[16:19]
	v_mfma_f32_16x16x32_bf16 v[16:19], v[60:63], v[216:219], v[162:165]
	v_mfma_f32_16x16x32_bf16 v[20:23], v[204:207], v[216:219], v[166:169]
	v_mfma_f32_16x16x32_bf16 v[0:3], v[60:63], v[236:239], v[0:3]
	v_mfma_f32_16x16x32_bf16 v[4:7], v[204:207], v[236:239], v[4:7]
	v_mfma_f32_16x16x32_bf16 v[16:19], v[174:177], v[232:235], v[16:19]
	v_mfma_f32_16x16x32_bf16 v[20:23], v[208:211], v[232:235], v[20:23]
	v_mfma_f32_16x16x32_bf16 v[0:3], v[174:177], v[240:243], v[0:3]
	v_mfma_f32_16x16x32_bf16 v[4:7], v[208:211], v[240:243], v[4:7]
	s_setprio 0
	s_setprio 1
	v_mfma_f32_16x16x32_bf16 v[8:11], v[212:215], v[56:59], v[8:11]
	v_mfma_f32_16x16x32_bf16 v[88:91], v[220:223], v[92:95], v[8:11]
	v_mfma_f32_16x16x32_bf16 v[8:11], v[224:227], v[56:59], v[12:15]
	v_mfma_f32_16x16x32_bf16 v[92:95], v[228:231], v[92:95], v[8:11]
	v_mfma_f32_16x16x32_bf16 v[8:11], v[212:215], v[178:181], v[24:27]
	v_mfma_f32_16x16x32_bf16 v[56:59], v[220:223], v[182:185], v[8:11]
	v_mfma_f32_16x16x32_bf16 v[8:11], v[224:227], v[178:181], v[28:31]
	v_mfma_f32_16x16x32_bf16 v[60:63], v[228:231], v[182:185], v[8:11]
	v_mfma_f32_16x16x32_bf16 v[8:11], v[212:215], v[216:219], v[186:189]
	v_mfma_f32_16x16x32_bf16 v[24:27], v[220:223], v[232:235], v[8:11]
	v_mfma_f32_16x16x32_bf16 v[8:11], v[224:227], v[216:219], v[196:199]
	v_mfma_f32_16x16x32_bf16 v[28:31], v[228:231], v[232:235], v[8:11]
	v_mfma_f32_16x16x32_bf16 v[8:11], v[212:215], v[236:239], v[200:203]
	v_mfma_f32_16x16x32_bf16 v[12:15], v[224:227], v[236:239], v[170:173]
	v_mfma_f32_16x16x32_bf16 v[8:11], v[220:223], v[240:243], v[8:11]
	v_mfma_f32_16x16x32_bf16 v[12:15], v[228:231], v[240:243], v[12:15]
	s_setprio 0
	s_barrier
	s_andn2_b64 vcc, exec, s[18:19]
	s_cbranch_vccnz .LBB0_165
	s_barrier

; #define PG8_STAGE(bufoff, gbase, voff) do { _Pragma("unroll") for (int _i = 0; _i < 2; ++_i) \
;         __builtin_amdgcn_global_load_lds((const unsigned*)((const char*)(gbase) + (voff)[_i]), (PG8_LAS unsigned*)(lds + (bufoff) + ldsw + _i * 8192), 16, 0, 0); } while (0)
; #define PG8_WAIT_V(n) asm volatile("s_waitcnt vmcnt(" #n ")" ::: "memory")
; #define PG8_BAR __builtin_amdgcn_s_barrier()
; template <class Epi, class Sched, bool ALIGN_EPI = false, bool SP2 = false>
; __device__ __forceinline__ void gemm_phase(PG8_LAS unsigned char* lds, const Gemm g, const Sched& S, const Epi& E) {
;     ...
;         PG8_STAGE(PG8_SB(0, 0), cB, voffB); PG8_STAGE(PG8_SB(0, 1), cB + hstepB, voffB); PG8_STAGE(PG8_SA(0, 0), cA, voffA); PG8_STAGE(PG8_SA(0, 1), cA + hstepA, voffA);
;         if (wr == 1) PG8_BAR;
;         PG8_WAIT_V(2); PG8_BAR;
;         PG8_STAGE(PG8_SB(1, 0), cB + kstep, voffB); PG8_STAGE(PG8_SA(1, 0), cA + kstep, voffA); PG8_STAGE(PG8_SB(1, 1), cB + hstepB + kstep, voffB);
;         PG8_WAIT_V(6); PG8_BAR;
.LBB0_176:
	s_lshl_b32 s16, s16, 5
	s_and_b32 s42, s16, 0x60
	s_mov_b64 s[16:17], 0x80
	s_add_i32 m0, s8, 0x18000
	v_lshl_add_u64 v[6:7], v[6:7], 0, s[16:17]
	s_lshl_b32 s41, s1, 6
	s_lshl_b32 s1, s1, 13
	s_lshl_b32 s19, s42, 7
	s_waitcnt vmcnt(2)
	s_barrier
	global_load_lds_dwordx4 v[6:7], off
	v_lshl_add_u64 v[4:5], v[4:5], 0, s[16:17]
	s_add_i32 m0, s8, 0x1a000
	s_add_i32 s43, s8, 0x8000
	s_add_i32 s50, s8, 0xa000
	global_load_lds_dwordx4 v[4:5], off
	v_lshl_add_u64 v[0:1], v[0:1], 0, s[16:17]
	s_mov_b32 m0, s43
	s_add_u32 s20, s36, 0x40080
	global_load_lds_dwordx4 v[0:1], off
	v_lshl_add_u64 v[0:1], v[2:3], 0, s[16:17]
	s_mov_b32 m0, s50
	s_addc_u32 s21, s37, 0
	global_load_lds_dwordx4 v[0:1], off
	s_add_i32 m0, s8, 0x1c000
	s_nop 0
	global_load_lds_dwordx4 v130, s[20:21]
	v_lshl_add_u64 v[0:1], s[20:21], 0, v[134:135]
	s_add_i32 m0, s8, 0x1e000
	v_bfe_u32 v144, v8, 4, 2
	global_load_lds_dwordx4 v[0:1], off
	v_and_b32_e32 v145, 15, v8
	v_lshlrev_b32_e32 v0, 4, v144
	v_lshlrev_b32_e32 v1, 2, v8
	v_lshl_or_b32 v0, v145, 6, v0
	v_and_b32_e32 v1, 32, v1
	v_bitop3_b32 v2, v0, s1, v1 bitop3:0xde
	v_bitop3_b32 v146, v0, s19, v1 bitop3:0xde
	v_lshlrev_b32_e32 v0, 14, v9
	v_and_b32_e32 v0, 0xffff8000, v0
	v_lshl_add_u32 v0, v10, 11, v0
	v_and_b32_e32 v1, 1, v9
	v_lshl_or_b32 v0, v1, 6, v0
	v_lshl_add_u32 v136, v11, 1, v0
	v_lshlrev_b32_e32 v0, 14, v12
	v_and_b32_e32 v0, 0xffff8000, v0
	s_waitcnt vmcnt(6)
	s_cmpk_lt_u32 s18, 0x100
	v_lshl_add_u32 v0, v13, 11, v0
	v_and_b32_e32 v1, 1, v12
	s_cselect_b64 s[18:19], -1, 0
	v_lshl_or_b32 v0, v1, 6, v0
	s_add_i32 s53, 0, 0x10000
	s_add_i32 s56, 0, 0x14000
	s_sext_i32_i8 s59, s0
	s_ashr_i32 s51, s88, 31
	s_mov_b32 s52, s88
	v_mov_b32_e32 v137, v131
	v_lshl_add_u32 v138, v14, 1, v0
	v_mov_b32_e32 v139, v131
	v_mov_b64_e32 v[140:141], 0x100
	v_mov_b64_e32 v[142:143], 0xff
	v_add_u32_e32 v147, s53, v146
	v_add_u32_e32 v148, s56, v146
	v_add_u32_e32 v149, 0, v2
	s_mov_b32 s57, 0xa0000
	s_mov_b64 s[20:21], 0xb0000
	s_mov_b32 s58, 0xb0000
	s_barrier
	s_branch .LBB0_179

; #define PG8_STAGE(bufoff, gbase, voff) do { _Pragma("unroll") for (int _i = 0; _i < 2; ++_i) \
;         __builtin_amdgcn_global_load_lds((const unsigned*)((const char*)(gbase) + (voff)[_i]), (PG8_LAS unsigned*)(lds + (bufoff) + ldsw + _i * 8192), 16, 0, 0); } while (0)
; #define PG8_LDA(dst, b, h) do { _Pragma("unroll") for (int m = 0; m < 4; ++m) _Pragma("unroll") for (int k = 0; k < 2; ++k) dst[m][k] = *(const PG8_LAS bf16x8*)(lds + PG8_SA(b, h) + aoff + m * 2048 + k * 1024); } while (0)
; #define PG8_LDB(dst, b, h) do { _Pragma("unroll") for (int n = 0; n < 2; ++n) _Pragma("unroll") for (int k = 0; k < 2; ++k) dst[n][k] = *(const PG8_LAS bf16x8*)(lds + PG8_SB(b, h) + boff + n * 2048 + k * 1024); } while (0)
; #define PG8_MMA(ai, bj, At, Bt) do { __builtin_amdgcn_s_setprio(1); _Pragma("unroll") for (int m = 0; m < 4; ++m) _Pragma("unroll") for (int n = 0; n < 2; ++n) _Pragma("unroll") for (int k = 0; k < 2; ++k) \
;         acc[ai][bj][m][n] = __builtin_amdgcn_mfma_f32_16x16x32_bf16(Bt[n][k], At[m][k], acc[ai][bj][m][n], 0, 0, 0); __builtin_amdgcn_s_setprio(0); } while (0)
; #define PG8_WAIT_V(n) asm volatile("s_waitcnt vmcnt(" #n ")" ::: "memory")
; #define PG8_WAIT_L(n) asm volatile("s_waitcnt lgkmcnt(" #n ")" ::: "memory")
; #define PG8_BAR __builtin_amdgcn_s_barrier()
; #define PG8_SCHED __builtin_amdgcn_sched_barrier(0)
; template <class Epi, class Sched, bool ALIGN_EPI = false, bool SP2 = false>
; __device__ __forceinline__ void gemm_phase(PG8_LAS unsigned char* lds, const Gemm g, const Sched& S, const Epi& E) {
;     ...
;             PG8_LDB(B0, 0, 0); PG8_LDB(B1, 0, 1); PG8_SCHED; PG8_LDA(At, 0, 0); PG8_STAGE(PG8_SA(1, 1), a1 + hstepA, voffA);
;             PG8_WAIT_V(8); PG8_WAIT_L(0); PG8_BAR; PG8_MMA(0, 0, At, B0); PG8_MMA(0, 1, At, B1); PG8_BAR; PG8_SCHED;
;             PG8_LDA(At, 0, 1); PG8_STAGE(PG8_SB(0, 0), b2, voffB); PG8_STAGE(PG8_SB(0, 1), b2 + hstepB, voffB); PG8_STAGE(PG8_SA(0, 0), a2, voffA);
;             PG8_WAIT_V(8); PG8_WAIT_L(0); PG8_BAR; PG8_MMA(1, 0, At, B0); PG8_MMA(1, 1, At, B1); PG8_BAR; PG8_SCHED;
.LBB0_186:
	ds_read_b128 v[150:153], v147
	ds_read_b128 v[154:157], v147 offset:1024
	ds_read_b128 v[158:161], v147 offset:2048
	ds_read_b128 v[162:165], v147 offset:3072
	ds_read_b128 v[166:169], v148
	ds_read_b128 v[170:173], v148 offset:1024
	ds_read_b128 v[174:177], v148 offset:2048
	ds_read_b128 v[178:181], v148 offset:3072
	s_add_u32 s36, s34, 0xfffc0080
	s_addc_u32 s37, s35, -1
	s_cmp_eq_u32 s64, 12
	s_cselect_b32 s39, s27, s37
	s_cselect_b32 s38, s60, s36
	s_cselect_b32 s37, s25, s63
	s_cselect_b32 s36, s61, s62
	s_add_i32 m0, s8, 0xc000
	ds_read_b128 v[182:185], v149
	ds_read_b128 v[186:189], v149 offset:1024
	ds_read_b128 v[196:199], v149 offset:2048
	ds_read_b128 v[200:203], v149 offset:3072
	ds_read_b128 v[204:207], v149 offset:4096
	ds_read_b128 v[208:211], v149 offset:5120
	ds_read_b128 v[212:215], v149 offset:6144
	ds_read_b128 v[216:219], v149 offset:7168
	global_load_lds_dwordx4 v136, s[34:35]
	s_add_i32 m0, s8, 0xe000
	s_nop 0
	global_load_lds_dwordx4 v138, s[34:35]
	s_waitcnt vmcnt(8)
	s_waitcnt lgkmcnt(0)
	s_barrier
	s_setprio 1
	s_waitcnt lgkmcnt(0)
	v_mfma_f32_16x16x32_bf16 v[124:127], v[150:153], v[182:185], v[124:127]
	v_mfma_f32_16x16x32_bf16 v[120:123], v[158:161], v[182:185], v[120:123]
	v_mfma_f32_16x16x32_bf16 v[116:119], v[150:153], v[196:199], v[116:119]
	v_mfma_f32_16x16x32_bf16 v[112:115], v[158:161], v[196:199], v[112:115]
	v_mfma_f32_16x16x32_bf16 v[100:103], v[150:153], v[204:207], v[100:103]
	v_mfma_f32_16x16x32_bf16 v[96:99], v[158:161], v[204:207], v[96:99]
	v_mfma_f32_16x16x32_bf16 v[84:87], v[150:153], v[212:215], v[84:87]
	v_mfma_f32_16x16x32_bf16 v[80:83], v[158:161], v[212:215], v[80:83]
	v_mfma_f32_16x16x32_bf16 v[124:127], v[154:157], v[186:189], v[124:127]
	v_mfma_f32_16x16x32_bf16 v[120:123], v[162:165], v[186:189], v[120:123]
	v_mfma_f32_16x16x32_bf16 v[116:119], v[154:157], v[200:203], v[116:119]
	v_mfma_f32_16x16x32_bf16 v[112:115], v[162:165], v[200:203], v[112:115]
	v_mfma_f32_16x16x32_bf16 v[100:103], v[154:157], v[208:211], v[100:103]
	v_mfma_f32_16x16x32_bf16 v[96:99], v[162:165], v[208:211], v[96:99]
	v_mfma_f32_16x16x32_bf16 v[84:87], v[154:157], v[216:219], v[84:87]
	v_mfma_f32_16x16x32_bf16 v[80:83], v[162:165], v[216:219], v[80:83]
	s_setprio 0
	s_setprio 1
	v_mfma_f32_16x16x32_bf16 v[108:111], v[166:169], v[182:185], v[108:111]
	v_mfma_f32_16x16x32_bf16 v[104:107], v[174:177], v[182:185], v[104:107]
	v_mfma_f32_16x16x32_bf16 v[92:95], v[166:169], v[196:199], v[92:95]
	v_mfma_f32_16x16x32_bf16 v[88:91], v[174:177], v[196:199], v[88:91]
	v_mfma_f32_16x16x32_bf16 v[76:79], v[166:169], v[204:207], v[76:79]
	v_mfma_f32_16x16x32_bf16 v[72:75], v[174:177], v[204:207], v[72:75]
	v_mfma_f32_16x16x32_bf16 v[68:71], v[166:169], v[212:215], v[68:71]
	v_mfma_f32_16x16x32_bf16 v[64:67], v[174:177], v[212:215], v[64:67]
	v_mfma_f32_16x16x32_bf16 v[108:111], v[170:173], v[186:189], v[108:111]
	v_mfma_f32_16x16x32_bf16 v[104:107], v[178:181], v[186:189], v[104:107]
	v_mfma_f32_16x16x32_bf16 v[92:95], v[170:173], v[200:203], v[92:95]
	v_mfma_f32_16x16x32_bf16 v[88:91], v[178:181], v[200:203], v[88:91]
	v_mfma_f32_16x16x32_bf16 v[76:79], v[170:173], v[208:211], v[76:79]
	v_mfma_f32_16x16x32_bf16 v[72:75], v[178:181], v[208:211], v[72:75]
	v_mfma_f32_16x16x32_bf16 v[68:71], v[170:173], v[216:219], v[68:71]
	v_mfma_f32_16x16x32_bf16 v[64:67], v[178:181], v[216:219], v[64:67]
	s_setprio 0
	s_barrier
	s_add_i32 s44, s53, s3
	v_lshl_add_u64 v[190:191], s[36:37], 0, v[130:131]
	s_mov_b32 m0, s44
	ds_read_b128 v[182:185], v149 offset:16384
	ds_read_b128 v[186:189], v149 offset:17408
	ds_read_b128 v[196:199], v149 offset:18432
	ds_read_b128 v[200:203], v149 offset:19456
	ds_read_b128 v[204:207], v149 offset:20480
	ds_read_b128 v[208:211], v149 offset:21504
	ds_read_b128 v[212:215], v149 offset:22528
	ds_read_b128 v[216:219], v149 offset:23552
	global_load_lds_dwordx4 v[190:191], off
	s_add_i32 m0, s44, 0x2000
	s_add_u32 s44, s36, 0x40000
	v_lshl_add_u64 v[192:193], s[36:37], 0, v[134:135]
	s_addc_u32 s45, s37, 0
	s_add_i32 s48, s56, s3
	global_load_lds_dwordx4 v[192:193], off
	s_mov_b32 m0, s48
	v_lshl_add_u64 v[220:221], s[38:39], 0, v[132:133]
	global_load_lds_dwordx4 v130, s[44:45]
	s_add_i32 m0, s48, 0x2000
	s_nop 0
	global_load_lds_dwordx4 v134, s[44:45]
	v_lshl_add_u64 v[194:195], s[38:39], 0, v[128:129]
	s_mov_b32 m0, s8
	s_nop 0
	global_load_lds_dwordx4 v[194:195], off
	s_mov_b32 m0, s9
	s_nop 0
	global_load_lds_dwordx4 v[220:221], off
	s_waitcnt vmcnt(8)
	s_waitcnt lgkmcnt(0)
	s_barrier
; #define PG8_STAGE(bufoff, gbase, voff) do { _Pragma("unroll") for (int _i = 0; _i < 2; ++_i) \
;         __builtin_amdgcn_global_load_lds((const unsigned*)((const char*)(gbase) + (voff)[_i]), (PG8_LAS unsigned*)(lds + (bufoff) + ldsw + _i * 8192), 16, 0, 0); } while (0)
; #define PG8_LDA(dst, b, h) do { _Pragma("unroll") for (int m = 0; m < 4; ++m) _Pragma("unroll") for (int k = 0; k < 2; ++k) dst[m][k] = *(const PG8_LAS bf16x8*)(lds + PG8_SA(b, h) + aoff + m * 2048 + k * 1024); } while (0)
; #define PG8_LDB(dst, b, h) do { _Pragma("unroll") for (int n = 0; n < 2; ++n) _Pragma("unroll") for (int k = 0; k < 2; ++k) dst[n][k] = *(const PG8_LAS bf16x8*)(lds + PG8_SB(b, h) + boff + n * 2048 + k * 1024); } while (0)
; #define PG8_MMA(ai, bj, At, Bt) do { __builtin_amdgcn_s_setprio(1); _Pragma("unroll") for (int m = 0; m < 4; ++m) _Pragma("unroll") for (int n = 0; n < 2; ++n) _Pragma("unroll") for (int k = 0; k < 2; ++k) \
;         acc[ai][bj][m][n] = __builtin_amdgcn_mfma_f32_16x16x32_bf16(Bt[n][k], At[m][k], acc[ai][bj][m][n], 0, 0, 0); __builtin_amdgcn_s_setprio(0); } while (0)
; #define PG8_WAIT_V(n) asm volatile("s_waitcnt vmcnt(" #n ")" ::: "memory")
; #define PG8_WAIT_L(n) asm volatile("s_waitcnt lgkmcnt(" #n ")" ::: "memory")
; #define PG8_BAR __builtin_amdgcn_s_barrier()
; #define PG8_SCHED __builtin_amdgcn_sched_barrier(0)
; template <class Epi, class Sched, bool ALIGN_EPI = false, bool SP2 = false>
; __device__ __forceinline__ void gemm_phase(PG8_LAS unsigned char* lds, const Gemm g, const Sched& S, const Epi& E) {
;     ...
;             PG8_WAIT_V(8); PG8_WAIT_L(0); PG8_BAR; PG8_MMA(1, 0, At, B0); PG8_MMA(1, 1, At, B1); PG8_BAR; PG8_SCHED;
;             PG8_LDB(B0, 1, 0); PG8_LDB(B1, 1, 1); PG8_SCHED; PG8_LDA(At, 1, 0); PG8_STAGE(PG8_SA(0, 1), a2 + hstepA, voffA);
;             PG8_WAIT_V(8); PG8_WAIT_L(0); PG8_BAR; PG8_MMA(0, 0, At, B0); PG8_MMA(0, 1, At, B1); PG8_BAR; PG8_SCHED;
	s_setprio 1
	s_waitcnt lgkmcnt(0)
	v_mfma_f32_16x16x32_bf16 v[60:63], v[150:153], v[182:185], v[60:63]
	v_mfma_f32_16x16x32_bf16 v[56:59], v[158:161], v[182:185], v[56:59]
	v_mfma_f32_16x16x32_bf16 v[52:55], v[150:153], v[196:199], v[52:55]
	v_mfma_f32_16x16x32_bf16 v[48:51], v[158:161], v[196:199], v[48:51]
	v_mfma_f32_16x16x32_bf16 v[36:39], v[150:153], v[204:207], v[36:39]
	v_mfma_f32_16x16x32_bf16 v[32:35], v[158:161], v[204:207], v[32:35]
	v_mfma_f32_16x16x32_bf16 v[20:23], v[150:153], v[212:215], v[20:23]
	v_mfma_f32_16x16x32_bf16 v[16:19], v[158:161], v[212:215], v[16:19]
	v_mfma_f32_16x16x32_bf16 v[60:63], v[154:157], v[186:189], v[60:63]
	v_mfma_f32_16x16x32_bf16 v[56:59], v[162:165], v[186:189], v[56:59]
	v_mfma_f32_16x16x32_bf16 v[52:55], v[154:157], v[200:203], v[52:55]
	v_mfma_f32_16x16x32_bf16 v[48:51], v[162:165], v[200:203], v[48:51]
	v_mfma_f32_16x16x32_bf16 v[36:39], v[154:157], v[208:211], v[36:39]
	v_mfma_f32_16x16x32_bf16 v[32:35], v[162:165], v[208:211], v[32:35]
	v_mfma_f32_16x16x32_bf16 v[20:23], v[154:157], v[216:219], v[20:23]
	v_mfma_f32_16x16x32_bf16 v[16:19], v[162:165], v[216:219], v[16:19]
	s_setprio 0
	s_setprio 1
	v_mfma_f32_16x16x32_bf16 v[44:47], v[166:169], v[182:185], v[44:47]
	v_mfma_f32_16x16x32_bf16 v[40:43], v[174:177], v[182:185], v[40:43]
	v_mfma_f32_16x16x32_bf16 v[28:31], v[166:169], v[196:199], v[28:31]
	v_mfma_f32_16x16x32_bf16 v[24:27], v[174:177], v[196:199], v[24:27]
	v_mfma_f32_16x16x32_bf16 v[12:15], v[166:169], v[204:207], v[12:15]
	v_mfma_f32_16x16x32_bf16 v[8:11], v[174:177], v[204:207], v[8:11]
	v_mfma_f32_16x16x32_bf16 v[4:7], v[166:169], v[212:215], v[4:7]
	v_mfma_f32_16x16x32_bf16 v[0:3], v[174:177], v[212:215], v[0:3]
	v_mfma_f32_16x16x32_bf16 v[44:47], v[170:173], v[186:189], v[44:47]
	v_mfma_f32_16x16x32_bf16 v[40:43], v[178:181], v[186:189], v[40:43]
	v_mfma_f32_16x16x32_bf16 v[28:31], v[170:173], v[200:203], v[28:31]
	v_mfma_f32_16x16x32_bf16 v[24:27], v[178:181], v[200:203], v[24:27]
	v_mfma_f32_16x16x32_bf16 v[12:15], v[170:173], v[208:211], v[12:15]
	v_mfma_f32_16x16x32_bf16 v[8:11], v[178:181], v[208:211], v[8:11]
	v_mfma_f32_16x16x32_bf16 v[4:7], v[170:173], v[216:219], v[4:7]
	v_mfma_f32_16x16x32_bf16 v[0:3], v[178:181], v[216:219], v[0:3]
	s_setprio 0
	s_barrier
	s_add_i32 s44, 0, 0x18000
	s_add_i32 s45, 0, 0x1c000
	v_add_u32_e32 v162, s44, v146
	v_add_u32_e32 v178, s45, v146
	ds_read_b128 v[150:153], v162
	ds_read_b128 v[154:157], v162 offset:1024
	ds_read_b128 v[158:161], v162 offset:2048
	ds_read_b128 v[162:165], v162 offset:3072
	ds_read_b128 v[166:169], v178
	ds_read_b128 v[170:173], v178 offset:1024
	ds_read_b128 v[174:177], v178 offset:2048
	ds_read_b128 v[178:181], v178 offset:3072
	s_add_u32 s38, s38, 0x40000
	s_addc_u32 s39, s39, 0
	s_mov_b32 m0, s23
	ds_read_b128 v[182:185], v149 offset:32768
	ds_read_b128 v[186:189], v149 offset:33792
	ds_read_b128 v[196:199], v149 offset:34816
	ds_read_b128 v[200:203], v149 offset:35840
	ds_read_b128 v[204:207], v149 offset:36864
	ds_read_b128 v[208:211], v149 offset:37888
	ds_read_b128 v[212:215], v149 offset:38912
	ds_read_b128 v[216:219], v149 offset:39936
	global_load_lds_dwordx4 v128, s[38:39]
	s_mov_b32 m0, s33
	s_nop 0
	global_load_lds_dwordx4 v132, s[38:39]
	s_waitcnt vmcnt(8)
	s_waitcnt lgkmcnt(0)
	s_barrier
	s_setprio 1
	s_waitcnt lgkmcnt(0)
	v_mfma_f32_16x16x32_bf16 v[124:127], v[150:153], v[182:185], v[124:127]
	v_mfma_f32_16x16x32_bf16 v[120:123], v[158:161], v[182:185], v[120:123]
	v_mfma_f32_16x16x32_bf16 v[116:119], v[150:153], v[196:199], v[116:119]
	v_mfma_f32_16x16x32_bf16 v[112:115], v[158:161], v[196:199], v[112:115]
	v_mfma_f32_16x16x32_bf16 v[100:103], v[150:153], v[204:207], v[100:103]
	v_mfma_f32_16x16x32_bf16 v[96:99], v[158:161], v[204:207], v[96:99]
	v_mfma_f32_16x16x32_bf16 v[84:87], v[150:153], v[212:215], v[84:87]
	v_mfma_f32_16x16x32_bf16 v[80:83], v[158:161], v[212:215], v[80:83]
	v_mfma_f32_16x16x32_bf16 v[124:127], v[154:157], v[186:189], v[124:127]
	v_mfma_f32_16x16x32_bf16 v[120:123], v[162:165], v[186:189], v[120:123]
	v_mfma_f32_16x16x32_bf16 v[116:119], v[154:157], v[200:203], v[116:119]
	v_mfma_f32_16x16x32_bf16 v[112:115], v[162:165], v[200:203], v[112:115]
	v_mfma_f32_16x16x32_bf16 v[100:103], v[154:157], v[208:211], v[100:103]
	v_mfma_f32_16x16x32_bf16 v[96:99], v[162:165], v[208:211], v[96:99]
	v_mfma_f32_16x16x32_bf16 v[84:87], v[154:157], v[216:219], v[84:87]
	v_mfma_f32_16x16x32_bf16 v[80:83], v[162:165], v[216:219], v[80:83]
	s_setprio 0
	s_setprio 1
	v_mfma_f32_16x16x32_bf16 v[108:111], v[166:169], v[182:185], v[108:111]
	v_mfma_f32_16x16x32_bf16 v[104:107], v[174:177], v[182:185], v[104:107]
	v_mfma_f32_16x16x32_bf16 v[92:95], v[166:169], v[196:199], v[92:95]
	v_mfma_f32_16x16x32_bf16 v[88:91], v[174:177], v[196:199], v[88:91]
	v_mfma_f32_16x16x32_bf16 v[76:79], v[166:169], v[204:207], v[76:79]
	v_mfma_f32_16x16x32_bf16 v[72:75], v[174:177], v[204:207], v[72:75]
	v_mfma_f32_16x16x32_bf16 v[68:71], v[166:169], v[212:215], v[68:71]
	v_mfma_f32_16x16x32_bf16 v[64:67], v[174:177], v[212:215], v[64:67]
	v_mfma_f32_16x16x32_bf16 v[108:111], v[170:173], v[186:189], v[108:111]
	v_mfma_f32_16x16x32_bf16 v[104:107], v[178:181], v[186:189], v[104:107]
	v_mfma_f32_16x16x32_bf16 v[92:95], v[170:173], v[200:203], v[92:95]
	v_mfma_f32_16x16x32_bf16 v[88:91], v[178:181], v[200:203], v[88:91]
	v_mfma_f32_16x16x32_bf16 v[76:79], v[170:173], v[208:211], v[76:79]
	v_mfma_f32_16x16x32_bf16 v[72:75], v[178:181], v[208:211], v[72:75]
	v_mfma_f32_16x16x32_bf16 v[68:71], v[170:173], v[216:219], v[68:71]
	v_mfma_f32_16x16x32_bf16 v[64:67], v[178:181], v[216:219], v[64:67]
	s_setprio 0
	s_barrier
; #define PG8_STAGE(bufoff, gbase, voff) do { _Pragma("unroll") for (int _i = 0; _i < 2; ++_i) \
;         __builtin_amdgcn_global_load_lds((const unsigned*)((const char*)(gbase) + (voff)[_i]), (PG8_LAS unsigned*)(lds + (bufoff) + ldsw + _i * 8192), 16, 0, 0); } while (0)
; #define PG8_LDA(dst, b, h) do { _Pragma("unroll") for (int m = 0; m < 4; ++m) _Pragma("unroll") for (int k = 0; k < 2; ++k) dst[m][k] = *(const PG8_LAS bf16x8*)(lds + PG8_SA(b, h) + aoff + m * 2048 + k * 1024); } while (0)
; #define PG8_MMA(ai, bj, At, Bt) do { __builtin_amdgcn_s_setprio(1); _Pragma("unroll") for (int m = 0; m < 4; ++m) _Pragma("unroll") for (int n = 0; n < 2; ++n) _Pragma("unroll") for (int k = 0; k < 2; ++k) \
;         acc[ai][bj][m][n] = __builtin_amdgcn_mfma_f32_16x16x32_bf16(Bt[n][k], At[m][k], acc[ai][bj][m][n], 0, 0, 0); __builtin_amdgcn_s_setprio(0); } while (0)
; #define PG8_WAIT_V(n) asm volatile("s_waitcnt vmcnt(" #n ")" ::: "memory")
; #define PG8_WAIT_L(n) asm volatile("s_waitcnt lgkmcnt(" #n ")" ::: "memory")
; #define PG8_BAR __builtin_amdgcn_s_barrier()
; #define PG8_SCHED __builtin_amdgcn_sched_barrier(0)
; template <class Epi, class Sched, bool ALIGN_EPI = false, bool SP2 = false>
; __device__ __forceinline__ void gemm_phase(PG8_LAS unsigned char* lds, const Gemm g, const Sched& S, const Epi& E) {
;     ...
;             PG8_WAIT_V(8); PG8_WAIT_L(0); PG8_BAR; PG8_MMA(0, 0, At, B0); PG8_MMA(0, 1, At, B1); PG8_BAR; PG8_SCHED;
;             PG8_LDA(At, 1, 1); PG8_STAGE(PG8_SB(1, 0), b3, voffB); PG8_STAGE(PG8_SB(1, 1), b3 + hstepB, voffB); PG8_STAGE(PG8_SA(1, 0), a3, voffA);
;             PG8_WAIT_V(8); PG8_WAIT_L(0); PG8_BAR; PG8_MMA(1, 0, At, B0); PG8_MMA(1, 1, At, B1); PG8_BAR; PG8_SCHED;
	s_add_i32 s38, s44, s3
	v_lshl_add_u64 v[190:191], v[190:191], 0, s[16:17]
	s_mov_b32 m0, s38
	ds_read_b128 v[182:185], v149 offset:49152
	ds_read_b128 v[186:189], v149 offset:50176
	ds_read_b128 v[196:199], v149 offset:51200
	ds_read_b128 v[200:203], v149 offset:52224
	ds_read_b128 v[204:207], v149 offset:53248
	ds_read_b128 v[208:211], v149 offset:54272
	ds_read_b128 v[212:215], v149 offset:55296
	ds_read_b128 v[216:219], v149 offset:56320
	global_load_lds_dwordx4 v[190:191], off
	s_add_i32 m0, s38, 0x2000
	s_add_u32 s36, s36, 0x40080
	v_lshl_add_u64 v[190:191], v[192:193], 0, s[16:17]
	s_addc_u32 s37, s37, 0
	s_add_i32 s38, s45, s3
	global_load_lds_dwordx4 v[190:191], off
	s_mov_b32 m0, s38
	s_nop 0
	global_load_lds_dwordx4 v130, s[36:37]
	s_add_i32 m0, s38, 0x2000
	s_nop 0
	global_load_lds_dwordx4 v134, s[36:37]
	v_lshl_add_u64 v[190:191], v[194:195], 0, s[16:17]
	s_mov_b32 m0, s43
	s_nop 0
	global_load_lds_dwordx4 v[190:191], off
	v_lshl_add_u64 v[190:191], v[220:221], 0, s[16:17]
	s_mov_b32 m0, s50
	s_nop 0
	global_load_lds_dwordx4 v[190:191], off
	s_waitcnt vmcnt(8)
	s_waitcnt lgkmcnt(0)
	s_barrier
	s_setprio 1
	s_waitcnt lgkmcnt(0)
	v_mfma_f32_16x16x32_bf16 v[60:63], v[150:153], v[182:185], v[60:63]
	v_mfma_f32_16x16x32_bf16 v[56:59], v[158:161], v[182:185], v[56:59]
	v_mfma_f32_16x16x32_bf16 v[52:55], v[150:153], v[196:199], v[52:55]
	v_mfma_f32_16x16x32_bf16 v[48:51], v[158:161], v[196:199], v[48:51]
	v_mfma_f32_16x16x32_bf16 v[36:39], v[150:153], v[204:207], v[36:39]
	v_mfma_f32_16x16x32_bf16 v[32:35], v[158:161], v[204:207], v[32:35]
	v_mfma_f32_16x16x32_bf16 v[20:23], v[150:153], v[212:215], v[20:23]
	v_mfma_f32_16x16x32_bf16 v[16:19], v[158:161], v[212:215], v[16:19]
	v_mfma_f32_16x16x32_bf16 v[60:63], v[154:157], v[186:189], v[60:63]
	v_mfma_f32_16x16x32_bf16 v[56:59], v[162:165], v[186:189], v[56:59]
	v_mfma_f32_16x16x32_bf16 v[52:55], v[154:157], v[200:203], v[52:55]
	v_mfma_f32_16x16x32_bf16 v[48:51], v[162:165], v[200:203], v[48:51]
	v_mfma_f32_16x16x32_bf16 v[36:39], v[154:157], v[208:211], v[36:39]
	v_mfma_f32_16x16x32_bf16 v[32:35], v[162:165], v[208:211], v[32:35]
	v_mfma_f32_16x16x32_bf16 v[20:23], v[154:157], v[216:219], v[20:23]
	v_mfma_f32_16x16x32_bf16 v[16:19], v[162:165], v[216:219], v[16:19]
	s_setprio 0
	s_setprio 1
	v_mfma_f32_16x16x32_bf16 v[44:47], v[166:169], v[182:185], v[44:47]
	v_mfma_f32_16x16x32_bf16 v[40:43], v[174:177], v[182:185], v[40:43]
	v_mfma_f32_16x16x32_bf16 v[28:31], v[166:169], v[196:199], v[28:31]
	v_mfma_f32_16x16x32_bf16 v[24:27], v[174:177], v[196:199], v[24:27]
	v_mfma_f32_16x16x32_bf16 v[12:15], v[166:169], v[204:207], v[12:15]
	v_mfma_f32_16x16x32_bf16 v[8:11], v[174:177], v[204:207], v[8:11]
	v_mfma_f32_16x16x32_bf16 v[4:7], v[166:169], v[212:215], v[4:7]
	v_mfma_f32_16x16x32_bf16 v[0:3], v[174:177], v[212:215], v[0:3]
	v_mfma_f32_16x16x32_bf16 v[44:47], v[170:173], v[186:189], v[44:47]
	v_mfma_f32_16x16x32_bf16 v[40:43], v[178:181], v[186:189], v[40:43]
	v_mfma_f32_16x16x32_bf16 v[28:31], v[170:173], v[200:203], v[28:31]
	v_mfma_f32_16x16x32_bf16 v[24:27], v[178:181], v[200:203], v[24:27]
	v_mfma_f32_16x16x32_bf16 v[12:15], v[170:173], v[208:211], v[12:15]
	v_mfma_f32_16x16x32_bf16 v[8:11], v[178:181], v[208:211], v[8:11]
	v_mfma_f32_16x16x32_bf16 v[4:7], v[170:173], v[216:219], v[4:7]
	v_mfma_f32_16x16x32_bf16 v[0:3], v[178:181], v[216:219], v[0:3]
	s_setprio 0
	s_barrier
	s_add_i32 s64, s64, 2
	s_add_u32 s34, s34, 0x100
	s_addc_u32 s35, s35, 0
	s_add_u32 s62, s62, 0x100
	s_addc_u32 s63, s63, 0
	s_cmp_gt_u32 s64, 13
	s_cbranch_scc0 .LBB0_186
	s_and_b64 vcc, exec, s[18:19]
	s_cbranch_vccz .LBB0_189
	s_barrier

; #define PG8_STAGE(bufoff, gbase, voff) do { _Pragma("unroll") for (int _i = 0; _i < 2; ++_i) \
;         __builtin_amdgcn_global_load_lds((const unsigned*)((const char*)(gbase) + (voff)[_i]), (PG8_LAS unsigned*)(lds + (bufoff) + ldsw + _i * 8192), 16, 0, 0); } while (0)
; #define PG8_WAIT_V(n) asm volatile("s_waitcnt vmcnt(" #n ")" ::: "memory")
; #define PG8_BAR __builtin_amdgcn_s_barrier()
; template <class Epi, class Sched, bool ALIGN_EPI = false, bool SP2 = false>
; __device__ __forceinline__ void gemm_phase(PG8_LAS unsigned char* lds, const Gemm g, const Sched& S, const Epi& E) {
;     ...
;         PG8_STAGE(PG8_SB(0, 0), cB, voffB); PG8_STAGE(PG8_SB(0, 1), cB + hstepB, voffB); PG8_STAGE(PG8_SA(0, 0), cA, voffA); PG8_STAGE(PG8_SA(0, 1), cA + hstepA, voffA);
;         if (wr == 1) PG8_BAR;
;         PG8_WAIT_V(2); PG8_BAR;
;         PG8_STAGE(PG8_SB(1, 0), cB + kstep, voffB); PG8_STAGE(PG8_SA(1, 0), cA + kstep, voffA); PG8_STAGE(PG8_SB(1, 1), cB + hstepB + kstep, voffB);
;         PG8_WAIT_V(6); PG8_BAR;
.LBB0_200:
	s_lshl_b32 s43, s16, 6
	s_lshl_b32 s19, s16, 13
	s_mov_b64 s[16:17], 0x80
	s_and_b32 s1, s1, 3
	s_add_i32 m0, s31, 0x18000
	v_lshl_add_u64 v[6:7], v[6:7], 0, s[16:17]
	s_lshl_b32 s22, s1, 12
	s_waitcnt vmcnt(2)
	s_barrier
	global_load_lds_dwordx4 v[6:7], off
	v_lshl_add_u64 v[4:5], v[4:5], 0, s[16:17]
	s_add_i32 m0, s31, 0x1a000
	s_add_i32 s50, s31, 0x8000
	s_add_i32 s51, s31, 0xa000
	global_load_lds_dwordx4 v[4:5], off
	v_lshl_add_u64 v[0:1], v[0:1], 0, s[16:17]
	s_mov_b32 m0, s50
	s_add_u32 s20, s36, 0x40080
	global_load_lds_dwordx4 v[0:1], off
	v_lshl_add_u64 v[0:1], v[2:3], 0, s[16:17]
	s_mov_b32 m0, s51
	s_addc_u32 s21, s37, 0
	global_load_lds_dwordx4 v[0:1], off
	s_add_i32 m0, s31, 0x1c000
	s_nop 0
	global_load_lds_dwordx4 v128, s[20:21]
	v_lshl_add_u64 v[0:1], s[20:21], 0, v[130:131]
	s_add_i32 m0, s31, 0x1e000
	v_bfe_u32 v141, v8, 4, 2
	global_load_lds_dwordx4 v[0:1], off
	v_and_b32_e32 v140, 15, v8
	v_lshlrev_b32_e32 v0, 4, v141
	v_lshlrev_b32_e32 v1, 2, v8
	v_lshl_or_b32 v0, v140, 6, v0
	v_and_b32_e32 v1, 32, v1
	v_bitop3_b32 v2, v0, s19, v1 bitop3:0xde
	v_bitop3_b32 v142, v0, s22, v1 bitop3:0xde
	v_lshlrev_b32_e32 v0, 14, v9
	v_and_b32_e32 v0, 0xffff8000, v0
	v_lshl_add_u32 v0, v10, 11, v0
	v_and_b32_e32 v1, 1, v9
	v_lshl_or_b32 v0, v1, 6, v0
	v_lshl_add_u32 v132, v11, 1, v0
	v_lshlrev_b32_e32 v0, 14, v12
	v_and_b32_e32 v0, 0xffff8000, v0
	s_waitcnt vmcnt(6)
	s_cmpk_lt_u32 s18, 0x100
	v_lshl_add_u32 v0, v13, 11, v0
	v_and_b32_e32 v1, 1, v12
	s_cselect_b64 s[18:19], -1, 0
	v_lshl_or_b32 v0, v1, 6, v0
	s_add_i32 s57, 0, 0x10000
	s_add_i32 s58, 0, 0x14000
	s_sext_i32_i8 s59, s0
	s_lshl_b32 s52, s1, 4
	s_ashr_i32 s53, s88, 31
	s_mov_b32 s56, s88
	v_mov_b32_e32 v133, v129
	v_lshl_add_u32 v134, v14, 1, v0
	v_mov_b32_e32 v135, v129
	v_mov_b64_e32 v[136:137], 0x200
	v_mov_b64_e32 v[138:139], 0x1ff
	v_add_u32_e32 v143, s57, v142
	v_add_u32_e32 v144, s58, v142
	v_add_u32_e32 v145, 0, v2
	s_mov_b64 s[20:21], 0xb0000
	s_barrier
	s_branch .LBB0_203

; #define PG8_STAGE(bufoff, gbase, voff) do { _Pragma("unroll") for (int _i = 0; _i < 2; ++_i) \
;         __builtin_amdgcn_global_load_lds((const unsigned*)((const char*)(gbase) + (voff)[_i]), (PG8_LAS unsigned*)(lds + (bufoff) + ldsw + _i * 8192), 16, 0, 0); } while (0)
; #define PG8_LDA(dst, b, h) do { _Pragma("unroll") for (int m = 0; m < 4; ++m) _Pragma("unroll") for (int k = 0; k < 2; ++k) dst[m][k] = *(const PG8_LAS bf16x8*)(lds + PG8_SA(b, h) + aoff + m * 2048 + k * 1024); } while (0)
; #define PG8_LDB(dst, b, h) do { _Pragma("unroll") for (int n = 0; n < 2; ++n) _Pragma("unroll") for (int k = 0; k < 2; ++k) dst[n][k] = *(const PG8_LAS bf16x8*)(lds + PG8_SB(b, h) + boff + n * 2048 + k * 1024); } while (0)
; #define PG8_MMA(ai, bj, At, Bt) do { __builtin_amdgcn_s_setprio(1); _Pragma("unroll") for (int m = 0; m < 4; ++m) _Pragma("unroll") for (int n = 0; n < 2; ++n) _Pragma("unroll") for (int k = 0; k < 2; ++k) \
;         acc[ai][bj][m][n] = __builtin_amdgcn_mfma_f32_16x16x32_bf16(Bt[n][k], At[m][k], acc[ai][bj][m][n], 0, 0, 0); __builtin_amdgcn_s_setprio(0); } while (0)
; #define PG8_WAIT_V(n) asm volatile("s_waitcnt vmcnt(" #n ")" ::: "memory")
; #define PG8_WAIT_L(n) asm volatile("s_waitcnt lgkmcnt(" #n ")" ::: "memory")
; #define PG8_BAR __builtin_amdgcn_s_barrier()
; #define PG8_SCHED __builtin_amdgcn_sched_barrier(0)
; template <class Epi, class Sched, bool ALIGN_EPI = false, bool SP2 = false>
; __device__ __forceinline__ void gemm_phase(PG8_LAS unsigned char* lds, const Gemm g, const Sched& S, const Epi& E) {
;     ...
;             PG8_LDB(B0, 0, 0); PG8_LDB(B1, 0, 1); PG8_SCHED; PG8_LDA(At, 0, 0); PG8_STAGE(PG8_SA(1, 1), a1 + hstepA, voffA);
;             PG8_WAIT_V(8); PG8_WAIT_L(0); PG8_BAR; PG8_MMA(0, 0, At, B0); PG8_MMA(0, 1, At, B1); PG8_BAR; PG8_SCHED;
;             PG8_LDA(At, 0, 1); PG8_STAGE(PG8_SB(0, 0), b2, voffB); PG8_STAGE(PG8_SB(0, 1), b2 + hstepB, voffB); PG8_STAGE(PG8_SA(0, 0), a2, voffA);
;             PG8_WAIT_V(8); PG8_WAIT_L(0); PG8_BAR; PG8_MMA(1, 0, At, B0); PG8_MMA(1, 1, At, B1); PG8_BAR; PG8_SCHED;
.LBB0_210:
	ds_read_b128 v[146:149], v143
	ds_read_b128 v[150:153], v143 offset:1024
	ds_read_b128 v[154:157], v143 offset:2048
	ds_read_b128 v[158:161], v143 offset:3072
	ds_read_b128 v[162:165], v144
	ds_read_b128 v[166:169], v144 offset:1024
	ds_read_b128 v[170:173], v144 offset:2048
	ds_read_b128 v[174:177], v144 offset:3072
	s_add_u32 s36, s34, 0xfffc0080
	s_addc_u32 s37, s35, -1
	s_cmp_eq_u32 s64, 12
	s_cselect_b32 s39, s25, s37
	s_cselect_b32 s38, s60, s36
	s_cselect_b32 s37, s23, s63
	s_cselect_b32 s36, s61, s62
	s_add_i32 m0, s31, 0xc000
	ds_read_b128 v[178:181], v145
	ds_read_b128 v[182:185], v145 offset:1024
	ds_read_b128 v[186:189], v145 offset:2048
	ds_read_b128 v[196:199], v145 offset:3072
	ds_read_b128 v[200:203], v145 offset:4096
	ds_read_b128 v[204:207], v145 offset:5120
	ds_read_b128 v[208:211], v145 offset:6144
	ds_read_b128 v[212:215], v145 offset:7168
	global_load_lds_dwordx4 v132, s[34:35]
	s_add_i32 m0, s31, 0xe000
	s_nop 0
	global_load_lds_dwordx4 v134, s[34:35]
	s_waitcnt vmcnt(8)
	s_waitcnt lgkmcnt(0)
	s_barrier
	s_setprio 1
	s_waitcnt lgkmcnt(0)
	v_mfma_f32_16x16x32_bf16 v[124:127], v[146:149], v[178:181], v[124:127]
	v_mfma_f32_16x16x32_bf16 v[120:123], v[154:157], v[178:181], v[120:123]
	v_mfma_f32_16x16x32_bf16 v[108:111], v[146:149], v[186:189], v[108:111]
	v_mfma_f32_16x16x32_bf16 v[104:107], v[154:157], v[186:189], v[104:107]
	v_mfma_f32_16x16x32_bf16 v[92:95], v[146:149], v[200:203], v[92:95]
	v_mfma_f32_16x16x32_bf16 v[88:91], v[154:157], v[200:203], v[88:91]
	v_mfma_f32_16x16x32_bf16 v[76:79], v[146:149], v[208:211], v[76:79]
	v_mfma_f32_16x16x32_bf16 v[72:75], v[154:157], v[208:211], v[72:75]
	v_mfma_f32_16x16x32_bf16 v[124:127], v[150:153], v[182:185], v[124:127]
	v_mfma_f32_16x16x32_bf16 v[120:123], v[158:161], v[182:185], v[120:123]
	v_mfma_f32_16x16x32_bf16 v[108:111], v[150:153], v[196:199], v[108:111]
	v_mfma_f32_16x16x32_bf16 v[104:107], v[158:161], v[196:199], v[104:107]
	v_mfma_f32_16x16x32_bf16 v[92:95], v[150:153], v[204:207], v[92:95]
	v_mfma_f32_16x16x32_bf16 v[88:91], v[158:161], v[204:207], v[88:91]
	v_mfma_f32_16x16x32_bf16 v[76:79], v[150:153], v[212:215], v[76:79]
	v_mfma_f32_16x16x32_bf16 v[72:75], v[158:161], v[212:215], v[72:75]
	s_setprio 0
	s_setprio 1
	v_mfma_f32_16x16x32_bf16 v[116:119], v[162:165], v[178:181], v[116:119]
	v_mfma_f32_16x16x32_bf16 v[112:115], v[170:173], v[178:181], v[112:115]
	v_mfma_f32_16x16x32_bf16 v[100:103], v[162:165], v[186:189], v[100:103]
	v_mfma_f32_16x16x32_bf16 v[96:99], v[170:173], v[186:189], v[96:99]
	v_mfma_f32_16x16x32_bf16 v[84:87], v[162:165], v[200:203], v[84:87]
	v_mfma_f32_16x16x32_bf16 v[80:83], v[170:173], v[200:203], v[80:83]
	v_mfma_f32_16x16x32_bf16 v[68:71], v[162:165], v[208:211], v[68:71]
	v_mfma_f32_16x16x32_bf16 v[64:67], v[170:173], v[208:211], v[64:67]
	v_mfma_f32_16x16x32_bf16 v[116:119], v[166:169], v[182:185], v[116:119]
	v_mfma_f32_16x16x32_bf16 v[112:115], v[174:177], v[182:185], v[112:115]
	v_mfma_f32_16x16x32_bf16 v[100:103], v[166:169], v[196:199], v[100:103]
	v_mfma_f32_16x16x32_bf16 v[96:99], v[174:177], v[196:199], v[96:99]
	v_mfma_f32_16x16x32_bf16 v[84:87], v[166:169], v[204:207], v[84:87]
	v_mfma_f32_16x16x32_bf16 v[80:83], v[174:177], v[204:207], v[80:83]
	v_mfma_f32_16x16x32_bf16 v[68:71], v[166:169], v[212:215], v[68:71]
	v_mfma_f32_16x16x32_bf16 v[64:67], v[174:177], v[212:215], v[64:67]
	s_setprio 0
	s_barrier
	s_add_i32 s44, s57, s9
	v_lshl_add_u64 v[190:191], s[36:37], 0, v[128:129]
	s_mov_b32 m0, s44
	ds_read_b128 v[178:181], v145 offset:16384
	ds_read_b128 v[182:185], v145 offset:17408
	ds_read_b128 v[186:189], v145 offset:18432
	ds_read_b128 v[196:199], v145 offset:19456
	ds_read_b128 v[200:203], v145 offset:20480
	ds_read_b128 v[204:207], v145 offset:21504
	ds_read_b128 v[208:211], v145 offset:22528
	ds_read_b128 v[212:215], v145 offset:23552
	global_load_lds_dwordx4 v[190:191], off
	s_add_i32 m0, s44, 0x2000
	s_add_u32 s44, s36, 0x40000
	v_lshl_add_u64 v[192:193], s[36:37], 0, v[130:131]
	s_addc_u32 s45, s37, 0
	s_add_i32 s48, s58, s9
	global_load_lds_dwordx4 v[192:193], off
	s_mov_b32 m0, s48
	v_lshl_add_u64 v[216:217], s[38:39], 0, v[130:131]
	global_load_lds_dwordx4 v128, s[44:45]
	s_add_i32 m0, s48, 0x2000
	s_nop 0
	global_load_lds_dwordx4 v130, s[44:45]
	v_lshl_add_u64 v[194:195], s[38:39], 0, v[128:129]
	s_mov_b32 m0, s31
	s_nop 0
	global_load_lds_dwordx4 v[194:195], off
	s_mov_b32 m0, s33
	s_nop 0
	global_load_lds_dwordx4 v[216:217], off
	s_waitcnt vmcnt(8)
	s_waitcnt lgkmcnt(0)
	s_barrier
; #define PG8_STAGE(bufoff, gbase, voff) do { _Pragma("unroll") for (int _i = 0; _i < 2; ++_i) \
;         __builtin_amdgcn_global_load_lds((const unsigned*)((const char*)(gbase) + (voff)[_i]), (PG8_LAS unsigned*)(lds + (bufoff) + ldsw + _i * 8192), 16, 0, 0); } while (0)
; #define PG8_LDA(dst, b, h) do { _Pragma("unroll") for (int m = 0; m < 4; ++m) _Pragma("unroll") for (int k = 0; k < 2; ++k) dst[m][k] = *(const PG8_LAS bf16x8*)(lds + PG8_SA(b, h) + aoff + m * 2048 + k * 1024); } while (0)
; #define PG8_LDB(dst, b, h) do { _Pragma("unroll") for (int n = 0; n < 2; ++n) _Pragma("unroll") for (int k = 0; k < 2; ++k) dst[n][k] = *(const PG8_LAS bf16x8*)(lds + PG8_SB(b, h) + boff + n * 2048 + k * 1024); } while (0)
; #define PG8_MMA(ai, bj, At, Bt) do { __builtin_amdgcn_s_setprio(1); _Pragma("unroll") for (int m = 0; m < 4; ++m) _Pragma("unroll") for (int n = 0; n < 2; ++n) _Pragma("unroll") for (int k = 0; k < 2; ++k) \
;         acc[ai][bj][m][n] = __builtin_amdgcn_mfma_f32_16x16x32_bf16(Bt[n][k], At[m][k], acc[ai][bj][m][n], 0, 0, 0); __builtin_amdgcn_s_setprio(0); } while (0)
; #define PG8_WAIT_V(n) asm volatile("s_waitcnt vmcnt(" #n ")" ::: "memory")
; #define PG8_WAIT_L(n) asm volatile("s_waitcnt lgkmcnt(" #n ")" ::: "memory")
; #define PG8_BAR __builtin_amdgcn_s_barrier()
; #define PG8_SCHED __builtin_amdgcn_sched_barrier(0)
; template <class Epi, class Sched, bool ALIGN_EPI = false, bool SP2 = false>
; __device__ __forceinline__ void gemm_phase(PG8_LAS unsigned char* lds, const Gemm g, const Sched& S, const Epi& E) {
;     ...
;             PG8_WAIT_V(8); PG8_WAIT_L(0); PG8_BAR; PG8_MMA(1, 0, At, B0); PG8_MMA(1, 1, At, B1); PG8_BAR; PG8_SCHED;
;             PG8_LDB(B0, 1, 0); PG8_LDB(B1, 1, 1); PG8_SCHED; PG8_LDA(At, 1, 0); PG8_STAGE(PG8_SA(0, 1), a2 + hstepA, voffA);
;             PG8_WAIT_V(8); PG8_WAIT_L(0); PG8_BAR; PG8_MMA(0, 0, At, B0); PG8_MMA(0, 1, At, B1); PG8_BAR; PG8_SCHED;
;             PG8_LDA(At, 1, 1); PG8_STAGE(PG8_SB(1, 0), b3, voffB); PG8_STAGE(PG8_SB(1, 1), b3 + hstepB, voffB); PG8_STAGE(PG8_SA(1, 0), a3, voffA);
	s_setprio 1
	s_waitcnt lgkmcnt(0)
	v_mfma_f32_16x16x32_bf16 v[60:63], v[146:149], v[178:181], v[60:63]
	v_mfma_f32_16x16x32_bf16 v[56:59], v[154:157], v[178:181], v[56:59]
	v_mfma_f32_16x16x32_bf16 v[44:47], v[146:149], v[186:189], v[44:47]
	v_mfma_f32_16x16x32_bf16 v[40:43], v[154:157], v[186:189], v[40:43]
	v_mfma_f32_16x16x32_bf16 v[28:31], v[146:149], v[200:203], v[28:31]
	v_mfma_f32_16x16x32_bf16 v[24:27], v[154:157], v[200:203], v[24:27]
	v_mfma_f32_16x16x32_bf16 v[12:15], v[146:149], v[208:211], v[12:15]
	v_mfma_f32_16x16x32_bf16 v[8:11], v[154:157], v[208:211], v[8:11]
	v_mfma_f32_16x16x32_bf16 v[60:63], v[150:153], v[182:185], v[60:63]
	v_mfma_f32_16x16x32_bf16 v[56:59], v[158:161], v[182:185], v[56:59]
	v_mfma_f32_16x16x32_bf16 v[44:47], v[150:153], v[196:199], v[44:47]
	v_mfma_f32_16x16x32_bf16 v[40:43], v[158:161], v[196:199], v[40:43]
	v_mfma_f32_16x16x32_bf16 v[28:31], v[150:153], v[204:207], v[28:31]
	v_mfma_f32_16x16x32_bf16 v[24:27], v[158:161], v[204:207], v[24:27]
	v_mfma_f32_16x16x32_bf16 v[12:15], v[150:153], v[212:215], v[12:15]
	v_mfma_f32_16x16x32_bf16 v[8:11], v[158:161], v[212:215], v[8:11]
	s_setprio 0
	s_setprio 1
	v_mfma_f32_16x16x32_bf16 v[52:55], v[162:165], v[178:181], v[52:55]
	v_mfma_f32_16x16x32_bf16 v[48:51], v[170:173], v[178:181], v[48:51]
	v_mfma_f32_16x16x32_bf16 v[36:39], v[162:165], v[186:189], v[36:39]
	v_mfma_f32_16x16x32_bf16 v[32:35], v[170:173], v[186:189], v[32:35]
	v_mfma_f32_16x16x32_bf16 v[20:23], v[162:165], v[200:203], v[20:23]
	v_mfma_f32_16x16x32_bf16 v[16:19], v[170:173], v[200:203], v[16:19]
	v_mfma_f32_16x16x32_bf16 v[4:7], v[162:165], v[208:211], v[4:7]
	v_mfma_f32_16x16x32_bf16 v[0:3], v[170:173], v[208:211], v[0:3]
	v_mfma_f32_16x16x32_bf16 v[52:55], v[166:169], v[182:185], v[52:55]
	v_mfma_f32_16x16x32_bf16 v[48:51], v[174:177], v[182:185], v[48:51]
	v_mfma_f32_16x16x32_bf16 v[36:39], v[166:169], v[196:199], v[36:39]
	v_mfma_f32_16x16x32_bf16 v[32:35], v[174:177], v[196:199], v[32:35]
	v_mfma_f32_16x16x32_bf16 v[20:23], v[166:169], v[204:207], v[20:23]
	v_mfma_f32_16x16x32_bf16 v[16:19], v[174:177], v[204:207], v[16:19]
	v_mfma_f32_16x16x32_bf16 v[4:7], v[166:169], v[212:215], v[4:7]
	v_mfma_f32_16x16x32_bf16 v[0:3], v[174:177], v[212:215], v[0:3]
	s_setprio 0
	s_barrier
	s_add_i32 s44, 0, 0x18000
	s_add_i32 s45, 0, 0x1c000
	v_add_u32_e32 v158, s44, v142
	v_add_u32_e32 v174, s45, v142
	ds_read_b128 v[146:149], v158
	ds_read_b128 v[150:153], v158 offset:1024
	ds_read_b128 v[154:157], v158 offset:2048
	ds_read_b128 v[158:161], v158 offset:3072
	ds_read_b128 v[162:165], v174
	ds_read_b128 v[166:169], v174 offset:1024
	ds_read_b128 v[170:173], v174 offset:2048
	ds_read_b128 v[174:177], v174 offset:3072
	s_add_u32 s38, s38, 0x40000
	s_addc_u32 s39, s39, 0
	s_mov_b32 m0, s40
	ds_read_b128 v[178:181], v145 offset:32768
	ds_read_b128 v[182:185], v145 offset:33792
	ds_read_b128 v[186:189], v145 offset:34816
	ds_read_b128 v[196:199], v145 offset:35840
	ds_read_b128 v[200:203], v145 offset:36864
	ds_read_b128 v[204:207], v145 offset:37888
	ds_read_b128 v[208:211], v145 offset:38912
	ds_read_b128 v[212:215], v145 offset:39936
	global_load_lds_dwordx4 v128, s[38:39]
	s_mov_b32 m0, s41
	s_nop 0
	global_load_lds_dwordx4 v130, s[38:39]
	s_waitcnt vmcnt(8)
	s_waitcnt lgkmcnt(0)
	s_barrier
	s_setprio 1
	s_waitcnt lgkmcnt(0)
	v_mfma_f32_16x16x32_bf16 v[124:127], v[146:149], v[178:181], v[124:127]
	v_mfma_f32_16x16x32_bf16 v[120:123], v[154:157], v[178:181], v[120:123]
	v_mfma_f32_16x16x32_bf16 v[108:111], v[146:149], v[186:189], v[108:111]
	v_mfma_f32_16x16x32_bf16 v[104:107], v[154:157], v[186:189], v[104:107]
	v_mfma_f32_16x16x32_bf16 v[92:95], v[146:149], v[200:203], v[92:95]
	v_mfma_f32_16x16x32_bf16 v[88:91], v[154:157], v[200:203], v[88:91]
	v_mfma_f32_16x16x32_bf16 v[76:79], v[146:149], v[208:211], v[76:79]
	v_mfma_f32_16x16x32_bf16 v[72:75], v[154:157], v[208:211], v[72:75]
	v_mfma_f32_16x16x32_bf16 v[124:127], v[150:153], v[182:185], v[124:127]
	v_mfma_f32_16x16x32_bf16 v[120:123], v[158:161], v[182:185], v[120:123]
	v_mfma_f32_16x16x32_bf16 v[108:111], v[150:153], v[196:199], v[108:111]
	v_mfma_f32_16x16x32_bf16 v[104:107], v[158:161], v[196:199], v[104:107]
	v_mfma_f32_16x16x32_bf16 v[92:95], v[150:153], v[204:207], v[92:95]
	v_mfma_f32_16x16x32_bf16 v[88:91], v[158:161], v[204:207], v[88:91]
	v_mfma_f32_16x16x32_bf16 v[76:79], v[150:153], v[212:215], v[76:79]
	v_mfma_f32_16x16x32_bf16 v[72:75], v[158:161], v[212:215], v[72:75]
	s_setprio 0
	s_setprio 1
	v_mfma_f32_16x16x32_bf16 v[116:119], v[162:165], v[178:181], v[116:119]
	v_mfma_f32_16x16x32_bf16 v[112:115], v[170:173], v[178:181], v[112:115]
	v_mfma_f32_16x16x32_bf16 v[100:103], v[162:165], v[186:189], v[100:103]
	v_mfma_f32_16x16x32_bf16 v[96:99], v[170:173], v[186:189], v[96:99]
	v_mfma_f32_16x16x32_bf16 v[84:87], v[162:165], v[200:203], v[84:87]
	v_mfma_f32_16x16x32_bf16 v[80:83], v[170:173], v[200:203], v[80:83]
	v_mfma_f32_16x16x32_bf16 v[68:71], v[162:165], v[208:211], v[68:71]
	v_mfma_f32_16x16x32_bf16 v[64:67], v[170:173], v[208:211], v[64:67]
	v_mfma_f32_16x16x32_bf16 v[116:119], v[166:169], v[182:185], v[116:119]
	v_mfma_f32_16x16x32_bf16 v[112:115], v[174:177], v[182:185], v[112:115]
	v_mfma_f32_16x16x32_bf16 v[100:103], v[166:169], v[196:199], v[100:103]
	v_mfma_f32_16x16x32_bf16 v[96:99], v[174:177], v[196:199], v[96:99]
	v_mfma_f32_16x16x32_bf16 v[84:87], v[166:169], v[204:207], v[84:87]
	v_mfma_f32_16x16x32_bf16 v[80:83], v[174:177], v[204:207], v[80:83]
	v_mfma_f32_16x16x32_bf16 v[68:71], v[166:169], v[212:215], v[68:71]
	v_mfma_f32_16x16x32_bf16 v[64:67], v[174:177], v[212:215], v[64:67]
	s_setprio 0
	s_barrier
; #define PG8_STAGE(bufoff, gbase, voff) do { _Pragma("unroll") for (int _i = 0; _i < 2; ++_i) \
;         __builtin_amdgcn_global_load_lds((const unsigned*)((const char*)(gbase) + (voff)[_i]), (PG8_LAS unsigned*)(lds + (bufoff) + ldsw + _i * 8192), 16, 0, 0); } while (0)
; #define PG8_LDA(dst, b, h) do { _Pragma("unroll") for (int m = 0; m < 4; ++m) _Pragma("unroll") for (int k = 0; k < 2; ++k) dst[m][k] = *(const PG8_LAS bf16x8*)(lds + PG8_SA(b, h) + aoff + m * 2048 + k * 1024); } while (0)
; #define PG8_MMA(ai, bj, At, Bt) do { __builtin_amdgcn_s_setprio(1); _Pragma("unroll") for (int m = 0; m < 4; ++m) _Pragma("unroll") for (int n = 0; n < 2; ++n) _Pragma("unroll") for (int k = 0; k < 2; ++k) \
;         acc[ai][bj][m][n] = __builtin_amdgcn_mfma_f32_16x16x32_bf16(Bt[n][k], At[m][k], acc[ai][bj][m][n], 0, 0, 0); __builtin_amdgcn_s_setprio(0); } while (0)
; #define PG8_WAIT_V(n) asm volatile("s_waitcnt vmcnt(" #n ")" ::: "memory")
; #define PG8_WAIT_L(n) asm volatile("s_waitcnt lgkmcnt(" #n ")" ::: "memory")
; #define PG8_BAR __builtin_amdgcn_s_barrier()
; #define PG8_SCHED __builtin_amdgcn_sched_barrier(0)
; template <class Epi, class Sched, bool ALIGN_EPI = false, bool SP2 = false>
; __device__ __forceinline__ void gemm_phase(PG8_LAS unsigned char* lds, const Gemm g, const Sched& S, const Epi& E) {
;     ...
;             PG8_WAIT_V(8); PG8_WAIT_L(0); PG8_BAR; PG8_MMA(0, 0, At, B0); PG8_MMA(0, 1, At, B1); PG8_BAR; PG8_SCHED;
;             PG8_LDA(At, 1, 1); PG8_STAGE(PG8_SB(1, 0), b3, voffB); PG8_STAGE(PG8_SB(1, 1), b3 + hstepB, voffB); PG8_STAGE(PG8_SA(1, 0), a3, voffA);
;             PG8_WAIT_V(8); PG8_WAIT_L(0); PG8_BAR; PG8_MMA(1, 0, At, B0); PG8_MMA(1, 1, At, B1); PG8_BAR; PG8_SCHED;
	s_add_i32 s38, s44, s9
	v_lshl_add_u64 v[190:191], v[190:191], 0, s[16:17]
	s_mov_b32 m0, s38
	ds_read_b128 v[178:181], v145 offset:49152
	ds_read_b128 v[182:185], v145 offset:50176
	ds_read_b128 v[186:189], v145 offset:51200
	ds_read_b128 v[196:199], v145 offset:52224
	ds_read_b128 v[200:203], v145 offset:53248
	ds_read_b128 v[204:207], v145 offset:54272
	ds_read_b128 v[208:211], v145 offset:55296
	ds_read_b128 v[212:215], v145 offset:56320
	global_load_lds_dwordx4 v[190:191], off
	s_add_i32 m0, s38, 0x2000
	s_add_u32 s36, s36, 0x40080
	v_lshl_add_u64 v[190:191], v[192:193], 0, s[16:17]
	s_addc_u32 s37, s37, 0
	s_add_i32 s38, s45, s9
	global_load_lds_dwordx4 v[190:191], off
	s_mov_b32 m0, s38
	s_nop 0
	global_load_lds_dwordx4 v128, s[36:37]
	s_add_i32 m0, s38, 0x2000
	s_nop 0
	global_load_lds_dwordx4 v130, s[36:37]
	v_lshl_add_u64 v[190:191], v[194:195], 0, s[16:17]
	s_mov_b32 m0, s50
	s_nop 0
	global_load_lds_dwordx4 v[190:191], off
	v_lshl_add_u64 v[190:191], v[216:217], 0, s[16:17]
	s_mov_b32 m0, s51
	s_nop 0
	global_load_lds_dwordx4 v[190:191], off
	s_waitcnt vmcnt(8)
	s_waitcnt lgkmcnt(0)
	s_barrier
	s_setprio 1
	s_waitcnt lgkmcnt(0)
	v_mfma_f32_16x16x32_bf16 v[60:63], v[146:149], v[178:181], v[60:63]
	v_mfma_f32_16x16x32_bf16 v[56:59], v[154:157], v[178:181], v[56:59]
	v_mfma_f32_16x16x32_bf16 v[44:47], v[146:149], v[186:189], v[44:47]
	v_mfma_f32_16x16x32_bf16 v[40:43], v[154:157], v[186:189], v[40:43]
	v_mfma_f32_16x16x32_bf16 v[28:31], v[146:149], v[200:203], v[28:31]
	v_mfma_f32_16x16x32_bf16 v[24:27], v[154:157], v[200:203], v[24:27]
	v_mfma_f32_16x16x32_bf16 v[12:15], v[146:149], v[208:211], v[12:15]
	v_mfma_f32_16x16x32_bf16 v[8:11], v[154:157], v[208:211], v[8:11]
	v_mfma_f32_16x16x32_bf16 v[60:63], v[150:153], v[182:185], v[60:63]
	v_mfma_f32_16x16x32_bf16 v[56:59], v[158:161], v[182:185], v[56:59]
	v_mfma_f32_16x16x32_bf16 v[44:47], v[150:153], v[196:199], v[44:47]
	v_mfma_f32_16x16x32_bf16 v[40:43], v[158:161], v[196:199], v[40:43]
	v_mfma_f32_16x16x32_bf16 v[28:31], v[150:153], v[204:207], v[28:31]
	v_mfma_f32_16x16x32_bf16 v[24:27], v[158:161], v[204:207], v[24:27]
	v_mfma_f32_16x16x32_bf16 v[12:15], v[150:153], v[212:215], v[12:15]
	v_mfma_f32_16x16x32_bf16 v[8:11], v[158:161], v[212:215], v[8:11]
	s_setprio 0
	s_setprio 1
	v_mfma_f32_16x16x32_bf16 v[52:55], v[162:165], v[178:181], v[52:55]
	v_mfma_f32_16x16x32_bf16 v[48:51], v[170:173], v[178:181], v[48:51]
	v_mfma_f32_16x16x32_bf16 v[36:39], v[162:165], v[186:189], v[36:39]
	v_mfma_f32_16x16x32_bf16 v[32:35], v[170:173], v[186:189], v[32:35]
	v_mfma_f32_16x16x32_bf16 v[20:23], v[162:165], v[200:203], v[20:23]
	v_mfma_f32_16x16x32_bf16 v[16:19], v[170:173], v[200:203], v[16:19]
	v_mfma_f32_16x16x32_bf16 v[4:7], v[162:165], v[208:211], v[4:7]
	v_mfma_f32_16x16x32_bf16 v[0:3], v[170:173], v[208:211], v[0:3]
	v_mfma_f32_16x16x32_bf16 v[52:55], v[166:169], v[182:185], v[52:55]
	v_mfma_f32_16x16x32_bf16 v[48:51], v[174:177], v[182:185], v[48:51]
	v_mfma_f32_16x16x32_bf16 v[36:39], v[166:169], v[196:199], v[36:39]
	v_mfma_f32_16x16x32_bf16 v[32:35], v[174:177], v[196:199], v[32:35]
	v_mfma_f32_16x16x32_bf16 v[20:23], v[166:169], v[204:207], v[20:23]
	v_mfma_f32_16x16x32_bf16 v[16:19], v[174:177], v[204:207], v[16:19]
	v_mfma_f32_16x16x32_bf16 v[4:7], v[166:169], v[212:215], v[4:7]
	v_mfma_f32_16x16x32_bf16 v[0:3], v[174:177], v[212:215], v[0:3]
	s_setprio 0
	s_barrier
	s_add_i32 s64, s64, 2
	s_add_u32 s34, s34, 0x100
	s_addc_u32 s35, s35, 0
	s_add_u32 s62, s62, 0x100
	s_addc_u32 s63, s63, 0
	s_cmp_gt_u32 s64, 13
	s_cbranch_scc0 .LBB0_210
	s_and_b64 vcc, exec, s[18:19]
	s_cbranch_vccz .LBB0_213
	s_barrier

; #define PG8_STAGE(bufoff, gbase, voff) do { _Pragma("unroll") for (int _i = 0; _i < 2; ++_i) \
;         __builtin_amdgcn_global_load_lds((const unsigned*)((const char*)(gbase) + (voff)[_i]), (PG8_LAS unsigned*)(lds + (bufoff) + ldsw + _i * 8192), 16, 0, 0); } while (0)
; #define PG8_WAIT_V(n) asm volatile("s_waitcnt vmcnt(" #n ")" ::: "memory")
; #define PG8_BAR __builtin_amdgcn_s_barrier()
; template <class Epi, class Sched, bool ALIGN_EPI = false, bool SP2 = false>
; __device__ __forceinline__ void gemm_phase(PG8_LAS unsigned char* lds, const Gemm g, const Sched& S, const Epi& E) {
;     ...
;         PG8_STAGE(PG8_SB(0, 0), cB, voffB); PG8_STAGE(PG8_SB(0, 1), cB + hstepB, voffB); PG8_STAGE(PG8_SA(0, 0), cA, voffA); PG8_STAGE(PG8_SA(0, 1), cA + hstepA, voffA);
;         if (wr == 1) PG8_BAR;
;         PG8_WAIT_V(2); PG8_BAR;
;         PG8_STAGE(PG8_SB(1, 0), cB + kstep, voffB); PG8_STAGE(PG8_SA(1, 0), cA + kstep, voffA); PG8_STAGE(PG8_SB(1, 1), cB + hstepB + kstep, voffB);
;         PG8_WAIT_V(6); PG8_BAR;
.LBB0_225:
	s_add_u32 s14, s82, 0x7800000
	s_addc_u32 s15, s83, 0
	s_lshl_b32 s33, s16, 6
	s_lshl_b32 s19, s16, 13
	s_lshl_b32 s16, s17, 5
	s_and_b32 s42, s16, 0x60
	s_mov_b64 s[16:17], 0x80
	s_add_i32 m0, s9, 0x18000
	v_lshl_add_u64 v[6:7], v[6:7], 0, s[16:17]
	s_lshl_b32 s22, s42, 7
	s_waitcnt vmcnt(2)
	s_barrier
	global_load_lds_dwordx4 v[6:7], off
	v_lshl_add_u64 v[4:5], v[4:5], 0, s[16:17]
	s_add_i32 m0, s9, 0x1a000
	s_add_i32 s43, s9, 0x8000
	s_add_i32 s56, s9, 0xa000
	global_load_lds_dwordx4 v[4:5], off
	v_lshl_add_u64 v[2:3], v[2:3], 0, s[16:17]
	s_mov_b32 m0, s43
	s_add_u32 s20, s40, 0x10080
	global_load_lds_dwordx4 v[2:3], off
	v_lshl_add_u64 v[0:1], v[0:1], 0, s[16:17]
	s_mov_b32 m0, s56
	s_addc_u32 s21, s41, 0
	global_load_lds_dwordx4 v[0:1], off
	s_add_i32 m0, s9, 0x1c000
	s_nop 0
	global_load_lds_dwordx4 v130, s[20:21]
	v_lshl_add_u64 v[0:1], s[20:21], 0, v[134:135]
	s_add_i32 m0, s9, 0x1e000
	v_bfe_u32 v141, v8, 4, 2
	global_load_lds_dwordx4 v[0:1], off
	v_and_b32_e32 v140, 15, v8
	v_lshlrev_b32_e32 v0, 4, v141
	v_lshlrev_b32_e32 v1, 2, v8
	v_lshl_or_b32 v0, v140, 6, v0
	v_and_b32_e32 v1, 32, v1
	s_cmpk_lt_u32 s18, 0x100
	v_bitop3_b32 v2, v0, s19, v1 bitop3:0xde
	s_cselect_b64 s[18:19], -1, 0
	s_ashr_i32 s57, s88, 31
	s_waitcnt vmcnt(6)
	s_add_u32 s20, s69, s88
	v_bitop3_b32 v142, v0, s22, v1 bitop3:0xde
	s_addc_u32 s21, s5, s57
	s_add_i32 s59, 0, 0x10000
	s_add_i32 s60, 0, 0x14000
	s_sext_i32_i8 s61, s4
	s_mov_b32 s58, s88
	s_mov_b64 s[22:23], 0x100
	v_mov_b64_e32 v[136:137], 0x100
	v_mov_b64_e32 v[138:139], 0xff
	v_add_u32_e32 v143, s59, v142
	v_add_u32_e32 v144, s60, v142
	v_add_u32_e32 v145, 0, v2
	s_mov_b64 s[24:25], 0x180
	s_barrier
	s_branch .LBB0_228

; #define PG8_STAGE(bufoff, gbase, voff) do { _Pragma("unroll") for (int _i = 0; _i < 2; ++_i) \
;         __builtin_amdgcn_global_load_lds((const unsigned*)((const char*)(gbase) + (voff)[_i]), (PG8_LAS unsigned*)(lds + (bufoff) + ldsw + _i * 8192), 16, 0, 0); } while (0)
; #define PG8_LDA(dst, b, h) do { _Pragma("unroll") for (int m = 0; m < 4; ++m) _Pragma("unroll") for (int k = 0; k < 2; ++k) dst[m][k] = *(const PG8_LAS bf16x8*)(lds + PG8_SA(b, h) + aoff + m * 2048 + k * 1024); } while (0)
; #define PG8_LDB(dst, b, h) do { _Pragma("unroll") for (int n = 0; n < 2; ++n) _Pragma("unroll") for (int k = 0; k < 2; ++k) dst[n][k] = *(const PG8_LAS bf16x8*)(lds + PG8_SB(b, h) + boff + n * 2048 + k * 1024); } while (0)
; #define PG8_MMA(ai, bj, At, Bt) do { __builtin_amdgcn_s_setprio(1); _Pragma("unroll") for (int m = 0; m < 4; ++m) _Pragma("unroll") for (int n = 0; n < 2; ++n) _Pragma("unroll") for (int k = 0; k < 2; ++k) \
;         acc[ai][bj][m][n] = __builtin_amdgcn_mfma_f32_16x16x32_bf16(Bt[n][k], At[m][k], acc[ai][bj][m][n], 0, 0, 0); __builtin_amdgcn_s_setprio(0); } while (0)
; #define PG8_WAIT_V(n) asm volatile("s_waitcnt vmcnt(" #n ")" ::: "memory")
; #define PG8_WAIT_L(n) asm volatile("s_waitcnt lgkmcnt(" #n ")" ::: "memory")
; #define PG8_BAR __builtin_amdgcn_s_barrier()
; #define PG8_SCHED __builtin_amdgcn_sched_barrier(0)
; template <class Epi, class Sched, bool ALIGN_EPI = false, bool SP2 = false>
; __device__ __forceinline__ void gemm_phase(PG8_LAS unsigned char* lds, const Gemm g, const Sched& S, const Epi& E) {
;     ...
;             PG8_LDB(B0, 0, 0); PG8_LDB(B1, 0, 1); PG8_SCHED; PG8_LDA(At, 0, 0); PG8_STAGE(PG8_SA(1, 1), a1 + hstepA, voffA);
;             PG8_WAIT_V(8); PG8_WAIT_L(0); PG8_BAR; PG8_MMA(0, 0, At, B0); PG8_MMA(0, 1, At, B1); PG8_BAR; PG8_SCHED;
;             PG8_LDA(At, 0, 1); PG8_STAGE(PG8_SB(0, 0), b2, voffB); PG8_STAGE(PG8_SB(0, 1), b2 + hstepB, voffB); PG8_STAGE(PG8_SA(0, 0), a2, voffA);
;             PG8_WAIT_V(8); PG8_WAIT_L(0); PG8_BAR; PG8_MMA(1, 0, At, B0); PG8_MMA(1, 1, At, B1); PG8_BAR; PG8_SCHED;
.LBB0_234:
	ds_read_b128 v[0:3], v143
	ds_read_b128 v[4:7], v143 offset:1024
	ds_read_b128 v[8:11], v143 offset:2048
	ds_read_b128 v[12:15], v143 offset:3072
	ds_read_b128 v[16:19], v144
	ds_read_b128 v[20:23], v144 offset:1024
	ds_read_b128 v[24:27], v144 offset:2048
	ds_read_b128 v[28:31], v144 offset:3072
	s_ashr_i32 s31, s30, 31
	s_lshl_b64 s[34:35], s[30:31], 17
	s_add_u32 s34, s54, s34
	s_addc_u32 s35, s55, s35
	s_and_b64 s[36:37], s[4:5], exec
	s_cselect_b32 s53, s35, s39
	s_cselect_b32 s52, s34, s38
	s_ashr_i32 s29, s28, 31
	s_lshl_b64 s[36:37], s[28:29], 17
	s_add_u32 s36, s2, s36
	s_addc_u32 s37, s3, s37
	s_and_b64 s[44:45], s[4:5], exec
	s_cselect_b32 s51, s37, s41
	s_cselect_b32 s50, s36, s40
	s_add_u32 s44, s38, 0x10080
	s_addc_u32 s45, s39, 0
	s_add_i32 s62, s9, 0xc000
	s_mov_b32 m0, s62
	s_add_i32 s29, s9, 0xe000
	ds_read_b128 v[32:35], v145
	ds_read_b128 v[36:39], v145 offset:1024
	ds_read_b128 v[40:43], v145 offset:2048
	ds_read_b128 v[44:47], v145 offset:3072
	ds_read_b128 v[48:51], v145 offset:4096
	ds_read_b128 v[52:55], v145 offset:5120
	ds_read_b128 v[56:59], v145 offset:6144
	ds_read_b128 v[60:63], v145 offset:7168
	global_load_lds_dwordx4 v128, s[44:45]
	s_mov_b32 m0, s29
	s_nop 0
	global_load_lds_dwordx4 v132, s[44:45]
	s_waitcnt vmcnt(8)
	s_waitcnt lgkmcnt(0)
	s_barrier
	s_setprio 1
	s_waitcnt lgkmcnt(0)
	v_mfma_f32_16x16x32_bf16 v[64:67], v[0:3], v[32:35], 0
	v_mfma_f32_16x16x32_bf16 v[68:71], v[8:11], v[32:35], 0
	v_mfma_f32_16x16x32_bf16 v[72:75], v[0:3], v[40:43], 0
	v_mfma_f32_16x16x32_bf16 v[76:79], v[8:11], v[40:43], 0
	v_mfma_f32_16x16x32_bf16 v[80:83], v[0:3], v[48:51], 0
	v_mfma_f32_16x16x32_bf16 v[84:87], v[8:11], v[48:51], 0
	v_mfma_f32_16x16x32_bf16 v[88:91], v[0:3], v[56:59], 0
	v_mfma_f32_16x16x32_bf16 v[92:95], v[8:11], v[56:59], 0
	v_mfma_f32_16x16x32_bf16 v[64:67], v[4:7], v[36:39], v[64:67]
	v_mfma_f32_16x16x32_bf16 v[68:71], v[12:15], v[36:39], v[68:71]
	v_mfma_f32_16x16x32_bf16 v[72:75], v[4:7], v[44:47], v[72:75]
	v_mfma_f32_16x16x32_bf16 v[76:79], v[12:15], v[44:47], v[76:79]
	v_mfma_f32_16x16x32_bf16 v[80:83], v[4:7], v[52:55], v[80:83]
	v_mfma_f32_16x16x32_bf16 v[84:87], v[12:15], v[52:55], v[84:87]
	v_mfma_f32_16x16x32_bf16 v[88:91], v[4:7], v[60:63], v[88:91]
	v_mfma_f32_16x16x32_bf16 v[92:95], v[12:15], v[60:63], v[92:95]
	s_setprio 0
	s_setprio 1
	v_mfma_f32_16x16x32_bf16 v[96:99], v[16:19], v[32:35], 0
	v_mfma_f32_16x16x32_bf16 v[32:35], v[24:27], v[32:35], 0
	v_mfma_f32_16x16x32_bf16 v[96:99], v[20:23], v[36:39], v[96:99]
	v_mfma_f32_16x16x32_bf16 v[32:35], v[28:31], v[36:39], v[32:35]
	v_mfma_f32_16x16x32_bf16 v[36:39], v[16:19], v[40:43], 0
	v_mfma_f32_16x16x32_bf16 v[40:43], v[24:27], v[40:43], 0
	v_mfma_f32_16x16x32_bf16 v[36:39], v[20:23], v[44:47], v[36:39]
	v_mfma_f32_16x16x32_bf16 v[40:43], v[28:31], v[44:47], v[40:43]
	v_mfma_f32_16x16x32_bf16 v[44:47], v[16:19], v[48:51], 0
	v_mfma_f32_16x16x32_bf16 v[48:51], v[24:27], v[48:51], 0
	v_mfma_f32_16x16x32_bf16 v[44:47], v[20:23], v[52:55], v[44:47]
	v_mfma_f32_16x16x32_bf16 v[48:51], v[28:31], v[52:55], v[48:51]
	v_mfma_f32_16x16x32_bf16 v[52:55], v[16:19], v[56:59], 0
	v_mfma_f32_16x16x32_bf16 v[56:59], v[24:27], v[56:59], 0
	v_mfma_f32_16x16x32_bf16 v[52:55], v[20:23], v[60:63], v[52:55]
	v_mfma_f32_16x16x32_bf16 v[56:59], v[28:31], v[60:63], v[56:59]
	s_setprio 0
	s_barrier
	s_add_i32 s48, s59, s8
	v_lshl_add_u64 v[190:191], s[40:41], 0, v[130:131]
	s_add_i32 s31, s48, 0x2000
	v_lshl_add_u64 v[146:147], v[190:191], 0, s[22:23]
	s_mov_b32 m0, s48
	v_lshl_add_u64 v[192:193], s[40:41], 0, v[134:135]
	s_add_u32 s64, s40, 0x10100
	ds_read_b128 v[60:63], v145 offset:16384
	ds_read_b128 v[100:103], v145 offset:17408
	ds_read_b128 v[104:107], v145 offset:18432
	ds_read_b128 v[108:111], v145 offset:19456
	ds_read_b128 v[112:115], v145 offset:20480
	ds_read_b128 v[116:119], v145 offset:21504
	ds_read_b128 v[120:123], v145 offset:22528
	ds_read_b128 v[124:127], v145 offset:23552
	global_load_lds_dwordx4 v[146:147], off
	v_lshl_add_u64 v[146:147], v[192:193], 0, s[22:23]
	s_mov_b32 m0, s31
	s_addc_u32 s65, s41, 0
	s_add_i32 s44, s60, s8
	global_load_lds_dwordx4 v[146:147], off
	s_mov_b32 m0, s44
	s_add_i32 s45, s44, 0x2000
	global_load_lds_dwordx4 v130, s[64:65]
	s_mov_b32 m0, s45
	v_lshl_add_u64 v[194:195], s[38:39], 0, v[128:129]
	global_load_lds_dwordx4 v134, s[64:65]
	v_lshl_add_u64 v[146:147], v[194:195], 0, s[22:23]
	s_mov_b32 m0, s9
	v_lshl_add_u64 v[216:217], s[38:39], 0, v[132:133]
	global_load_lds_dwordx4 v[146:147], off
	v_lshl_add_u64 v[146:147], v[216:217], 0, s[22:23]
	s_mov_b32 m0, s10
	s_nop 0
	global_load_lds_dwordx4 v[146:147], off
	s_waitcnt vmcnt(8)
	s_waitcnt lgkmcnt(0)
	s_barrier
; #define PG8_STAGE(bufoff, gbase, voff) do { _Pragma("unroll") for (int _i = 0; _i < 2; ++_i) \
;         __builtin_amdgcn_global_load_lds((const unsigned*)((const char*)(gbase) + (voff)[_i]), (PG8_LAS unsigned*)(lds + (bufoff) + ldsw + _i * 8192), 16, 0, 0); } while (0)
; #define PG8_LDA(dst, b, h) do { _Pragma("unroll") for (int m = 0; m < 4; ++m) _Pragma("unroll") for (int k = 0; k < 2; ++k) dst[m][k] = *(const PG8_LAS bf16x8*)(lds + PG8_SA(b, h) + aoff + m * 2048 + k * 1024); } while (0)
; #define PG8_LDB(dst, b, h) do { _Pragma("unroll") for (int n = 0; n < 2; ++n) _Pragma("unroll") for (int k = 0; k < 2; ++k) dst[n][k] = *(const PG8_LAS bf16x8*)(lds + PG8_SB(b, h) + boff + n * 2048 + k * 1024); } while (0)
; #define PG8_MMA(ai, bj, At, Bt) do { __builtin_amdgcn_s_setprio(1); _Pragma("unroll") for (int m = 0; m < 4; ++m) _Pragma("unroll") for (int n = 0; n < 2; ++n) _Pragma("unroll") for (int k = 0; k < 2; ++k) \
;         acc[ai][bj][m][n] = __builtin_amdgcn_mfma_f32_16x16x32_bf16(Bt[n][k], At[m][k], acc[ai][bj][m][n], 0, 0, 0); __builtin_amdgcn_s_setprio(0); } while (0)
; #define PG8_WAIT_V(n) asm volatile("s_waitcnt vmcnt(" #n ")" ::: "memory")
; #define PG8_WAIT_L(n) asm volatile("s_waitcnt lgkmcnt(" #n ")" ::: "memory")
; #define PG8_BAR __builtin_amdgcn_s_barrier()
; #define PG8_SCHED __builtin_amdgcn_sched_barrier(0)
; template <class Epi, class Sched, bool ALIGN_EPI = false, bool SP2 = false>
; __device__ __forceinline__ void gemm_phase(PG8_LAS unsigned char* lds, const Gemm g, const Sched& S, const Epi& E) {
;     ...
;             PG8_WAIT_V(8); PG8_WAIT_L(0); PG8_BAR; PG8_MMA(1, 0, At, B0); PG8_MMA(1, 1, At, B1); PG8_BAR; PG8_SCHED;
;             PG8_LDB(B0, 1, 0); PG8_LDB(B1, 1, 1); PG8_SCHED; PG8_LDA(At, 1, 0); PG8_STAGE(PG8_SA(0, 1), a2 + hstepA, voffA);
;             PG8_WAIT_V(8); PG8_WAIT_L(0); PG8_BAR; PG8_MMA(0, 0, At, B0); PG8_MMA(0, 1, At, B1); PG8_BAR; PG8_SCHED;
	s_setprio 1
	s_waitcnt lgkmcnt(0)
	v_mfma_f32_16x16x32_bf16 v[146:149], v[0:3], v[60:63], 0
	v_mfma_f32_16x16x32_bf16 v[154:157], v[0:3], v[104:107], 0
	v_mfma_f32_16x16x32_bf16 v[162:165], v[0:3], v[112:115], 0
	v_mfma_f32_16x16x32_bf16 v[0:3], v[0:3], v[120:123], 0
	v_mfma_f32_16x16x32_bf16 v[146:149], v[4:7], v[100:103], v[146:149]
	v_mfma_f32_16x16x32_bf16 v[154:157], v[4:7], v[108:111], v[154:157]
	v_mfma_f32_16x16x32_bf16 v[162:165], v[4:7], v[116:119], v[162:165]
	v_mfma_f32_16x16x32_bf16 v[0:3], v[4:7], v[124:127], v[0:3]
	v_mfma_f32_16x16x32_bf16 v[4:7], v[8:11], v[120:123], 0
	v_mfma_f32_16x16x32_bf16 v[150:153], v[8:11], v[60:63], 0
	v_mfma_f32_16x16x32_bf16 v[158:161], v[8:11], v[104:107], 0
	v_mfma_f32_16x16x32_bf16 v[166:169], v[8:11], v[112:115], 0
	v_mfma_f32_16x16x32_bf16 v[4:7], v[12:15], v[124:127], v[4:7]
	v_mfma_f32_16x16x32_bf16 v[150:153], v[12:15], v[100:103], v[150:153]
	v_mfma_f32_16x16x32_bf16 v[158:161], v[12:15], v[108:111], v[158:161]
	v_mfma_f32_16x16x32_bf16 v[166:169], v[12:15], v[116:119], v[166:169]
	s_setprio 0
	s_setprio 1
	v_mfma_f32_16x16x32_bf16 v[8:11], v[16:19], v[60:63], 0
	v_mfma_f32_16x16x32_bf16 v[12:15], v[24:27], v[60:63], 0
	v_mfma_f32_16x16x32_bf16 v[8:11], v[20:23], v[100:103], v[8:11]
	v_mfma_f32_16x16x32_bf16 v[12:15], v[28:31], v[100:103], v[12:15]
	v_mfma_f32_16x16x32_bf16 v[60:63], v[16:19], v[104:107], 0
	v_mfma_f32_16x16x32_bf16 v[100:103], v[24:27], v[104:107], 0
	v_mfma_f32_16x16x32_bf16 v[104:107], v[16:19], v[112:115], 0
	v_mfma_f32_16x16x32_bf16 v[16:19], v[16:19], v[120:123], 0
	v_mfma_f32_16x16x32_bf16 v[60:63], v[20:23], v[108:111], v[60:63]
	v_mfma_f32_16x16x32_bf16 v[100:103], v[28:31], v[108:111], v[100:103]
	v_mfma_f32_16x16x32_bf16 v[104:107], v[20:23], v[116:119], v[104:107]
	v_mfma_f32_16x16x32_bf16 v[108:111], v[24:27], v[112:115], 0
	v_mfma_f32_16x16x32_bf16 v[16:19], v[20:23], v[124:127], v[16:19]
	v_mfma_f32_16x16x32_bf16 v[20:23], v[24:27], v[120:123], 0
	v_mfma_f32_16x16x32_bf16 v[108:111], v[28:31], v[116:119], v[108:111]
	v_mfma_f32_16x16x32_bf16 v[20:23], v[28:31], v[124:127], v[20:23]
	s_setprio 0
	s_barrier
	s_add_i32 s63, 0, 0x18000
	s_add_i32 s66, 0, 0x1c000
	v_add_u32_e32 v220, s63, v142
	v_add_u32_e32 v228, s66, v142
	ds_read_b128 v[24:27], v220
	ds_read_b128 v[28:31], v220 offset:1024
	ds_read_b128 v[112:115], v220 offset:2048
	ds_read_b128 v[116:119], v220 offset:3072
	ds_read_b128 v[120:123], v228
	ds_read_b128 v[124:127], v228 offset:1024
	ds_read_b128 v[170:173], v228 offset:2048
	ds_read_b128 v[174:177], v228 offset:3072
	s_add_u32 s64, s38, 0x10100
	s_addc_u32 s65, s39, 0
	s_mov_b32 m0, s11
	ds_read_b128 v[178:181], v145 offset:32768
	ds_read_b128 v[182:185], v145 offset:33792
	ds_read_b128 v[186:189], v145 offset:34816
	ds_read_b128 v[196:199], v145 offset:35840
	ds_read_b128 v[200:203], v145 offset:36864
	ds_read_b128 v[204:207], v145 offset:37888
	ds_read_b128 v[208:211], v145 offset:38912
	ds_read_b128 v[212:215], v145 offset:39936
	global_load_lds_dwordx4 v128, s[64:65]
	s_mov_b32 m0, s27
	s_nop 0
	global_load_lds_dwordx4 v132, s[64:65]
	s_waitcnt vmcnt(8)
	s_waitcnt lgkmcnt(0)
	s_barrier
	s_setprio 1
	s_waitcnt lgkmcnt(0)
	v_mfma_f32_16x16x32_bf16 v[64:67], v[24:27], v[178:181], v[64:67]
	v_mfma_f32_16x16x32_bf16 v[68:71], v[112:115], v[178:181], v[68:71]
	v_mfma_f32_16x16x32_bf16 v[72:75], v[24:27], v[186:189], v[72:75]
	v_mfma_f32_16x16x32_bf16 v[76:79], v[112:115], v[186:189], v[76:79]
	v_mfma_f32_16x16x32_bf16 v[80:83], v[24:27], v[200:203], v[80:83]
	v_mfma_f32_16x16x32_bf16 v[84:87], v[112:115], v[200:203], v[84:87]
	v_mfma_f32_16x16x32_bf16 v[88:91], v[24:27], v[208:211], v[88:91]
	v_mfma_f32_16x16x32_bf16 v[92:95], v[112:115], v[208:211], v[92:95]
	v_mfma_f32_16x16x32_bf16 v[64:67], v[28:31], v[182:185], v[64:67]
	v_mfma_f32_16x16x32_bf16 v[68:71], v[116:119], v[182:185], v[68:71]
	v_mfma_f32_16x16x32_bf16 v[72:75], v[28:31], v[196:199], v[72:75]
	v_mfma_f32_16x16x32_bf16 v[76:79], v[116:119], v[196:199], v[76:79]
	v_mfma_f32_16x16x32_bf16 v[80:83], v[28:31], v[204:207], v[80:83]
	v_mfma_f32_16x16x32_bf16 v[84:87], v[116:119], v[204:207], v[84:87]
	v_mfma_f32_16x16x32_bf16 v[88:91], v[28:31], v[212:215], v[88:91]
	v_mfma_f32_16x16x32_bf16 v[92:95], v[116:119], v[212:215], v[92:95]
	s_setprio 0
	s_setprio 1
	v_mfma_f32_16x16x32_bf16 v[96:99], v[120:123], v[178:181], v[96:99]
	v_mfma_f32_16x16x32_bf16 v[32:35], v[170:173], v[178:181], v[32:35]
	v_mfma_f32_16x16x32_bf16 v[36:39], v[120:123], v[186:189], v[36:39]
	v_mfma_f32_16x16x32_bf16 v[40:43], v[170:173], v[186:189], v[40:43]
	v_mfma_f32_16x16x32_bf16 v[44:47], v[120:123], v[200:203], v[44:47]
	v_mfma_f32_16x16x32_bf16 v[48:51], v[170:173], v[200:203], v[48:51]
	v_mfma_f32_16x16x32_bf16 v[52:55], v[120:123], v[208:211], v[52:55]
	v_mfma_f32_16x16x32_bf16 v[56:59], v[170:173], v[208:211], v[56:59]
	v_mfma_f32_16x16x32_bf16 v[96:99], v[124:127], v[182:185], v[96:99]
	v_mfma_f32_16x16x32_bf16 v[32:35], v[174:177], v[182:185], v[32:35]
	v_mfma_f32_16x16x32_bf16 v[36:39], v[124:127], v[196:199], v[36:39]
	v_mfma_f32_16x16x32_bf16 v[40:43], v[174:177], v[196:199], v[40:43]
	v_mfma_f32_16x16x32_bf16 v[44:47], v[124:127], v[204:207], v[44:47]
	v_mfma_f32_16x16x32_bf16 v[48:51], v[174:177], v[204:207], v[48:51]
	v_mfma_f32_16x16x32_bf16 v[52:55], v[124:127], v[212:215], v[52:55]
	v_mfma_f32_16x16x32_bf16 v[56:59], v[174:177], v[212:215], v[56:59]
	s_setprio 0
	s_barrier
; #define PG8_STAGE(bufoff, gbase, voff) do { _Pragma("unroll") for (int _i = 0; _i < 2; ++_i) \
;         __builtin_amdgcn_global_load_lds((const unsigned*)((const char*)(gbase) + (voff)[_i]), (PG8_LAS unsigned*)(lds + (bufoff) + ldsw + _i * 8192), 16, 0, 0); } while (0)
; #define PG8_LDA(dst, b, h) do { _Pragma("unroll") for (int m = 0; m < 4; ++m) _Pragma("unroll") for (int k = 0; k < 2; ++k) dst[m][k] = *(const PG8_LAS bf16x8*)(lds + PG8_SA(b, h) + aoff + m * 2048 + k * 1024); } while (0)
; #define PG8_LDB(dst, b, h) do { _Pragma("unroll") for (int n = 0; n < 2; ++n) _Pragma("unroll") for (int k = 0; k < 2; ++k) dst[n][k] = *(const PG8_LAS bf16x8*)(lds + PG8_SB(b, h) + boff + n * 2048 + k * 1024); } while (0)
; #define PG8_MMA(ai, bj, At, Bt) do { __builtin_amdgcn_s_setprio(1); _Pragma("unroll") for (int m = 0; m < 4; ++m) _Pragma("unroll") for (int n = 0; n < 2; ++n) _Pragma("unroll") for (int k = 0; k < 2; ++k) \
;         acc[ai][bj][m][n] = __builtin_amdgcn_mfma_f32_16x16x32_bf16(Bt[n][k], At[m][k], acc[ai][bj][m][n], 0, 0, 0); __builtin_amdgcn_s_setprio(0); } while (0)
; #define PG8_WAIT_V(n) asm volatile("s_waitcnt vmcnt(" #n ")" ::: "memory")
; template <class Epi, class Sched, bool ALIGN_EPI = false, bool SP2 = false>
; __device__ __forceinline__ void gemm_phase(PG8_LAS unsigned char* lds, const Gemm g, const Sched& S, const Epi& E) {
;     ...
;             PG8_LDB(B0, 0, 0); PG8_LDB(B1, 0, 1); PG8_SCHED; PG8_LDA(At, 0, 0); PG8_STAGE(PG8_SA(1, 1), a1 + hstepA, voffA);
;             PG8_WAIT_V(8); PG8_WAIT_L(0); PG8_BAR; PG8_MMA(0, 0, At, B0); PG8_MMA(0, 1, At, B1); PG8_BAR; PG8_SCHED;
;             PG8_LDA(At, 0, 1); PG8_STAGE(PG8_SB(0, 0), b2, voffB); PG8_STAGE(PG8_SB(0, 1), b2 + hstepB, voffB); PG8_STAGE(PG8_SA(0, 0), a2, voffA);
;             PG8_WAIT_V(8); PG8_WAIT_L(0); PG8_BAR; PG8_MMA(1, 0, At, B0); PG8_MMA(1, 1, At, B1); PG8_BAR; PG8_SCHED;
;             PG8_LDB(B0, 1, 0); PG8_LDB(B1, 1, 1); PG8_SCHED; PG8_LDA(At, 1, 0); PG8_STAGE(PG8_SA(0, 1), a2 + hstepA, voffA);
;             PG8_WAIT_V(8); PG8_WAIT_L(0); PG8_BAR; PG8_MMA(0, 0, At, B0); PG8_MMA(0, 1, At, B1); PG8_BAR; PG8_SCHED;
;             PG8_LDA(At, 1, 1); PG8_STAGE(PG8_SB(1, 0), b3, voffB); PG8_STAGE(PG8_SB(1, 1), b3 + hstepB, voffB); PG8_STAGE(PG8_SA(1, 0), a3, voffA);
;             PG8_WAIT_V(8); PG8_WAIT_L(0); PG8_BAR; PG8_MMA(1, 0, At, B0); PG8_MMA(1, 1, At, B1); PG8_BAR; PG8_SCHED;
	s_add_i32 s63, s63, s8
	s_add_i32 s49, s63, 0x2000
	v_lshl_add_u64 v[190:191], v[190:191], 0, s[24:25]
	s_mov_b32 m0, s63
	s_add_u32 s64, s40, 0x10180
	ds_read_b128 v[178:181], v145 offset:49152
	ds_read_b128 v[182:185], v145 offset:50176
	ds_read_b128 v[186:189], v145 offset:51200
	ds_read_b128 v[196:199], v145 offset:52224
	ds_read_b128 v[200:203], v145 offset:53248
	ds_read_b128 v[204:207], v145 offset:54272
	ds_read_b128 v[208:211], v145 offset:55296
	ds_read_b128 v[212:215], v145 offset:56320
	global_load_lds_dwordx4 v[190:191], off
	v_lshl_add_u64 v[190:191], v[192:193], 0, s[24:25]
	s_mov_b32 m0, s49
	s_addc_u32 s65, s41, 0
	s_add_i32 s40, s66, s8
	global_load_lds_dwordx4 v[190:191], off
	s_mov_b32 m0, s40
	s_add_i32 s41, s40, 0x2000
	global_load_lds_dwordx4 v130, s[64:65]
	s_mov_b32 m0, s41
	s_nop 0
	global_load_lds_dwordx4 v134, s[64:65]
	v_lshl_add_u64 v[190:191], v[194:195], 0, s[24:25]
	s_mov_b32 m0, s43
	s_nop 0
	global_load_lds_dwordx4 v[190:191], off
	v_lshl_add_u64 v[190:191], v[216:217], 0, s[24:25]
	s_mov_b32 m0, s56
	s_nop 0
	global_load_lds_dwordx4 v[190:191], off
	s_waitcnt vmcnt(8)
	s_waitcnt lgkmcnt(0)
	s_barrier
	s_setprio 1
	s_waitcnt lgkmcnt(0)
	v_mfma_f32_16x16x32_bf16 v[0:3], v[24:27], v[208:211], v[0:3]
	v_mfma_f32_16x16x32_bf16 v[4:7], v[112:115], v[208:211], v[4:7]
	v_mfma_f32_16x16x32_bf16 v[146:149], v[24:27], v[178:181], v[146:149]
	v_mfma_f32_16x16x32_bf16 v[150:153], v[112:115], v[178:181], v[150:153]
	v_mfma_f32_16x16x32_bf16 v[154:157], v[24:27], v[186:189], v[154:157]
	v_mfma_f32_16x16x32_bf16 v[158:161], v[112:115], v[186:189], v[158:161]
	v_mfma_f32_16x16x32_bf16 v[162:165], v[24:27], v[200:203], v[162:165]
	v_mfma_f32_16x16x32_bf16 v[166:169], v[112:115], v[200:203], v[166:169]
	v_mfma_f32_16x16x32_bf16 v[0:3], v[28:31], v[212:215], v[0:3]
	v_mfma_f32_16x16x32_bf16 v[4:7], v[116:119], v[212:215], v[4:7]
	v_mfma_f32_16x16x32_bf16 v[146:149], v[28:31], v[182:185], v[146:149]
	v_mfma_f32_16x16x32_bf16 v[150:153], v[116:119], v[182:185], v[150:153]
	v_mfma_f32_16x16x32_bf16 v[154:157], v[28:31], v[196:199], v[154:157]
	v_mfma_f32_16x16x32_bf16 v[158:161], v[116:119], v[196:199], v[158:161]
	v_mfma_f32_16x16x32_bf16 v[162:165], v[28:31], v[204:207], v[162:165]
	v_mfma_f32_16x16x32_bf16 v[166:169], v[116:119], v[204:207], v[166:169]
	s_setprio 0
	s_setprio 1
	v_mfma_f32_16x16x32_bf16 v[8:11], v[120:123], v[178:181], v[8:11]
	v_mfma_f32_16x16x32_bf16 v[12:15], v[170:173], v[178:181], v[12:15]
	v_mfma_f32_16x16x32_bf16 v[24:27], v[120:123], v[186:189], v[60:63]
	v_mfma_f32_16x16x32_bf16 v[28:31], v[170:173], v[186:189], v[100:103]
	v_mfma_f32_16x16x32_bf16 v[60:63], v[120:123], v[200:203], v[104:107]
	v_mfma_f32_16x16x32_bf16 v[100:103], v[170:173], v[200:203], v[108:111]
	v_mfma_f32_16x16x32_bf16 v[16:19], v[120:123], v[208:211], v[16:19]
	v_mfma_f32_16x16x32_bf16 v[20:23], v[170:173], v[208:211], v[20:23]
	v_mfma_f32_16x16x32_bf16 v[8:11], v[124:127], v[182:185], v[8:11]
	v_mfma_f32_16x16x32_bf16 v[12:15], v[174:177], v[182:185], v[12:15]
	v_mfma_f32_16x16x32_bf16 v[24:27], v[124:127], v[196:199], v[24:27]
	v_mfma_f32_16x16x32_bf16 v[28:31], v[174:177], v[196:199], v[28:31]
	v_mfma_f32_16x16x32_bf16 v[60:63], v[124:127], v[204:207], v[60:63]
	v_mfma_f32_16x16x32_bf16 v[100:103], v[174:177], v[204:207], v[100:103]
	v_mfma_f32_16x16x32_bf16 v[16:19], v[124:127], v[212:215], v[16:19]
	v_mfma_f32_16x16x32_bf16 v[20:23], v[174:177], v[212:215], v[20:23]
	s_setprio 0
	s_barrier
	ds_read_b128 v[104:107], v143
	ds_read_b128 v[108:111], v143 offset:1024
	ds_read_b128 v[112:115], v143 offset:2048
	ds_read_b128 v[116:119], v143 offset:3072
	ds_read_b128 v[120:123], v144
	ds_read_b128 v[124:127], v144 offset:1024
	ds_read_b128 v[170:173], v144 offset:2048
	ds_read_b128 v[174:177], v144 offset:3072
	s_add_u32 s38, s38, 0x10180
	s_addc_u32 s39, s39, 0
	s_mov_b32 m0, s62
	ds_read_b128 v[178:181], v145
	ds_read_b128 v[182:185], v145 offset:1024
	ds_read_b128 v[186:189], v145 offset:2048
	ds_read_b128 v[196:199], v145 offset:3072
	ds_read_b128 v[200:203], v145 offset:4096
	ds_read_b128 v[204:207], v145 offset:5120
	ds_read_b128 v[208:211], v145 offset:6144
	ds_read_b128 v[212:215], v145 offset:7168
	global_load_lds_dwordx4 v128, s[38:39]
	s_mov_b32 m0, s29
	s_nop 0
	global_load_lds_dwordx4 v132, s[38:39]
	s_waitcnt vmcnt(8)
	s_waitcnt lgkmcnt(0)
	s_barrier
	s_setprio 1
	s_waitcnt lgkmcnt(0)
	v_mfma_f32_16x16x32_bf16 v[64:67], v[104:107], v[178:181], v[64:67]
	v_mfma_f32_16x16x32_bf16 v[68:71], v[112:115], v[178:181], v[68:71]
	v_mfma_f32_16x16x32_bf16 v[72:75], v[104:107], v[186:189], v[72:75]
	v_mfma_f32_16x16x32_bf16 v[76:79], v[112:115], v[186:189], v[76:79]
	v_mfma_f32_16x16x32_bf16 v[80:83], v[104:107], v[200:203], v[80:83]
	v_mfma_f32_16x16x32_bf16 v[84:87], v[112:115], v[200:203], v[84:87]
	v_mfma_f32_16x16x32_bf16 v[88:91], v[104:107], v[208:211], v[88:91]
	v_mfma_f32_16x16x32_bf16 v[92:95], v[112:115], v[208:211], v[92:95]
	v_mfma_f32_16x16x32_bf16 v[64:67], v[108:111], v[182:185], v[64:67]
	v_mfma_f32_16x16x32_bf16 v[68:71], v[116:119], v[182:185], v[68:71]
	v_mfma_f32_16x16x32_bf16 v[72:75], v[108:111], v[196:199], v[72:75]
	v_mfma_f32_16x16x32_bf16 v[76:79], v[116:119], v[196:199], v[76:79]
	v_mfma_f32_16x16x32_bf16 v[80:83], v[108:111], v[204:207], v[80:83]
	v_mfma_f32_16x16x32_bf16 v[84:87], v[116:119], v[204:207], v[84:87]
	v_mfma_f32_16x16x32_bf16 v[88:91], v[108:111], v[212:215], v[88:91]
	v_mfma_f32_16x16x32_bf16 v[92:95], v[116:119], v[212:215], v[92:95]
	s_setprio 0
	s_setprio 1
	v_mfma_f32_16x16x32_bf16 v[32:35], v[170:173], v[178:181], v[32:35]
	v_mfma_f32_16x16x32_bf16 v[96:99], v[120:123], v[178:181], v[96:99]
	v_mfma_f32_16x16x32_bf16 v[178:181], v[174:177], v[182:185], v[32:35]
	v_mfma_f32_16x16x32_bf16 v[32:35], v[120:123], v[186:189], v[36:39]
	v_mfma_f32_16x16x32_bf16 v[216:219], v[124:127], v[182:185], v[96:99]
	v_mfma_f32_16x16x32_bf16 v[182:185], v[124:127], v[196:199], v[32:35]
	v_mfma_f32_16x16x32_bf16 v[32:35], v[170:173], v[186:189], v[40:43]
	v_mfma_f32_16x16x32_bf16 v[40:43], v[174:177], v[196:199], v[32:35]
	v_mfma_f32_16x16x32_bf16 v[32:35], v[120:123], v[200:203], v[44:47]
	v_mfma_f32_16x16x32_bf16 v[44:47], v[124:127], v[204:207], v[32:35]
	v_mfma_f32_16x16x32_bf16 v[32:35], v[170:173], v[200:203], v[48:51]
	v_mfma_f32_16x16x32_bf16 v[48:51], v[174:177], v[204:207], v[32:35]
	v_mfma_f32_16x16x32_bf16 v[32:35], v[120:123], v[208:211], v[52:55]
	v_mfma_f32_16x16x32_bf16 v[52:55], v[124:127], v[212:215], v[32:35]
	v_mfma_f32_16x16x32_bf16 v[32:35], v[170:173], v[208:211], v[56:59]
	v_mfma_f32_16x16x32_bf16 v[56:59], v[174:177], v[212:215], v[32:35]
	s_setprio 0
	s_barrier
; #define PG8_STAGE(bufoff, gbase, voff) do { _Pragma("unroll") for (int _i = 0; _i < 2; ++_i) \
;         __builtin_amdgcn_global_load_lds((const unsigned*)((const char*)(gbase) + (voff)[_i]), (PG8_LAS unsigned*)(lds + (bufoff) + ldsw + _i * 8192), 16, 0, 0); } while (0)
; #define PG8_LDA(dst, b, h) do { _Pragma("unroll") for (int m = 0; m < 4; ++m) _Pragma("unroll") for (int k = 0; k < 2; ++k) dst[m][k] = *(const PG8_LAS bf16x8*)(lds + PG8_SA(b, h) + aoff + m * 2048 + k * 1024); } while (0)
; #define PG8_LDB(dst, b, h) do { _Pragma("unroll") for (int n = 0; n < 2; ++n) _Pragma("unroll") for (int k = 0; k < 2; ++k) dst[n][k] = *(const PG8_LAS bf16x8*)(lds + PG8_SB(b, h) + boff + n * 2048 + k * 1024); } while (0)
; #define PG8_MMA(ai, bj, At, Bt) do { __builtin_amdgcn_s_setprio(1); _Pragma("unroll") for (int m = 0; m < 4; ++m) _Pragma("unroll") for (int n = 0; n < 2; ++n) _Pragma("unroll") for (int k = 0; k < 2; ++k) \
;         acc[ai][bj][m][n] = __builtin_amdgcn_mfma_f32_16x16x32_bf16(Bt[n][k], At[m][k], acc[ai][bj][m][n], 0, 0, 0); __builtin_amdgcn_s_setprio(0); } while (0)
; #define PG8_WAIT_V(n) asm volatile("s_waitcnt vmcnt(" #n ")" ::: "memory")
; #define PG8_WAIT_L(n) asm volatile("s_waitcnt lgkmcnt(" #n ")" ::: "memory")
; #define PG8_BAR __builtin_amdgcn_s_barrier()
; #define PG8_SCHED __builtin_amdgcn_sched_barrier(0)
; template <class Epi, class Sched, bool ALIGN_EPI = false, bool SP2 = false>
; __device__ __forceinline__ void gemm_phase(PG8_LAS unsigned char* lds, const Gemm g, const Sched& S, const Epi& E) {
;     ...
;             PG8_WAIT_V(8); PG8_WAIT_L(0); PG8_BAR; PG8_MMA(0, 0, At, B0); PG8_MMA(0, 1, At, B1); PG8_BAR; PG8_SCHED;
;             PG8_LDA(At, 0, 1); PG8_STAGE(PG8_SB(0, 0), b2, voffB); PG8_STAGE(PG8_SB(0, 1), b2 + hstepB, voffB); PG8_STAGE(PG8_SA(0, 0), a2, voffA);
;             PG8_WAIT_V(8); PG8_WAIT_L(0); PG8_BAR; PG8_MMA(1, 0, At, B0); PG8_MMA(1, 1, At, B1); PG8_BAR; PG8_SCHED;
;             PG8_LDB(B0, 1, 0); PG8_LDB(B1, 1, 1); PG8_SCHED; PG8_LDA(At, 1, 0); PG8_STAGE(PG8_SA(0, 1), a2 + hstepA, voffA);
	s_mov_b32 m0, s48
	v_lshl_add_u64 v[190:191], s[50:51], 0, v[130:131]
	s_add_u32 s38, s50, 0x10000
	s_nop 1
	ds_read_b128 v[32:35], v145 offset:16384
	ds_read_b128 v[36:39], v145 offset:17408
	ds_read_b128 v[96:99], v145 offset:18432
	ds_read_b128 v[186:189], v145 offset:19456
	ds_read_b128 v[196:199], v145 offset:20480
	ds_read_b128 v[200:203], v145 offset:21504
	ds_read_b128 v[204:207], v145 offset:22528
	ds_read_b128 v[208:211], v145 offset:23552
	global_load_lds_dwordx4 v[190:191], off
	v_lshl_add_u64 v[192:193], s[50:51], 0, v[134:135]
	s_mov_b32 m0, s31
	s_addc_u32 s39, s51, 0
	global_load_lds_dwordx4 v[192:193], off
	s_mov_b32 m0, s44
	v_lshl_add_u64 v[252:253], s[52:53], 0, v[132:133]
	global_load_lds_dwordx4 v130, s[38:39]
	s_mov_b32 m0, s45
	s_nop 0
	global_load_lds_dwordx4 v134, s[38:39]
	v_lshl_add_u64 v[194:195], s[52:53], 0, v[128:129]
	s_mov_b32 m0, s9
	s_nop 0
	global_load_lds_dwordx4 v[194:195], off
	s_mov_b32 m0, s10
	s_nop 0
	global_load_lds_dwordx4 v[252:253], off
	s_waitcnt vmcnt(8)
	s_waitcnt lgkmcnt(0)
	s_barrier
	s_setprio 1
	s_waitcnt lgkmcnt(0)
	v_mfma_f32_16x16x32_bf16 v[0:3], v[104:107], v[204:207], v[0:3]
	v_mfma_f32_16x16x32_bf16 v[4:7], v[112:115], v[204:207], v[4:7]
	v_mfma_f32_16x16x32_bf16 v[146:149], v[104:107], v[32:35], v[146:149]
	v_mfma_f32_16x16x32_bf16 v[150:153], v[112:115], v[32:35], v[150:153]
	v_mfma_f32_16x16x32_bf16 v[154:157], v[104:107], v[96:99], v[154:157]
	v_mfma_f32_16x16x32_bf16 v[158:161], v[112:115], v[96:99], v[158:161]
	v_mfma_f32_16x16x32_bf16 v[162:165], v[104:107], v[196:199], v[162:165]
	v_mfma_f32_16x16x32_bf16 v[166:169], v[112:115], v[196:199], v[166:169]
	v_mfma_f32_16x16x32_bf16 v[0:3], v[108:111], v[208:211], v[0:3]
	v_mfma_f32_16x16x32_bf16 v[4:7], v[116:119], v[208:211], v[4:7]
	v_mfma_f32_16x16x32_bf16 v[146:149], v[108:111], v[36:39], v[146:149]
	v_mfma_f32_16x16x32_bf16 v[150:153], v[116:119], v[36:39], v[150:153]
	v_mfma_f32_16x16x32_bf16 v[154:157], v[108:111], v[186:189], v[154:157]
	v_mfma_f32_16x16x32_bf16 v[158:161], v[116:119], v[186:189], v[158:161]
	v_mfma_f32_16x16x32_bf16 v[162:165], v[108:111], v[200:203], v[162:165]
	v_mfma_f32_16x16x32_bf16 v[166:169], v[116:119], v[200:203], v[166:169]
	s_setprio 0
	s_setprio 1
	v_mfma_f32_16x16x32_bf16 v[8:11], v[120:123], v[32:35], v[8:11]
	v_mfma_f32_16x16x32_bf16 v[12:15], v[170:173], v[32:35], v[12:15]
	v_mfma_f32_16x16x32_bf16 v[24:27], v[120:123], v[96:99], v[24:27]
	v_mfma_f32_16x16x32_bf16 v[28:31], v[170:173], v[96:99], v[28:31]
	v_mfma_f32_16x16x32_bf16 v[32:35], v[120:123], v[196:199], v[60:63]
	v_mfma_f32_16x16x32_bf16 v[24:27], v[124:127], v[186:189], v[24:27]
	v_mfma_f32_16x16x32_bf16 v[28:31], v[174:177], v[186:189], v[28:31]
	v_mfma_f32_16x16x32_bf16 v[186:189], v[124:127], v[200:203], v[32:35]
	v_mfma_f32_16x16x32_bf16 v[32:35], v[170:173], v[196:199], v[100:103]
	v_mfma_f32_16x16x32_bf16 v[16:19], v[120:123], v[204:207], v[16:19]
	v_mfma_f32_16x16x32_bf16 v[8:11], v[124:127], v[36:39], v[8:11]
	v_mfma_f32_16x16x32_bf16 v[12:15], v[174:177], v[36:39], v[12:15]
	v_mfma_f32_16x16x32_bf16 v[196:199], v[174:177], v[200:203], v[32:35]
	v_mfma_f32_16x16x32_bf16 v[200:203], v[124:127], v[208:211], v[16:19]
	v_mfma_f32_16x16x32_bf16 v[16:19], v[170:173], v[204:207], v[20:23]
	v_mfma_f32_16x16x32_bf16 v[170:173], v[174:177], v[208:211], v[16:19]
	s_setprio 0
	s_barrier
	ds_read_b128 v[60:63], v220
	ds_read_b128 v[174:177], v220 offset:1024
	ds_read_b128 v[204:207], v220 offset:2048
	ds_read_b128 v[208:211], v220 offset:3072
	ds_read_b128 v[212:215], v228
	ds_read_b128 v[220:223], v228 offset:1024
	ds_read_b128 v[224:227], v228 offset:2048
	ds_read_b128 v[228:231], v228 offset:3072
	s_add_u32 s38, s52, 0x10000
	s_addc_u32 s39, s53, 0
	s_mov_b32 m0, s11
	ds_read_b128 v[16:19], v145 offset:32768
	ds_read_b128 v[20:23], v145 offset:33792
	ds_read_b128 v[108:111], v145 offset:34816
	ds_read_b128 v[232:235], v145 offset:35840
	ds_read_b128 v[236:239], v145 offset:36864
	ds_read_b128 v[240:243], v145 offset:37888
	ds_read_b128 v[244:247], v145 offset:38912
	ds_read_b128 v[248:251], v145 offset:39936
	global_load_lds_dwordx4 v128, s[38:39]
	s_mov_b32 m0, s27
	s_nop 0
	global_load_lds_dwordx4 v132, s[38:39]
	s_waitcnt vmcnt(8)
	s_waitcnt lgkmcnt(0)
	s_barrier
; #define PG8_STAGE(bufoff, gbase, voff) do { _Pragma("unroll") for (int _i = 0; _i < 2; ++_i) \
;         __builtin_amdgcn_global_load_lds((const unsigned*)((const char*)(gbase) + (voff)[_i]), (PG8_LAS unsigned*)(lds + (bufoff) + ldsw + _i * 8192), 16, 0, 0); } while (0)
; #define PG8_LDA(dst, b, h) do { _Pragma("unroll") for (int m = 0; m < 4; ++m) _Pragma("unroll") for (int k = 0; k < 2; ++k) dst[m][k] = *(const PG8_LAS bf16x8*)(lds + PG8_SA(b, h) + aoff + m * 2048 + k * 1024); } while (0)
; #define PG8_LDB(dst, b, h) do { _Pragma("unroll") for (int n = 0; n < 2; ++n) _Pragma("unroll") for (int k = 0; k < 2; ++k) dst[n][k] = *(const PG8_LAS bf16x8*)(lds + PG8_SB(b, h) + boff + n * 2048 + k * 1024); } while (0)
; #define PG8_MMA(ai, bj, At, Bt) do { __builtin_amdgcn_s_setprio(1); _Pragma("unroll") for (int m = 0; m < 4; ++m) _Pragma("unroll") for (int n = 0; n < 2; ++n) _Pragma("unroll") for (int k = 0; k < 2; ++k) \
;         acc[ai][bj][m][n] = __builtin_amdgcn_mfma_f32_16x16x32_bf16(Bt[n][k], At[m][k], acc[ai][bj][m][n], 0, 0, 0); __builtin_amdgcn_s_setprio(0); } while (0)
; #define PG8_WAIT_V(n) asm volatile("s_waitcnt vmcnt(" #n ")" ::: "memory")
; #define PG8_WAIT_L(n) asm volatile("s_waitcnt lgkmcnt(" #n ")" ::: "memory")
; #define PG8_BAR __builtin_amdgcn_s_barrier()
; #define PG8_SCHED __builtin_amdgcn_sched_barrier(0)
; template <class Epi, class Sched, bool ALIGN_EPI = false, bool SP2 = false>
; __device__ __forceinline__ void gemm_phase(PG8_LAS unsigned char* lds, const Gemm g, const Sched& S, const Epi& E) {
;     ...
;             PG8_WAIT_V(8); PG8_WAIT_L(0); PG8_BAR; PG8_MMA(1, 0, At, B0); PG8_MMA(1, 1, At, B1); PG8_BAR; PG8_SCHED;
;             PG8_LDB(B0, 1, 0); PG8_LDB(B1, 1, 1); PG8_SCHED; PG8_LDA(At, 1, 0); PG8_STAGE(PG8_SA(0, 1), a2 + hstepA, voffA);
;             PG8_WAIT_V(8); PG8_WAIT_L(0); PG8_BAR; PG8_MMA(0, 0, At, B0); PG8_MMA(0, 1, At, B1); PG8_BAR; PG8_SCHED;
;             PG8_LDA(At, 1, 1); PG8_STAGE(PG8_SB(1, 0), b3, voffB); PG8_STAGE(PG8_SB(1, 1), b3 + hstepB, voffB); PG8_STAGE(PG8_SA(1, 0), a3, voffA);
;             PG8_WAIT_V(8); PG8_WAIT_L(0); PG8_BAR; PG8_MMA(1, 0, At, B0); PG8_MMA(1, 1, At, B1); PG8_BAR; PG8_SCHED;
;     ...
;         if constexpr (ALIGN_EPI) { if (wr == 0) PG8_BAR; }
	s_setprio 1
	s_waitcnt lgkmcnt(0)
	v_mfma_f32_16x16x32_bf16 v[32:35], v[60:63], v[16:19], v[64:67]
	v_mfma_f32_16x16x32_bf16 v[112:115], v[174:177], v[20:23], v[32:35]
	v_mfma_f32_16x16x32_bf16 v[32:35], v[204:207], v[16:19], v[68:71]
	v_mfma_f32_16x16x32_bf16 v[116:119], v[208:211], v[20:23], v[32:35]
	v_mfma_f32_16x16x32_bf16 v[32:35], v[60:63], v[108:111], v[72:75]
	v_mfma_f32_16x16x32_bf16 v[96:99], v[174:177], v[232:235], v[32:35]
	v_mfma_f32_16x16x32_bf16 v[32:35], v[204:207], v[108:111], v[76:79]
	v_mfma_f32_16x16x32_bf16 v[100:103], v[208:211], v[232:235], v[32:35]
	v_mfma_f32_16x16x32_bf16 v[32:35], v[60:63], v[236:239], v[80:83]
	v_mfma_f32_16x16x32_bf16 v[64:67], v[174:177], v[240:243], v[32:35]
	v_mfma_f32_16x16x32_bf16 v[32:35], v[204:207], v[236:239], v[84:87]
	v_mfma_f32_16x16x32_bf16 v[68:71], v[208:211], v[240:243], v[32:35]
	v_mfma_f32_16x16x32_bf16 v[32:35], v[60:63], v[244:247], v[88:91]
	v_mfma_f32_16x16x32_bf16 v[36:39], v[204:207], v[244:247], v[92:95]
	v_mfma_f32_16x16x32_bf16 v[32:35], v[174:177], v[248:251], v[32:35]
	v_mfma_f32_16x16x32_bf16 v[36:39], v[208:211], v[248:251], v[36:39]
	s_setprio 0
	s_setprio 1
	v_mfma_f32_16x16x32_bf16 v[72:75], v[212:215], v[16:19], v[216:219]
	v_mfma_f32_16x16x32_bf16 v[16:19], v[224:227], v[16:19], v[178:181]
	v_mfma_f32_16x16x32_bf16 v[124:127], v[228:231], v[20:23], v[16:19]
	v_mfma_f32_16x16x32_bf16 v[16:19], v[212:215], v[108:111], v[182:185]
	v_mfma_f32_16x16x32_bf16 v[104:107], v[220:223], v[232:235], v[16:19]
	v_mfma_f32_16x16x32_bf16 v[16:19], v[224:227], v[108:111], v[40:43]
	v_mfma_f32_16x16x32_bf16 v[108:111], v[228:231], v[232:235], v[16:19]
	v_mfma_f32_16x16x32_bf16 v[16:19], v[212:215], v[236:239], v[44:47]
	v_mfma_f32_16x16x32_bf16 v[120:123], v[220:223], v[20:23], v[72:75]
	v_mfma_f32_16x16x32_bf16 v[72:75], v[220:223], v[240:243], v[16:19]
	v_mfma_f32_16x16x32_bf16 v[16:19], v[224:227], v[236:239], v[48:51]
	v_mfma_f32_16x16x32_bf16 v[76:79], v[228:231], v[240:243], v[16:19]
	v_mfma_f32_16x16x32_bf16 v[16:19], v[212:215], v[244:247], v[52:55]
	v_mfma_f32_16x16x32_bf16 v[40:43], v[220:223], v[248:251], v[16:19]
	v_mfma_f32_16x16x32_bf16 v[16:19], v[224:227], v[244:247], v[56:59]
	v_mfma_f32_16x16x32_bf16 v[44:47], v[228:231], v[248:251], v[16:19]
	s_setprio 0
	s_barrier
	s_mov_b32 m0, s63
	s_nop 3
	v_lshl_add_u64 v[16:17], v[190:191], 0, s[16:17]
	s_add_u32 s38, s50, 0x10080
	ds_read_b128 v[56:59], v145 offset:49152
	ds_read_b128 v[92:95], v145 offset:50176
	ds_read_b128 v[178:181], v145 offset:51200
	ds_read_b128 v[182:185], v145 offset:52224
	ds_read_b128 v[216:219], v145 offset:53248
	ds_read_b128 v[232:235], v145 offset:54272
	ds_read_b128 v[236:239], v145 offset:55296
	ds_read_b128 v[240:243], v145 offset:56320
	global_load_lds_dwordx4 v[16:17], off
	v_lshl_add_u64 v[16:17], v[192:193], 0, s[16:17]
	s_mov_b32 m0, s49
	s_addc_u32 s39, s51, 0
	global_load_lds_dwordx4 v[16:17], off
	s_mov_b32 m0, s40
	s_nop 0
	global_load_lds_dwordx4 v130, s[38:39]
	s_mov_b32 m0, s41
	s_nop 0
	global_load_lds_dwordx4 v134, s[38:39]
	v_lshl_add_u64 v[16:17], v[194:195], 0, s[16:17]
	s_mov_b32 m0, s43
	s_nop 0
	global_load_lds_dwordx4 v[16:17], off
	v_lshl_add_u64 v[16:17], v[252:253], 0, s[16:17]
	s_mov_b32 m0, s56
	s_nop 0
	global_load_lds_dwordx4 v[16:17], off
	s_waitcnt vmcnt(8)
	s_waitcnt lgkmcnt(0)
	s_barrier
	s_setprio 1
	s_waitcnt lgkmcnt(0)
	v_mfma_f32_16x16x32_bf16 v[16:19], v[60:63], v[56:59], v[146:149]
	v_mfma_f32_16x16x32_bf16 v[80:83], v[174:177], v[92:95], v[16:19]
	v_mfma_f32_16x16x32_bf16 v[16:19], v[204:207], v[56:59], v[150:153]
	v_mfma_f32_16x16x32_bf16 v[84:87], v[208:211], v[92:95], v[16:19]
	v_mfma_f32_16x16x32_bf16 v[16:19], v[60:63], v[178:181], v[154:157]
	v_mfma_f32_16x16x32_bf16 v[48:51], v[174:177], v[182:185], v[16:19]
	v_mfma_f32_16x16x32_bf16 v[16:19], v[204:207], v[178:181], v[158:161]
	v_mfma_f32_16x16x32_bf16 v[52:55], v[208:211], v[182:185], v[16:19]
	v_mfma_f32_16x16x32_bf16 v[16:19], v[60:63], v[216:219], v[162:165]
	v_mfma_f32_16x16x32_bf16 v[20:23], v[204:207], v[216:219], v[166:169]
	v_mfma_f32_16x16x32_bf16 v[0:3], v[60:63], v[236:239], v[0:3]
	v_mfma_f32_16x16x32_bf16 v[4:7], v[204:207], v[236:239], v[4:7]
	v_mfma_f32_16x16x32_bf16 v[16:19], v[174:177], v[232:235], v[16:19]
	v_mfma_f32_16x16x32_bf16 v[20:23], v[208:211], v[232:235], v[20:23]
	v_mfma_f32_16x16x32_bf16 v[0:3], v[174:177], v[240:243], v[0:3]
	v_mfma_f32_16x16x32_bf16 v[4:7], v[208:211], v[240:243], v[4:7]
	s_setprio 0
	s_setprio 1
	v_mfma_f32_16x16x32_bf16 v[8:11], v[212:215], v[56:59], v[8:11]
	v_mfma_f32_16x16x32_bf16 v[88:91], v[220:223], v[92:95], v[8:11]
	v_mfma_f32_16x16x32_bf16 v[8:11], v[224:227], v[56:59], v[12:15]
	v_mfma_f32_16x16x32_bf16 v[92:95], v[228:231], v[92:95], v[8:11]
	v_mfma_f32_16x16x32_bf16 v[8:11], v[212:215], v[178:181], v[24:27]
	v_mfma_f32_16x16x32_bf16 v[56:59], v[220:223], v[182:185], v[8:11]
	v_mfma_f32_16x16x32_bf16 v[8:11], v[224:227], v[178:181], v[28:31]
	v_mfma_f32_16x16x32_bf16 v[60:63], v[228:231], v[182:185], v[8:11]
	v_mfma_f32_16x16x32_bf16 v[8:11], v[212:215], v[216:219], v[186:189]
	v_mfma_f32_16x16x32_bf16 v[24:27], v[220:223], v[232:235], v[8:11]
	v_mfma_f32_16x16x32_bf16 v[8:11], v[224:227], v[216:219], v[196:199]
	v_mfma_f32_16x16x32_bf16 v[28:31], v[228:231], v[232:235], v[8:11]
	v_mfma_f32_16x16x32_bf16 v[8:11], v[212:215], v[236:239], v[200:203]
	v_mfma_f32_16x16x32_bf16 v[12:15], v[224:227], v[236:239], v[170:173]
	v_mfma_f32_16x16x32_bf16 v[8:11], v[220:223], v[240:243], v[8:11]
	v_mfma_f32_16x16x32_bf16 v[12:15], v[228:231], v[240:243], v[12:15]
	s_setprio 0
	s_barrier
	s_andn2_b64 vcc, exec, s[18:19]
	s_cbranch_vccnz .LBB0_236
	s_barrier

; #define PG8_STAGE(bufoff, gbase, voff) do { _Pragma("unroll") for (int _i = 0; _i < 2; ++_i) \
;         __builtin_amdgcn_global_load_lds((const unsigned*)((const char*)(gbase) + (voff)[_i]), (PG8_LAS unsigned*)(lds + (bufoff) + ldsw + _i * 8192), 16, 0, 0); } while (0)
; #define PG8_WAIT_V(n) asm volatile("s_waitcnt vmcnt(" #n ")" ::: "memory")
; #define PG8_BAR __builtin_amdgcn_s_barrier()
; template <class Epi, class Sched, bool ALIGN_EPI = false, bool SP2 = false>
; __device__ __forceinline__ void gemm_phase(PG8_LAS unsigned char* lds, const Gemm g, const Sched& S, const Epi& E) {
;     ...
;         PG8_STAGE(PG8_SB(0, 0), cB, voffB); PG8_STAGE(PG8_SB(0, 1), cB + hstepB, voffB); PG8_STAGE(PG8_SA(0, 0), cA, voffA); PG8_STAGE(PG8_SA(0, 1), cA + hstepA, voffA);
;         if (wr == 1) PG8_BAR;
;         PG8_WAIT_V(2); PG8_BAR;
;         PG8_STAGE(PG8_SB(1, 0), cB + kstep, voffB); PG8_STAGE(PG8_SA(1, 0), cA + kstep, voffA); PG8_STAGE(PG8_SB(1, 1), cB + hstepB + kstep, voffB);
;         PG8_WAIT_V(6); PG8_BAR;
.LBB0_295:
	s_lshl_b32 s1, s1, 5
	s_mov_b64 s[16:17], 0x80
	s_and_b32 s34, s1, 0x60
	s_add_i32 m0, s8, 0x18000
	v_lshl_add_u64 v[6:7], v[6:7], 0, s[16:17]
	s_lshl_b32 s33, s4, 6
	s_lshl_b32 s4, s4, 13
	s_lshl_b32 s1, s34, 7
	s_waitcnt vmcnt(2)
	s_barrier
	global_load_lds_dwordx4 v[6:7], off
	v_lshl_add_u64 v[4:5], v[4:5], 0, s[16:17]
	s_add_i32 m0, s8, 0x1a000
	s_add_i32 s35, s8, 0x8000
	s_add_i32 s36, s8, 0xa000
	global_load_lds_dwordx4 v[4:5], off
	v_lshl_add_u64 v[0:1], v[0:1], 0, s[16:17]
	s_mov_b32 m0, s35
	s_add_u32 s18, s28, 0x18080
	global_load_lds_dwordx4 v[0:1], off
	v_lshl_add_u64 v[0:1], v[2:3], 0, s[16:17]
	s_mov_b32 m0, s36
	s_addc_u32 s19, s29, 0
	global_load_lds_dwordx4 v[0:1], off
	s_add_i32 m0, s8, 0x1c000
	s_nop 0
	global_load_lds_dwordx4 v132, s[18:19]
	v_lshl_add_u64 v[0:1], s[18:19], 0, v[128:129]
	s_add_i32 m0, s8, 0x1e000
	v_bfe_u32 v144, v10, 4, 2
	global_load_lds_dwordx4 v[0:1], off
	v_and_b32_e32 v145, 15, v10
	v_lshlrev_b32_e32 v0, 4, v144
	v_lshlrev_b32_e32 v1, 2, v10
	v_lshl_or_b32 v0, v145, 6, v0
	v_and_b32_e32 v1, 32, v1
	v_bitop3_b32 v2, v0, s4, v1 bitop3:0xde
	v_bitop3_b32 v146, v0, s1, v1 bitop3:0xde
	v_lshlrev_b32_e32 v0, 15, v13
	v_and_b32_e32 v0, 0xffff0000, v0
	v_lshl_add_u32 v0, v12, 12, v0
	v_and_b32_e32 v1, 1, v13
	v_lshl_or_b32 v0, v1, 6, v0
	v_lshl_add_u32 v136, v14, 1, v0
	v_lshlrev_b32_e32 v0, 15, v8
	v_and_b32_e32 v0, 0xffff0000, v0
	s_waitcnt vmcnt(6)
	s_cmpk_lt_u32 s0, 0x100
	v_lshl_add_u32 v0, v9, 12, v0
	v_and_b32_e32 v1, 1, v8
	s_cselect_b64 s[18:19], -1, 0
	v_lshl_or_b32 v0, v1, 6, v0
	s_add_i32 s39, 0, 0x10000
	s_add_i32 s40, 0, 0x14000
	s_sext_i32_i8 s43, s5
	s_ashr_i32 s37, s88, 31
	s_mov_b32 s38, s88
	v_mov_b32_e32 v137, v133
	v_lshl_add_u32 v138, v11, 1, v0
	v_mov_b32_e32 v139, v133
	v_mov_b64_e32 v[140:141], 0x1c0
	v_mov_b64_e32 v[142:143], 0x1bf
	v_add_u32_e32 v147, s39, v146
	v_add_u32_e32 v148, s40, v146
	v_add_u32_e32 v149, 0, v2
	s_movk_i32 s41, 0xe00
	s_barrier
	s_branch .LBB0_298

; #define PG8_STAGE(bufoff, gbase, voff) do { _Pragma("unroll") for (int _i = 0; _i < 2; ++_i) \
;         __builtin_amdgcn_global_load_lds((const unsigned*)((const char*)(gbase) + (voff)[_i]), (PG8_LAS unsigned*)(lds + (bufoff) + ldsw + _i * 8192), 16, 0, 0); } while (0)
; #define PG8_LDA(dst, b, h) do { _Pragma("unroll") for (int m = 0; m < 4; ++m) _Pragma("unroll") for (int k = 0; k < 2; ++k) dst[m][k] = *(const PG8_LAS bf16x8*)(lds + PG8_SA(b, h) + aoff + m * 2048 + k * 1024); } while (0)
; #define PG8_LDB(dst, b, h) do { _Pragma("unroll") for (int n = 0; n < 2; ++n) _Pragma("unroll") for (int k = 0; k < 2; ++k) dst[n][k] = *(const PG8_LAS bf16x8*)(lds + PG8_SB(b, h) + boff + n * 2048 + k * 1024); } while (0)
; #define PG8_MMA(ai, bj, At, Bt) do { __builtin_amdgcn_s_setprio(1); _Pragma("unroll") for (int m = 0; m < 4; ++m) _Pragma("unroll") for (int n = 0; n < 2; ++n) _Pragma("unroll") for (int k = 0; k < 2; ++k) \
;         acc[ai][bj][m][n] = __builtin_amdgcn_mfma_f32_16x16x32_bf16(Bt[n][k], At[m][k], acc[ai][bj][m][n], 0, 0, 0); __builtin_amdgcn_s_setprio(0); } while (0)
; #define PG8_WAIT_V(n) asm volatile("s_waitcnt vmcnt(" #n ")" ::: "memory")
; #define PG8_WAIT_L(n) asm volatile("s_waitcnt lgkmcnt(" #n ")" ::: "memory")
; #define PG8_BAR __builtin_amdgcn_s_barrier()
; #define PG8_SCHED __builtin_amdgcn_sched_barrier(0)
; template <class Epi, class Sched, bool ALIGN_EPI = false, bool SP2 = false>
; __device__ __forceinline__ void gemm_phase(PG8_LAS unsigned char* lds, const Gemm g, const Sched& S, const Epi& E) {
;     ...
;             PG8_LDB(B0, 0, 0); PG8_LDB(B1, 0, 1); PG8_SCHED; PG8_LDA(At, 0, 0); PG8_STAGE(PG8_SA(1, 1), a1 + hstepA, voffA);
;             PG8_WAIT_V(8); PG8_WAIT_L(0); PG8_BAR; PG8_MMA(0, 0, At, B0); PG8_MMA(0, 1, At, B1); PG8_BAR; PG8_SCHED;
;             PG8_LDA(At, 0, 1); PG8_STAGE(PG8_SB(0, 0), b2, voffB); PG8_STAGE(PG8_SB(0, 1), b2 + hstepB, voffB); PG8_STAGE(PG8_SA(0, 0), a2, voffA);
;             PG8_WAIT_V(8); PG8_WAIT_L(0); PG8_BAR; PG8_MMA(1, 0, At, B0); PG8_MMA(1, 1, At, B1); PG8_BAR; PG8_SCHED;
.LBB0_303:
	ds_read_b128 v[150:153], v147
	ds_read_b128 v[154:157], v147 offset:1024
	ds_read_b128 v[158:161], v147 offset:2048
	ds_read_b128 v[162:165], v147 offset:3072
	ds_read_b128 v[166:169], v148
	ds_read_b128 v[170:173], v148 offset:1024
	ds_read_b128 v[174:177], v148 offset:2048
	ds_read_b128 v[178:181], v148 offset:3072
	s_add_u32 s28, s0, 0xfff80080
	s_addc_u32 s29, s1, -1
	s_cmp_eq_u32 s53, 2
	s_cselect_b32 s31, s23, s29
	s_cselect_b32 s30, s50, s28
	s_cselect_b32 s29, s25, s52
	s_cselect_b32 s28, s24, s51
	s_add_i32 m0, s8, 0xc000
	ds_read_b128 v[182:185], v149
	ds_read_b128 v[186:189], v149 offset:1024
	ds_read_b128 v[196:199], v149 offset:2048
	ds_read_b128 v[200:203], v149 offset:3072
	ds_read_b128 v[204:207], v149 offset:4096
	ds_read_b128 v[208:211], v149 offset:5120
	ds_read_b128 v[212:215], v149 offset:6144
	ds_read_b128 v[216:219], v149 offset:7168
	global_load_lds_dwordx4 v136, s[0:1]
	s_add_i32 m0, s8, 0xe000
	s_nop 0
	global_load_lds_dwordx4 v138, s[0:1]
	s_waitcnt vmcnt(8)
	s_waitcnt lgkmcnt(0)
	s_barrier
	s_setprio 1
	s_waitcnt lgkmcnt(0)
	v_mfma_f32_16x16x32_bf16 v[124:127], v[150:153], v[182:185], v[124:127]
	v_mfma_f32_16x16x32_bf16 v[120:123], v[158:161], v[182:185], v[120:123]
	v_mfma_f32_16x16x32_bf16 v[116:119], v[150:153], v[196:199], v[116:119]
	v_mfma_f32_16x16x32_bf16 v[112:115], v[158:161], v[196:199], v[112:115]
	v_mfma_f32_16x16x32_bf16 v[100:103], v[150:153], v[204:207], v[100:103]
	v_mfma_f32_16x16x32_bf16 v[96:99], v[158:161], v[204:207], v[96:99]
	v_mfma_f32_16x16x32_bf16 v[84:87], v[150:153], v[212:215], v[84:87]
	v_mfma_f32_16x16x32_bf16 v[80:83], v[158:161], v[212:215], v[80:83]
	v_mfma_f32_16x16x32_bf16 v[124:127], v[154:157], v[186:189], v[124:127]
	v_mfma_f32_16x16x32_bf16 v[120:123], v[162:165], v[186:189], v[120:123]
	v_mfma_f32_16x16x32_bf16 v[116:119], v[154:157], v[200:203], v[116:119]
	v_mfma_f32_16x16x32_bf16 v[112:115], v[162:165], v[200:203], v[112:115]
	v_mfma_f32_16x16x32_bf16 v[100:103], v[154:157], v[208:211], v[100:103]
	v_mfma_f32_16x16x32_bf16 v[96:99], v[162:165], v[208:211], v[96:99]
	v_mfma_f32_16x16x32_bf16 v[84:87], v[154:157], v[216:219], v[84:87]
	v_mfma_f32_16x16x32_bf16 v[80:83], v[162:165], v[216:219], v[80:83]
	s_setprio 0
	s_setprio 1
	v_mfma_f32_16x16x32_bf16 v[108:111], v[166:169], v[182:185], v[108:111]
	v_mfma_f32_16x16x32_bf16 v[104:107], v[174:177], v[182:185], v[104:107]
	v_mfma_f32_16x16x32_bf16 v[92:95], v[166:169], v[196:199], v[92:95]
	v_mfma_f32_16x16x32_bf16 v[88:91], v[174:177], v[196:199], v[88:91]
	v_mfma_f32_16x16x32_bf16 v[76:79], v[166:169], v[204:207], v[76:79]
	v_mfma_f32_16x16x32_bf16 v[72:75], v[174:177], v[204:207], v[72:75]
	v_mfma_f32_16x16x32_bf16 v[68:71], v[166:169], v[212:215], v[68:71]
	v_mfma_f32_16x16x32_bf16 v[64:67], v[174:177], v[212:215], v[64:67]
	v_mfma_f32_16x16x32_bf16 v[108:111], v[170:173], v[186:189], v[108:111]
	v_mfma_f32_16x16x32_bf16 v[104:107], v[178:181], v[186:189], v[104:107]
	v_mfma_f32_16x16x32_bf16 v[92:95], v[170:173], v[200:203], v[92:95]
	v_mfma_f32_16x16x32_bf16 v[88:91], v[178:181], v[200:203], v[88:91]
	v_mfma_f32_16x16x32_bf16 v[76:79], v[170:173], v[208:211], v[76:79]
	v_mfma_f32_16x16x32_bf16 v[72:75], v[178:181], v[208:211], v[72:75]
	v_mfma_f32_16x16x32_bf16 v[68:71], v[170:173], v[216:219], v[68:71]
	v_mfma_f32_16x16x32_bf16 v[64:67], v[178:181], v[216:219], v[64:67]
	s_setprio 0
	s_barrier
	s_add_i32 s44, s39, s2
	v_lshl_add_u64 v[190:191], s[28:29], 0, v[132:133]
	s_mov_b32 m0, s44
	ds_read_b128 v[182:185], v149 offset:16384
	ds_read_b128 v[186:189], v149 offset:17408
	ds_read_b128 v[196:199], v149 offset:18432
	ds_read_b128 v[200:203], v149 offset:19456
	ds_read_b128 v[204:207], v149 offset:20480
	ds_read_b128 v[208:211], v149 offset:21504
	ds_read_b128 v[212:215], v149 offset:22528
	ds_read_b128 v[216:219], v149 offset:23552
	global_load_lds_dwordx4 v[190:191], off
	s_add_i32 m0, s44, 0x2000
	s_add_u32 s44, s28, 0x18000
	v_lshl_add_u64 v[192:193], s[28:29], 0, v[128:129]
	s_addc_u32 s45, s29, 0
	s_add_i32 s48, s40, s2
	global_load_lds_dwordx4 v[192:193], off
	s_mov_b32 m0, s48
	v_lshl_add_u64 v[220:221], s[30:31], 0, v[130:131]
	global_load_lds_dwordx4 v132, s[44:45]
	s_add_i32 m0, s48, 0x2000
	s_nop 0
	global_load_lds_dwordx4 v128, s[44:45]
	v_lshl_add_u64 v[194:195], s[30:31], 0, v[134:135]
	s_mov_b32 m0, s8
	s_nop 0
	global_load_lds_dwordx4 v[194:195], off
	s_mov_b32 m0, s9
	s_nop 0
	global_load_lds_dwordx4 v[220:221], off
	s_waitcnt vmcnt(8)
	s_waitcnt lgkmcnt(0)
	s_barrier
; #define PG8_STAGE(bufoff, gbase, voff) do { _Pragma("unroll") for (int _i = 0; _i < 2; ++_i) \
;         __builtin_amdgcn_global_load_lds((const unsigned*)((const char*)(gbase) + (voff)[_i]), (PG8_LAS unsigned*)(lds + (bufoff) + ldsw + _i * 8192), 16, 0, 0); } while (0)
; #define PG8_LDA(dst, b, h) do { _Pragma("unroll") for (int m = 0; m < 4; ++m) _Pragma("unroll") for (int k = 0; k < 2; ++k) dst[m][k] = *(const PG8_LAS bf16x8*)(lds + PG8_SA(b, h) + aoff + m * 2048 + k * 1024); } while (0)
; #define PG8_LDB(dst, b, h) do { _Pragma("unroll") for (int n = 0; n < 2; ++n) _Pragma("unroll") for (int k = 0; k < 2; ++k) dst[n][k] = *(const PG8_LAS bf16x8*)(lds + PG8_SB(b, h) + boff + n * 2048 + k * 1024); } while (0)
; #define PG8_MMA(ai, bj, At, Bt) do { __builtin_amdgcn_s_setprio(1); _Pragma("unroll") for (int m = 0; m < 4; ++m) _Pragma("unroll") for (int n = 0; n < 2; ++n) _Pragma("unroll") for (int k = 0; k < 2; ++k) \
;         acc[ai][bj][m][n] = __builtin_amdgcn_mfma_f32_16x16x32_bf16(Bt[n][k], At[m][k], acc[ai][bj][m][n], 0, 0, 0); __builtin_amdgcn_s_setprio(0); } while (0)
; #define PG8_WAIT_V(n) asm volatile("s_waitcnt vmcnt(" #n ")" ::: "memory")
; #define PG8_WAIT_L(n) asm volatile("s_waitcnt lgkmcnt(" #n ")" ::: "memory")
; #define PG8_BAR __builtin_amdgcn_s_barrier()
; #define PG8_SCHED __builtin_amdgcn_sched_barrier(0)
; template <class Epi, class Sched, bool ALIGN_EPI = false, bool SP2 = false>
; __device__ __forceinline__ void gemm_phase(PG8_LAS unsigned char* lds, const Gemm g, const Sched& S, const Epi& E) {
;     ...
;             PG8_WAIT_V(8); PG8_WAIT_L(0); PG8_BAR; PG8_MMA(1, 0, At, B0); PG8_MMA(1, 1, At, B1); PG8_BAR; PG8_SCHED;
;             PG8_LDB(B0, 1, 0); PG8_LDB(B1, 1, 1); PG8_SCHED; PG8_LDA(At, 1, 0); PG8_STAGE(PG8_SA(0, 1), a2 + hstepA, voffA);
;             PG8_WAIT_V(8); PG8_WAIT_L(0); PG8_BAR; PG8_MMA(0, 0, At, B0); PG8_MMA(0, 1, At, B1); PG8_BAR; PG8_SCHED;
;             PG8_LDA(At, 1, 1); PG8_STAGE(PG8_SB(1, 0), b3, voffB); PG8_STAGE(PG8_SB(1, 1), b3 + hstepB, voffB); PG8_STAGE(PG8_SA(1, 0), a3, voffA);
	s_setprio 1
	s_waitcnt lgkmcnt(0)
	v_mfma_f32_16x16x32_bf16 v[60:63], v[150:153], v[182:185], v[60:63]
	v_mfma_f32_16x16x32_bf16 v[56:59], v[158:161], v[182:185], v[56:59]
	v_mfma_f32_16x16x32_bf16 v[52:55], v[150:153], v[196:199], v[52:55]
	v_mfma_f32_16x16x32_bf16 v[48:51], v[158:161], v[196:199], v[48:51]
	v_mfma_f32_16x16x32_bf16 v[36:39], v[150:153], v[204:207], v[36:39]
	v_mfma_f32_16x16x32_bf16 v[32:35], v[158:161], v[204:207], v[32:35]
	v_mfma_f32_16x16x32_bf16 v[20:23], v[150:153], v[212:215], v[20:23]
	v_mfma_f32_16x16x32_bf16 v[16:19], v[158:161], v[212:215], v[16:19]
	v_mfma_f32_16x16x32_bf16 v[60:63], v[154:157], v[186:189], v[60:63]
	v_mfma_f32_16x16x32_bf16 v[56:59], v[162:165], v[186:189], v[56:59]
	v_mfma_f32_16x16x32_bf16 v[52:55], v[154:157], v[200:203], v[52:55]
	v_mfma_f32_16x16x32_bf16 v[48:51], v[162:165], v[200:203], v[48:51]
	v_mfma_f32_16x16x32_bf16 v[36:39], v[154:157], v[208:211], v[36:39]
	v_mfma_f32_16x16x32_bf16 v[32:35], v[162:165], v[208:211], v[32:35]
	v_mfma_f32_16x16x32_bf16 v[20:23], v[154:157], v[216:219], v[20:23]
	v_mfma_f32_16x16x32_bf16 v[16:19], v[162:165], v[216:219], v[16:19]
	s_setprio 0
	s_setprio 1
	v_mfma_f32_16x16x32_bf16 v[44:47], v[166:169], v[182:185], v[44:47]
	v_mfma_f32_16x16x32_bf16 v[40:43], v[174:177], v[182:185], v[40:43]
	v_mfma_f32_16x16x32_bf16 v[28:31], v[166:169], v[196:199], v[28:31]
	v_mfma_f32_16x16x32_bf16 v[24:27], v[174:177], v[196:199], v[24:27]
	v_mfma_f32_16x16x32_bf16 v[12:15], v[166:169], v[204:207], v[12:15]
	v_mfma_f32_16x16x32_bf16 v[8:11], v[174:177], v[204:207], v[8:11]
	v_mfma_f32_16x16x32_bf16 v[4:7], v[166:169], v[212:215], v[4:7]
	v_mfma_f32_16x16x32_bf16 v[0:3], v[174:177], v[212:215], v[0:3]
	v_mfma_f32_16x16x32_bf16 v[44:47], v[170:173], v[186:189], v[44:47]
	v_mfma_f32_16x16x32_bf16 v[40:43], v[178:181], v[186:189], v[40:43]
	v_mfma_f32_16x16x32_bf16 v[28:31], v[170:173], v[200:203], v[28:31]
	v_mfma_f32_16x16x32_bf16 v[24:27], v[178:181], v[200:203], v[24:27]
	v_mfma_f32_16x16x32_bf16 v[12:15], v[170:173], v[208:211], v[12:15]
	v_mfma_f32_16x16x32_bf16 v[8:11], v[178:181], v[208:211], v[8:11]
	v_mfma_f32_16x16x32_bf16 v[4:7], v[170:173], v[216:219], v[4:7]
	v_mfma_f32_16x16x32_bf16 v[0:3], v[178:181], v[216:219], v[0:3]
	s_setprio 0
	s_barrier
	s_add_i32 s44, 0, 0x18000
	s_add_i32 s45, 0, 0x1c000
	v_add_u32_e32 v162, s44, v146
	v_add_u32_e32 v178, s45, v146
	ds_read_b128 v[150:153], v162
	ds_read_b128 v[154:157], v162 offset:1024
	ds_read_b128 v[158:161], v162 offset:2048
	ds_read_b128 v[162:165], v162 offset:3072
	ds_read_b128 v[166:169], v178
	ds_read_b128 v[170:173], v178 offset:1024
	ds_read_b128 v[174:177], v178 offset:2048
	ds_read_b128 v[178:181], v178 offset:3072
	s_add_u32 s30, s30, 0x80000
	s_addc_u32 s31, s31, 0
	s_mov_b32 m0, s10
	ds_read_b128 v[182:185], v149 offset:32768
	ds_read_b128 v[186:189], v149 offset:33792
	ds_read_b128 v[196:199], v149 offset:34816
	ds_read_b128 v[200:203], v149 offset:35840
	ds_read_b128 v[204:207], v149 offset:36864
	ds_read_b128 v[208:211], v149 offset:37888
	ds_read_b128 v[212:215], v149 offset:38912
	ds_read_b128 v[216:219], v149 offset:39936
	global_load_lds_dwordx4 v134, s[30:31]
	s_mov_b32 m0, s11
	s_nop 0
	global_load_lds_dwordx4 v130, s[30:31]
	s_waitcnt vmcnt(8)
	s_waitcnt lgkmcnt(0)
	s_barrier
	s_setprio 1
	s_waitcnt lgkmcnt(0)
	v_mfma_f32_16x16x32_bf16 v[124:127], v[150:153], v[182:185], v[124:127]
	v_mfma_f32_16x16x32_bf16 v[120:123], v[158:161], v[182:185], v[120:123]
	v_mfma_f32_16x16x32_bf16 v[116:119], v[150:153], v[196:199], v[116:119]
	v_mfma_f32_16x16x32_bf16 v[112:115], v[158:161], v[196:199], v[112:115]
	v_mfma_f32_16x16x32_bf16 v[100:103], v[150:153], v[204:207], v[100:103]
	v_mfma_f32_16x16x32_bf16 v[96:99], v[158:161], v[204:207], v[96:99]
	v_mfma_f32_16x16x32_bf16 v[84:87], v[150:153], v[212:215], v[84:87]
	v_mfma_f32_16x16x32_bf16 v[80:83], v[158:161], v[212:215], v[80:83]
	v_mfma_f32_16x16x32_bf16 v[124:127], v[154:157], v[186:189], v[124:127]
	v_mfma_f32_16x16x32_bf16 v[120:123], v[162:165], v[186:189], v[120:123]
	v_mfma_f32_16x16x32_bf16 v[116:119], v[154:157], v[200:203], v[116:119]
	v_mfma_f32_16x16x32_bf16 v[112:115], v[162:165], v[200:203], v[112:115]
	v_mfma_f32_16x16x32_bf16 v[100:103], v[154:157], v[208:211], v[100:103]
	v_mfma_f32_16x16x32_bf16 v[96:99], v[162:165], v[208:211], v[96:99]
	v_mfma_f32_16x16x32_bf16 v[84:87], v[154:157], v[216:219], v[84:87]
	v_mfma_f32_16x16x32_bf16 v[80:83], v[162:165], v[216:219], v[80:83]
	s_setprio 0
	s_setprio 1
	v_mfma_f32_16x16x32_bf16 v[108:111], v[166:169], v[182:185], v[108:111]
	v_mfma_f32_16x16x32_bf16 v[104:107], v[174:177], v[182:185], v[104:107]
	v_mfma_f32_16x16x32_bf16 v[92:95], v[166:169], v[196:199], v[92:95]
	v_mfma_f32_16x16x32_bf16 v[88:91], v[174:177], v[196:199], v[88:91]
	v_mfma_f32_16x16x32_bf16 v[76:79], v[166:169], v[204:207], v[76:79]
	v_mfma_f32_16x16x32_bf16 v[72:75], v[174:177], v[204:207], v[72:75]
	v_mfma_f32_16x16x32_bf16 v[68:71], v[166:169], v[212:215], v[68:71]
	v_mfma_f32_16x16x32_bf16 v[64:67], v[174:177], v[212:215], v[64:67]
	v_mfma_f32_16x16x32_bf16 v[108:111], v[170:173], v[186:189], v[108:111]
	v_mfma_f32_16x16x32_bf16 v[104:107], v[178:181], v[186:189], v[104:107]
	v_mfma_f32_16x16x32_bf16 v[92:95], v[170:173], v[200:203], v[92:95]
	v_mfma_f32_16x16x32_bf16 v[88:91], v[178:181], v[200:203], v[88:91]
	v_mfma_f32_16x16x32_bf16 v[76:79], v[170:173], v[208:211], v[76:79]
	v_mfma_f32_16x16x32_bf16 v[72:75], v[178:181], v[208:211], v[72:75]
	v_mfma_f32_16x16x32_bf16 v[68:71], v[170:173], v[216:219], v[68:71]
	v_mfma_f32_16x16x32_bf16 v[64:67], v[178:181], v[216:219], v[64:67]
	s_setprio 0
	s_barrier
; #define PG8_STAGE(bufoff, gbase, voff) do { _Pragma("unroll") for (int _i = 0; _i < 2; ++_i) \
;         __builtin_amdgcn_global_load_lds((const unsigned*)((const char*)(gbase) + (voff)[_i]), (PG8_LAS unsigned*)(lds + (bufoff) + ldsw + _i * 8192), 16, 0, 0); } while (0)
; #define PG8_LDA(dst, b, h) do { _Pragma("unroll") for (int m = 0; m < 4; ++m) _Pragma("unroll") for (int k = 0; k < 2; ++k) dst[m][k] = *(const PG8_LAS bf16x8*)(lds + PG8_SA(b, h) + aoff + m * 2048 + k * 1024); } while (0)
; #define PG8_MMA(ai, bj, At, Bt) do { __builtin_amdgcn_s_setprio(1); _Pragma("unroll") for (int m = 0; m < 4; ++m) _Pragma("unroll") for (int n = 0; n < 2; ++n) _Pragma("unroll") for (int k = 0; k < 2; ++k) \
;         acc[ai][bj][m][n] = __builtin_amdgcn_mfma_f32_16x16x32_bf16(Bt[n][k], At[m][k], acc[ai][bj][m][n], 0, 0, 0); __builtin_amdgcn_s_setprio(0); } while (0)
; #define PG8_WAIT_V(n) asm volatile("s_waitcnt vmcnt(" #n ")" ::: "memory")
; #define PG8_WAIT_L(n) asm volatile("s_waitcnt lgkmcnt(" #n ")" ::: "memory")
; #define PG8_BAR __builtin_amdgcn_s_barrier()
; #define PG8_SCHED __builtin_amdgcn_sched_barrier(0)
; template <class Epi, class Sched, bool ALIGN_EPI = false, bool SP2 = false>
; __device__ __forceinline__ void gemm_phase(PG8_LAS unsigned char* lds, const Gemm g, const Sched& S, const Epi& E) {
;     ...
;             PG8_WAIT_V(8); PG8_WAIT_L(0); PG8_BAR; PG8_MMA(0, 0, At, B0); PG8_MMA(0, 1, At, B1); PG8_BAR; PG8_SCHED;
;             PG8_LDA(At, 1, 1); PG8_STAGE(PG8_SB(1, 0), b3, voffB); PG8_STAGE(PG8_SB(1, 1), b3 + hstepB, voffB); PG8_STAGE(PG8_SA(1, 0), a3, voffA);
;             PG8_WAIT_V(8); PG8_WAIT_L(0); PG8_BAR; PG8_MMA(1, 0, At, B0); PG8_MMA(1, 1, At, B1); PG8_BAR; PG8_SCHED;
	s_add_i32 s30, s44, s2
	v_lshl_add_u64 v[190:191], v[190:191], 0, s[16:17]
	s_mov_b32 m0, s30
	ds_read_b128 v[182:185], v149 offset:49152
	ds_read_b128 v[186:189], v149 offset:50176
	ds_read_b128 v[196:199], v149 offset:51200
	ds_read_b128 v[200:203], v149 offset:52224
	ds_read_b128 v[204:207], v149 offset:53248
	ds_read_b128 v[208:211], v149 offset:54272
	ds_read_b128 v[212:215], v149 offset:55296
	ds_read_b128 v[216:219], v149 offset:56320
	global_load_lds_dwordx4 v[190:191], off
	s_add_i32 m0, s30, 0x2000
	s_add_u32 s28, s28, 0x18080
	v_lshl_add_u64 v[190:191], v[192:193], 0, s[16:17]
	s_addc_u32 s29, s29, 0
	s_add_i32 s30, s45, s2
	global_load_lds_dwordx4 v[190:191], off
	s_mov_b32 m0, s30
	s_nop 0
	global_load_lds_dwordx4 v132, s[28:29]
	s_add_i32 m0, s30, 0x2000
	s_nop 0
	global_load_lds_dwordx4 v128, s[28:29]
	v_lshl_add_u64 v[190:191], v[194:195], 0, s[16:17]
	s_mov_b32 m0, s35
	s_nop 0
	global_load_lds_dwordx4 v[190:191], off
	v_lshl_add_u64 v[190:191], v[220:221], 0, s[16:17]
	s_mov_b32 m0, s36
	s_nop 0
	global_load_lds_dwordx4 v[190:191], off
	s_waitcnt vmcnt(8)
	s_waitcnt lgkmcnt(0)
	s_barrier
	s_setprio 1
	s_waitcnt lgkmcnt(0)
	v_mfma_f32_16x16x32_bf16 v[60:63], v[150:153], v[182:185], v[60:63]
	v_mfma_f32_16x16x32_bf16 v[56:59], v[158:161], v[182:185], v[56:59]
	v_mfma_f32_16x16x32_bf16 v[52:55], v[150:153], v[196:199], v[52:55]
	v_mfma_f32_16x16x32_bf16 v[48:51], v[158:161], v[196:199], v[48:51]
	v_mfma_f32_16x16x32_bf16 v[36:39], v[150:153], v[204:207], v[36:39]
	v_mfma_f32_16x16x32_bf16 v[32:35], v[158:161], v[204:207], v[32:35]
	v_mfma_f32_16x16x32_bf16 v[20:23], v[150:153], v[212:215], v[20:23]
	v_mfma_f32_16x16x32_bf16 v[16:19], v[158:161], v[212:215], v[16:19]
	v_mfma_f32_16x16x32_bf16 v[60:63], v[154:157], v[186:189], v[60:63]
	v_mfma_f32_16x16x32_bf16 v[56:59], v[162:165], v[186:189], v[56:59]
	v_mfma_f32_16x16x32_bf16 v[52:55], v[154:157], v[200:203], v[52:55]
	v_mfma_f32_16x16x32_bf16 v[48:51], v[162:165], v[200:203], v[48:51]
	v_mfma_f32_16x16x32_bf16 v[36:39], v[154:157], v[208:211], v[36:39]
	v_mfma_f32_16x16x32_bf16 v[32:35], v[162:165], v[208:211], v[32:35]
	v_mfma_f32_16x16x32_bf16 v[20:23], v[154:157], v[216:219], v[20:23]
	v_mfma_f32_16x16x32_bf16 v[16:19], v[162:165], v[216:219], v[16:19]
	s_setprio 0
	s_setprio 1
	v_mfma_f32_16x16x32_bf16 v[44:47], v[166:169], v[182:185], v[44:47]
	v_mfma_f32_16x16x32_bf16 v[40:43], v[174:177], v[182:185], v[40:43]
	v_mfma_f32_16x16x32_bf16 v[28:31], v[166:169], v[196:199], v[28:31]
	v_mfma_f32_16x16x32_bf16 v[24:27], v[174:177], v[196:199], v[24:27]
	v_mfma_f32_16x16x32_bf16 v[12:15], v[166:169], v[204:207], v[12:15]
	v_mfma_f32_16x16x32_bf16 v[8:11], v[174:177], v[204:207], v[8:11]
	v_mfma_f32_16x16x32_bf16 v[4:7], v[166:169], v[212:215], v[4:7]
	v_mfma_f32_16x16x32_bf16 v[0:3], v[174:177], v[212:215], v[0:3]
	v_mfma_f32_16x16x32_bf16 v[44:47], v[170:173], v[186:189], v[44:47]
	v_mfma_f32_16x16x32_bf16 v[40:43], v[178:181], v[186:189], v[40:43]
	v_mfma_f32_16x16x32_bf16 v[28:31], v[170:173], v[200:203], v[28:31]
	v_mfma_f32_16x16x32_bf16 v[24:27], v[178:181], v[200:203], v[24:27]
	v_mfma_f32_16x16x32_bf16 v[12:15], v[170:173], v[208:211], v[12:15]
	v_mfma_f32_16x16x32_bf16 v[8:11], v[178:181], v[208:211], v[8:11]
	v_mfma_f32_16x16x32_bf16 v[4:7], v[170:173], v[216:219], v[4:7]
	v_mfma_f32_16x16x32_bf16 v[0:3], v[178:181], v[216:219], v[0:3]
	s_setprio 0
	s_barrier
	s_add_i32 s53, s53, 2
	s_add_u32 s0, s0, 0x100
	s_addc_u32 s1, s1, 0
	s_add_u32 s51, s51, 0x100
	s_addc_u32 s52, s52, 0
	s_cmp_gt_u32 s53, 3
	s_cbranch_scc0 .LBB0_303
	s_and_b64 vcc, exec, s[18:19]
	s_cbranch_vccz .LBB0_306
	s_barrier

; #define PG8_STAGE(bufoff, gbase, voff) do { _Pragma("unroll") for (int _i = 0; _i < 2; ++_i) \
;         __builtin_amdgcn_global_load_lds((const unsigned*)((const char*)(gbase) + (voff)[_i]), (PG8_LAS unsigned*)(lds + (bufoff) + ldsw + _i * 8192), 16, 0, 0); } while (0)
; #define PG8_WAIT_V(n) asm volatile("s_waitcnt vmcnt(" #n ")" ::: "memory")
; #define PG8_BAR __builtin_amdgcn_s_barrier()
; template <class Epi, class Sched, bool ALIGN_EPI = false, bool SP2 = false>
; __device__ __forceinline__ void gemm_phase(PG8_LAS unsigned char* lds, const Gemm g, const Sched& S, const Epi& E) {
;     ...
;         PG8_STAGE(PG8_SB(0, 0), cB, voffB); PG8_STAGE(PG8_SB(0, 1), cB + hstepB, voffB); PG8_STAGE(PG8_SA(0, 0), cA, voffA); PG8_STAGE(PG8_SA(0, 1), cA + hstepA, voffA);
;         if (wr == 1) PG8_BAR;
;         PG8_WAIT_V(2); PG8_BAR;
;         PG8_STAGE(PG8_SB(1, 0), cB + kstep, voffB); PG8_STAGE(PG8_SA(1, 0), cA + kstep, voffA); PG8_STAGE(PG8_SB(1, 1), cB + hstepB + kstep, voffB);
;         PG8_WAIT_V(6); PG8_BAR;
.LBB0_622:
	s_lshl_b32 s6, s6, 5
	s_and_b32 s35, s6, 0x60
	s_mov_b64 s[6:7], 0x80
	s_add_i32 m0, s9, 0x18000
	v_lshl_add_u64 v[6:7], v[6:7], 0, s[6:7]
	s_lshl_b32 s34, s5, 6
	s_lshl_b32 s5, s5, 13
	s_lshl_b32 s14, s35, 7
	s_waitcnt vmcnt(2)
	s_barrier
	global_load_lds_dwordx4 v[6:7], off
	v_lshl_add_u64 v[4:5], v[4:5], 0, s[6:7]
	s_add_i32 m0, s9, 0x1a000
	s_add_i32 s36, s9, 0x8000
	s_add_i32 s37, s9, 0xa000
	global_load_lds_dwordx4 v[4:5], off
	v_lshl_add_u64 v[0:1], v[0:1], 0, s[6:7]
	s_mov_b32 m0, s36
	s_add_u32 s12, s28, 0x40080
	global_load_lds_dwordx4 v[0:1], off
	v_lshl_add_u64 v[0:1], v[2:3], 0, s[6:7]
	s_mov_b32 m0, s37
	s_addc_u32 s13, s29, 0
	global_load_lds_dwordx4 v[0:1], off
	s_add_i32 m0, s9, 0x1c000
	s_nop 0
	global_load_lds_dwordx4 v130, s[12:13]
	v_lshl_add_u64 v[0:1], s[12:13], 0, v[134:135]
	s_add_i32 m0, s9, 0x1e000
	v_bfe_u32 v149, v8, 4, 2
	global_load_lds_dwordx4 v[0:1], off
	v_and_b32_e32 v148, 15, v8
	v_lshlrev_b32_e32 v0, 4, v149
	v_lshlrev_b32_e32 v1, 2, v8
	v_lshl_or_b32 v0, v148, 6, v0
	v_and_b32_e32 v1, 32, v1
	v_bitop3_b32 v2, v0, s5, v1 bitop3:0xde
	v_bitop3_b32 v150, v0, s14, v1 bitop3:0xde
	v_lshlrev_b32_e32 v0, 14, v9
	v_and_b32_e32 v0, 0xffff8000, v0
	v_lshl_add_u32 v0, v10, 11, v0
	v_and_b32_e32 v1, 1, v9
	v_lshl_or_b32 v0, v1, 6, v0
	v_lshl_add_u32 v136, v11, 1, v0
	v_lshlrev_b32_e32 v0, 14, v12
	v_and_b32_e32 v0, 0xffff8000, v0
	v_lshl_add_u32 v0, v13, 11, v0
	v_and_b32_e32 v1, 1, v12
	s_waitcnt vmcnt(6)
	s_cmpk_lt_u32 s4, 0x100
	v_lshl_or_b32 v0, v1, 6, v0
	s_cselect_b64 s[12:13], -1, 0
	v_lshl_add_u32 v138, v14, 1, v0
	s_add_i32 s41, 0, 0x10000
	s_add_i32 s42, 0, 0x14000
	v_mbcnt_lo_u32_b32 v0, -1, 0
	s_ashr_i32 s38, s88, 31
	s_mov_b32 s39, s88
	s_ashr_i32 s40, s67, 31
	v_mov_b32_e32 v137, v131
	v_mov_b32_e32 v139, v131
	v_mov_b64_e32 v[140:141], 0x100
	v_mov_b64_e32 v[142:143], 0xff
	v_add_u32_e32 v151, s41, v150
	v_add_u32_e32 v152, s42, v150
	v_add_u32_e32 v153, 0, v2
	v_mbcnt_hi_u32_b32 v154, -1, v0
	s_barrier
	s_branch .LBB0_625

; #define PG8_STAGE(bufoff, gbase, voff) do { _Pragma("unroll") for (int _i = 0; _i < 2; ++_i) \
;         __builtin_amdgcn_global_load_lds((const unsigned*)((const char*)(gbase) + (voff)[_i]), (PG8_LAS unsigned*)(lds + (bufoff) + ldsw + _i * 8192), 16, 0, 0); } while (0)
; #define PG8_LDA(dst, b, h) do { _Pragma("unroll") for (int m = 0; m < 4; ++m) _Pragma("unroll") for (int k = 0; k < 2; ++k) dst[m][k] = *(const PG8_LAS bf16x8*)(lds + PG8_SA(b, h) + aoff + m * 2048 + k * 1024); } while (0)
; #define PG8_LDB(dst, b, h) do { _Pragma("unroll") for (int n = 0; n < 2; ++n) _Pragma("unroll") for (int k = 0; k < 2; ++k) dst[n][k] = *(const PG8_LAS bf16x8*)(lds + PG8_SB(b, h) + boff + n * 2048 + k * 1024); } while (0)
; #define PG8_MMA(ai, bj, At, Bt) do { __builtin_amdgcn_s_setprio(1); _Pragma("unroll") for (int m = 0; m < 4; ++m) _Pragma("unroll") for (int n = 0; n < 2; ++n) _Pragma("unroll") for (int k = 0; k < 2; ++k) \
;         acc[ai][bj][m][n] = __builtin_amdgcn_mfma_f32_16x16x32_bf16(Bt[n][k], At[m][k], acc[ai][bj][m][n], 0, 0, 0); __builtin_amdgcn_s_setprio(0); } while (0)
; #define PG8_WAIT_V(n) asm volatile("s_waitcnt vmcnt(" #n ")" ::: "memory")
; #define PG8_WAIT_L(n) asm volatile("s_waitcnt lgkmcnt(" #n ")" ::: "memory")
; #define PG8_BAR __builtin_amdgcn_s_barrier()
; #define PG8_SCHED __builtin_amdgcn_sched_barrier(0)
; template <class Epi, class Sched, bool ALIGN_EPI = false, bool SP2 = false>
; __device__ __forceinline__ void gemm_phase(PG8_LAS unsigned char* lds, const Gemm g, const Sched& S, const Epi& E) {
;     ...
;             PG8_LDB(B0, 0, 0); PG8_LDB(B1, 0, 1); PG8_SCHED; PG8_LDA(At, 0, 0); PG8_STAGE(PG8_SA(1, 1), a1 + hstepA, voffA);
;             PG8_WAIT_V(8); PG8_WAIT_L(0); PG8_BAR; PG8_MMA(0, 0, At, B0); PG8_MMA(0, 1, At, B1); PG8_BAR; PG8_SCHED;
;             PG8_LDA(At, 0, 1); PG8_STAGE(PG8_SB(0, 0), b2, voffB); PG8_STAGE(PG8_SB(0, 1), b2 + hstepB, voffB); PG8_STAGE(PG8_SA(0, 0), a2, voffA);
;             PG8_WAIT_V(8); PG8_WAIT_L(0); PG8_BAR; PG8_MMA(1, 0, At, B0); PG8_MMA(1, 1, At, B1); PG8_BAR; PG8_SCHED;
.LBB0_632:
	ds_read_b128 v[144:147], v151
	ds_read_b128 v[156:159], v151 offset:1024
	ds_read_b128 v[160:163], v151 offset:2048
	ds_read_b128 v[164:167], v151 offset:3072
	ds_read_b128 v[168:171], v152
	ds_read_b128 v[172:175], v152 offset:1024
	ds_read_b128 v[176:179], v152 offset:2048
	ds_read_b128 v[180:183], v152 offset:3072
	s_add_u32 s28, s26, 0xfffc0080
	s_addc_u32 s29, s27, -1
	s_cmp_eq_u32 s50, 12
	s_cselect_b32 s31, s17, s29
	s_cselect_b32 s30, s23, s28
	s_cselect_b32 s29, s15, s49
	s_cselect_b32 s28, s43, s48
	s_add_i32 m0, s9, 0xc000
	ds_read_b128 v[184:187], v153
	ds_read_b128 v[188:191], v153 offset:1024
	ds_read_b128 v[194:197], v153 offset:2048
	ds_read_b128 v[198:201], v153 offset:3072
	ds_read_b128 v[202:205], v153 offset:4096
	ds_read_b128 v[206:209], v153 offset:5120
	ds_read_b128 v[210:213], v153 offset:6144
	ds_read_b128 v[214:217], v153 offset:7168
	global_load_lds_dwordx4 v136, s[26:27]
	s_add_i32 m0, s9, 0xe000
	s_nop 0
	global_load_lds_dwordx4 v138, s[26:27]
	s_waitcnt vmcnt(8)
	s_waitcnt lgkmcnt(0)
	s_barrier
	s_setprio 1
	s_waitcnt lgkmcnt(0)
	v_mfma_f32_16x16x32_bf16 v[124:127], v[144:147], v[184:187], v[124:127]
	v_mfma_f32_16x16x32_bf16 v[120:123], v[160:163], v[184:187], v[120:123]
	v_mfma_f32_16x16x32_bf16 v[108:111], v[144:147], v[194:197], v[108:111]
	v_mfma_f32_16x16x32_bf16 v[104:107], v[160:163], v[194:197], v[104:107]
	v_mfma_f32_16x16x32_bf16 v[92:95], v[144:147], v[202:205], v[92:95]
	v_mfma_f32_16x16x32_bf16 v[88:91], v[160:163], v[202:205], v[88:91]
	v_mfma_f32_16x16x32_bf16 v[76:79], v[144:147], v[210:213], v[76:79]
	v_mfma_f32_16x16x32_bf16 v[72:75], v[160:163], v[210:213], v[72:75]
	v_mfma_f32_16x16x32_bf16 v[124:127], v[156:159], v[188:191], v[124:127]
	v_mfma_f32_16x16x32_bf16 v[120:123], v[164:167], v[188:191], v[120:123]
	v_mfma_f32_16x16x32_bf16 v[108:111], v[156:159], v[198:201], v[108:111]
	v_mfma_f32_16x16x32_bf16 v[104:107], v[164:167], v[198:201], v[104:107]
	v_mfma_f32_16x16x32_bf16 v[92:95], v[156:159], v[206:209], v[92:95]
	v_mfma_f32_16x16x32_bf16 v[88:91], v[164:167], v[206:209], v[88:91]
	v_mfma_f32_16x16x32_bf16 v[76:79], v[156:159], v[214:217], v[76:79]
	v_mfma_f32_16x16x32_bf16 v[72:75], v[164:167], v[214:217], v[72:75]
	s_setprio 0
	s_setprio 1
	v_mfma_f32_16x16x32_bf16 v[116:119], v[168:171], v[184:187], v[116:119]
	v_mfma_f32_16x16x32_bf16 v[112:115], v[176:179], v[184:187], v[112:115]
	v_mfma_f32_16x16x32_bf16 v[100:103], v[168:171], v[194:197], v[100:103]
	v_mfma_f32_16x16x32_bf16 v[96:99], v[176:179], v[194:197], v[96:99]
	v_mfma_f32_16x16x32_bf16 v[84:87], v[168:171], v[202:205], v[84:87]
	v_mfma_f32_16x16x32_bf16 v[80:83], v[176:179], v[202:205], v[80:83]
	v_mfma_f32_16x16x32_bf16 v[68:71], v[168:171], v[210:213], v[68:71]
	v_mfma_f32_16x16x32_bf16 v[64:67], v[176:179], v[210:213], v[64:67]
	v_mfma_f32_16x16x32_bf16 v[116:119], v[172:175], v[188:191], v[116:119]
	v_mfma_f32_16x16x32_bf16 v[112:115], v[180:183], v[188:191], v[112:115]
	v_mfma_f32_16x16x32_bf16 v[100:103], v[172:175], v[198:201], v[100:103]
	v_mfma_f32_16x16x32_bf16 v[96:99], v[180:183], v[198:201], v[96:99]
	v_mfma_f32_16x16x32_bf16 v[84:87], v[172:175], v[206:209], v[84:87]
	v_mfma_f32_16x16x32_bf16 v[80:83], v[180:183], v[206:209], v[80:83]
	v_mfma_f32_16x16x32_bf16 v[68:71], v[172:175], v[214:217], v[68:71]
	v_mfma_f32_16x16x32_bf16 v[64:67], v[180:183], v[214:217], v[64:67]
	s_setprio 0
	s_barrier
	s_add_i32 s44, s41, s8
	v_lshl_add_u64 v[192:193], s[28:29], 0, v[130:131]
	s_mov_b32 m0, s44
	ds_read_b128 v[184:187], v153 offset:16384
	ds_read_b128 v[188:191], v153 offset:17408
	ds_read_b128 v[194:197], v153 offset:18432
	ds_read_b128 v[198:201], v153 offset:19456
	ds_read_b128 v[202:205], v153 offset:20480
	ds_read_b128 v[206:209], v153 offset:21504
	ds_read_b128 v[210:213], v153 offset:22528
	ds_read_b128 v[214:217], v153 offset:23552
	global_load_lds_dwordx4 v[192:193], off
	s_add_i32 m0, s44, 0x2000
	s_add_u32 s44, s28, 0x40000
	v_lshl_add_u64 v[218:219], s[28:29], 0, v[134:135]
	s_addc_u32 s45, s29, 0
	s_add_i32 s51, s42, s8
	global_load_lds_dwordx4 v[218:219], off
	s_mov_b32 m0, s51
	v_lshl_add_u64 v[222:223], s[30:31], 0, v[132:133]
	global_load_lds_dwordx4 v130, s[44:45]
	s_add_i32 m0, s51, 0x2000
	s_nop 0
	global_load_lds_dwordx4 v134, s[44:45]
	v_lshl_add_u64 v[220:221], s[30:31], 0, v[128:129]
	s_mov_b32 m0, s9
	s_nop 0
	global_load_lds_dwordx4 v[220:221], off
	s_mov_b32 m0, s10
	s_nop 0
	global_load_lds_dwordx4 v[222:223], off
	s_waitcnt vmcnt(8)
	s_waitcnt lgkmcnt(0)
	s_barrier
; #define PG8_STAGE(bufoff, gbase, voff) do { _Pragma("unroll") for (int _i = 0; _i < 2; ++_i) \
;         __builtin_amdgcn_global_load_lds((const unsigned*)((const char*)(gbase) + (voff)[_i]), (PG8_LAS unsigned*)(lds + (bufoff) + ldsw + _i * 8192), 16, 0, 0); } while (0)
; #define PG8_LDA(dst, b, h) do { _Pragma("unroll") for (int m = 0; m < 4; ++m) _Pragma("unroll") for (int k = 0; k < 2; ++k) dst[m][k] = *(const PG8_LAS bf16x8*)(lds + PG8_SA(b, h) + aoff + m * 2048 + k * 1024); } while (0)
; #define PG8_LDB(dst, b, h) do { _Pragma("unroll") for (int n = 0; n < 2; ++n) _Pragma("unroll") for (int k = 0; k < 2; ++k) dst[n][k] = *(const PG8_LAS bf16x8*)(lds + PG8_SB(b, h) + boff + n * 2048 + k * 1024); } while (0)
; #define PG8_MMA(ai, bj, At, Bt) do { __builtin_amdgcn_s_setprio(1); _Pragma("unroll") for (int m = 0; m < 4; ++m) _Pragma("unroll") for (int n = 0; n < 2; ++n) _Pragma("unroll") for (int k = 0; k < 2; ++k) \
;         acc[ai][bj][m][n] = __builtin_amdgcn_mfma_f32_16x16x32_bf16(Bt[n][k], At[m][k], acc[ai][bj][m][n], 0, 0, 0); __builtin_amdgcn_s_setprio(0); } while (0)
; #define PG8_WAIT_V(n) asm volatile("s_waitcnt vmcnt(" #n ")" ::: "memory")
; #define PG8_WAIT_L(n) asm volatile("s_waitcnt lgkmcnt(" #n ")" ::: "memory")
; #define PG8_BAR __builtin_amdgcn_s_barrier()
; #define PG8_SCHED __builtin_amdgcn_sched_barrier(0)
; template <class Epi, class Sched, bool ALIGN_EPI = false, bool SP2 = false>
; __device__ __forceinline__ void gemm_phase(PG8_LAS unsigned char* lds, const Gemm g, const Sched& S, const Epi& E) {
;     ...
;             PG8_WAIT_V(8); PG8_WAIT_L(0); PG8_BAR; PG8_MMA(1, 0, At, B0); PG8_MMA(1, 1, At, B1); PG8_BAR; PG8_SCHED;
;             PG8_LDB(B0, 1, 0); PG8_LDB(B1, 1, 1); PG8_SCHED; PG8_LDA(At, 1, 0); PG8_STAGE(PG8_SA(0, 1), a2 + hstepA, voffA);
;             PG8_WAIT_V(8); PG8_WAIT_L(0); PG8_BAR; PG8_MMA(0, 0, At, B0); PG8_MMA(0, 1, At, B1); PG8_BAR; PG8_SCHED;
;             PG8_LDA(At, 1, 1); PG8_STAGE(PG8_SB(1, 0), b3, voffB); PG8_STAGE(PG8_SB(1, 1), b3 + hstepB, voffB); PG8_STAGE(PG8_SA(1, 0), a3, voffA);
	s_setprio 1
	s_waitcnt lgkmcnt(0)
	v_mfma_f32_16x16x32_bf16 v[60:63], v[144:147], v[184:187], v[60:63]
	v_mfma_f32_16x16x32_bf16 v[56:59], v[160:163], v[184:187], v[56:59]
	v_mfma_f32_16x16x32_bf16 v[44:47], v[144:147], v[194:197], v[44:47]
	v_mfma_f32_16x16x32_bf16 v[40:43], v[160:163], v[194:197], v[40:43]
	v_mfma_f32_16x16x32_bf16 v[28:31], v[144:147], v[202:205], v[28:31]
	v_mfma_f32_16x16x32_bf16 v[24:27], v[160:163], v[202:205], v[24:27]
	v_mfma_f32_16x16x32_bf16 v[12:15], v[144:147], v[210:213], v[12:15]
	v_mfma_f32_16x16x32_bf16 v[8:11], v[160:163], v[210:213], v[8:11]
	v_mfma_f32_16x16x32_bf16 v[60:63], v[156:159], v[188:191], v[60:63]
	v_mfma_f32_16x16x32_bf16 v[56:59], v[164:167], v[188:191], v[56:59]
	v_mfma_f32_16x16x32_bf16 v[44:47], v[156:159], v[198:201], v[44:47]
	v_mfma_f32_16x16x32_bf16 v[40:43], v[164:167], v[198:201], v[40:43]
	v_mfma_f32_16x16x32_bf16 v[28:31], v[156:159], v[206:209], v[28:31]
	v_mfma_f32_16x16x32_bf16 v[24:27], v[164:167], v[206:209], v[24:27]
	v_mfma_f32_16x16x32_bf16 v[12:15], v[156:159], v[214:217], v[12:15]
	v_mfma_f32_16x16x32_bf16 v[8:11], v[164:167], v[214:217], v[8:11]
	s_setprio 0
	s_setprio 1
	v_mfma_f32_16x16x32_bf16 v[52:55], v[168:171], v[184:187], v[52:55]
	v_mfma_f32_16x16x32_bf16 v[48:51], v[176:179], v[184:187], v[48:51]
	v_mfma_f32_16x16x32_bf16 v[36:39], v[168:171], v[194:197], v[36:39]
	v_mfma_f32_16x16x32_bf16 v[32:35], v[176:179], v[194:197], v[32:35]
	v_mfma_f32_16x16x32_bf16 v[20:23], v[168:171], v[202:205], v[20:23]
	v_mfma_f32_16x16x32_bf16 v[16:19], v[176:179], v[202:205], v[16:19]
	v_mfma_f32_16x16x32_bf16 v[4:7], v[168:171], v[210:213], v[4:7]
	v_mfma_f32_16x16x32_bf16 v[0:3], v[176:179], v[210:213], v[0:3]
	v_mfma_f32_16x16x32_bf16 v[52:55], v[172:175], v[188:191], v[52:55]
	v_mfma_f32_16x16x32_bf16 v[48:51], v[180:183], v[188:191], v[48:51]
	v_mfma_f32_16x16x32_bf16 v[36:39], v[172:175], v[198:201], v[36:39]
	v_mfma_f32_16x16x32_bf16 v[32:35], v[180:183], v[198:201], v[32:35]
	v_mfma_f32_16x16x32_bf16 v[20:23], v[172:175], v[206:209], v[20:23]
	v_mfma_f32_16x16x32_bf16 v[16:19], v[180:183], v[206:209], v[16:19]
	v_mfma_f32_16x16x32_bf16 v[4:7], v[172:175], v[214:217], v[4:7]
	v_mfma_f32_16x16x32_bf16 v[0:3], v[180:183], v[214:217], v[0:3]
	s_setprio 0
	s_barrier
	s_add_i32 s44, 0, 0x18000
	v_add_u32_e32 v155, s44, v150
	s_add_i32 s45, 0, 0x1c000
	ds_read_b128 v[144:147], v155
	ds_read_b128 v[156:159], v155 offset:1024
	ds_read_b128 v[160:163], v155 offset:2048
	ds_read_b128 v[164:167], v155 offset:3072
	v_add_u32_e32 v155, s45, v150
	ds_read_b128 v[168:171], v155
	ds_read_b128 v[172:175], v155 offset:1024
	ds_read_b128 v[176:179], v155 offset:2048
	ds_read_b128 v[180:183], v155 offset:3072
	s_add_u32 s30, s30, 0x40000
	s_addc_u32 s31, s31, 0
	s_mov_b32 m0, s11
	ds_read_b128 v[184:187], v153 offset:32768
	ds_read_b128 v[188:191], v153 offset:33792
	ds_read_b128 v[194:197], v153 offset:34816
	ds_read_b128 v[198:201], v153 offset:35840
	ds_read_b128 v[202:205], v153 offset:36864
	ds_read_b128 v[206:209], v153 offset:37888
	ds_read_b128 v[210:213], v153 offset:38912
	ds_read_b128 v[214:217], v153 offset:39936
	global_load_lds_dwordx4 v128, s[30:31]
	s_mov_b32 m0, s25
	s_nop 0
	global_load_lds_dwordx4 v132, s[30:31]
	s_waitcnt vmcnt(8)
	s_waitcnt lgkmcnt(0)
	s_barrier
	s_setprio 1
	s_waitcnt lgkmcnt(0)
	v_mfma_f32_16x16x32_bf16 v[124:127], v[144:147], v[184:187], v[124:127]
	v_mfma_f32_16x16x32_bf16 v[120:123], v[160:163], v[184:187], v[120:123]
	v_mfma_f32_16x16x32_bf16 v[108:111], v[144:147], v[194:197], v[108:111]
	v_mfma_f32_16x16x32_bf16 v[104:107], v[160:163], v[194:197], v[104:107]
	v_mfma_f32_16x16x32_bf16 v[92:95], v[144:147], v[202:205], v[92:95]
	v_mfma_f32_16x16x32_bf16 v[88:91], v[160:163], v[202:205], v[88:91]
	v_mfma_f32_16x16x32_bf16 v[76:79], v[144:147], v[210:213], v[76:79]
	v_mfma_f32_16x16x32_bf16 v[72:75], v[160:163], v[210:213], v[72:75]
	v_mfma_f32_16x16x32_bf16 v[124:127], v[156:159], v[188:191], v[124:127]
	v_mfma_f32_16x16x32_bf16 v[120:123], v[164:167], v[188:191], v[120:123]
	v_mfma_f32_16x16x32_bf16 v[108:111], v[156:159], v[198:201], v[108:111]
	v_mfma_f32_16x16x32_bf16 v[104:107], v[164:167], v[198:201], v[104:107]
	v_mfma_f32_16x16x32_bf16 v[92:95], v[156:159], v[206:209], v[92:95]
	v_mfma_f32_16x16x32_bf16 v[88:91], v[164:167], v[206:209], v[88:91]
	v_mfma_f32_16x16x32_bf16 v[76:79], v[156:159], v[214:217], v[76:79]
	v_mfma_f32_16x16x32_bf16 v[72:75], v[164:167], v[214:217], v[72:75]
	s_setprio 0
	s_setprio 1
	v_mfma_f32_16x16x32_bf16 v[116:119], v[168:171], v[184:187], v[116:119]
	v_mfma_f32_16x16x32_bf16 v[112:115], v[176:179], v[184:187], v[112:115]
	v_mfma_f32_16x16x32_bf16 v[100:103], v[168:171], v[194:197], v[100:103]
	v_mfma_f32_16x16x32_bf16 v[96:99], v[176:179], v[194:197], v[96:99]
	v_mfma_f32_16x16x32_bf16 v[84:87], v[168:171], v[202:205], v[84:87]
	v_mfma_f32_16x16x32_bf16 v[80:83], v[176:179], v[202:205], v[80:83]
	v_mfma_f32_16x16x32_bf16 v[68:71], v[168:171], v[210:213], v[68:71]
	v_mfma_f32_16x16x32_bf16 v[64:67], v[176:179], v[210:213], v[64:67]
	v_mfma_f32_16x16x32_bf16 v[116:119], v[172:175], v[188:191], v[116:119]
	v_mfma_f32_16x16x32_bf16 v[112:115], v[180:183], v[188:191], v[112:115]
	v_mfma_f32_16x16x32_bf16 v[100:103], v[172:175], v[198:201], v[100:103]
	v_mfma_f32_16x16x32_bf16 v[96:99], v[180:183], v[198:201], v[96:99]
	v_mfma_f32_16x16x32_bf16 v[84:87], v[172:175], v[206:209], v[84:87]
	v_mfma_f32_16x16x32_bf16 v[80:83], v[180:183], v[206:209], v[80:83]
	v_mfma_f32_16x16x32_bf16 v[68:71], v[172:175], v[214:217], v[68:71]
	v_mfma_f32_16x16x32_bf16 v[64:67], v[180:183], v[214:217], v[64:67]
	s_setprio 0
	s_barrier
; #define PG8_STAGE(bufoff, gbase, voff) do { _Pragma("unroll") for (int _i = 0; _i < 2; ++_i) \
;         __builtin_amdgcn_global_load_lds((const unsigned*)((const char*)(gbase) + (voff)[_i]), (PG8_LAS unsigned*)(lds + (bufoff) + ldsw + _i * 8192), 16, 0, 0); } while (0)
; #define PG8_LDA(dst, b, h) do { _Pragma("unroll") for (int m = 0; m < 4; ++m) _Pragma("unroll") for (int k = 0; k < 2; ++k) dst[m][k] = *(const PG8_LAS bf16x8*)(lds + PG8_SA(b, h) + aoff + m * 2048 + k * 1024); } while (0)
; #define PG8_MMA(ai, bj, At, Bt) do { __builtin_amdgcn_s_setprio(1); _Pragma("unroll") for (int m = 0; m < 4; ++m) _Pragma("unroll") for (int n = 0; n < 2; ++n) _Pragma("unroll") for (int k = 0; k < 2; ++k) \
;         acc[ai][bj][m][n] = __builtin_amdgcn_mfma_f32_16x16x32_bf16(Bt[n][k], At[m][k], acc[ai][bj][m][n], 0, 0, 0); __builtin_amdgcn_s_setprio(0); } while (0)
; #define PG8_WAIT_V(n) asm volatile("s_waitcnt vmcnt(" #n ")" ::: "memory")
; #define PG8_WAIT_L(n) asm volatile("s_waitcnt lgkmcnt(" #n ")" ::: "memory")
; #define PG8_BAR __builtin_amdgcn_s_barrier()
;     __device__ __forceinline__ void operator()(const f32x4 (&acc)[2][2][4][2], const Unit& u, int wr, int wc, int fr, int fq) const {
;         const int row0 = u.pm * BM + wr * 64 + fr; const int col0 = u.pn * BM + wc * 32 + 8 * fq;
; #pragma unroll
;         for (int ai = 0; ai < 2; ++ai)
; #pragma unroll
;             for (int m = 0; m < 4; ++m) { const int row = row0 + ai * HALF + m * 16; const size_t off = (size_t)row * ldc + col0; float s = 0.f;
; #pragma unroll
;                 for (int bj = 0; bj < 2; ++bj) { const size_t o2 = off + bj * HALF;
;                     const f32x4 v0 = *(const f32x4*)(base + o2) + acc[ai][bj][m][0], v1 = *(const f32x4*)(base + o2 + 4) + acc[ai][bj][m][1];
; template <class Epi, class Sched, bool ALIGN_EPI = false, bool SP2 = false>
; __device__ __forceinline__ void gemm_phase(PG8_LAS unsigned char* lds, const Gemm g, const Sched& S, const Epi& E) {
;     ...
;             PG8_WAIT_V(8); PG8_WAIT_L(0); PG8_BAR; PG8_MMA(0, 0, At, B0); PG8_MMA(0, 1, At, B1); PG8_BAR; PG8_SCHED;
;             PG8_LDA(At, 1, 1); PG8_STAGE(PG8_SB(1, 0), b3, voffB); PG8_STAGE(PG8_SB(1, 1), b3 + hstepB, voffB); PG8_STAGE(PG8_SA(1, 0), a3, voffA);
;             PG8_WAIT_V(8); PG8_WAIT_L(0); PG8_BAR; PG8_MMA(1, 0, At, B0); PG8_MMA(1, 1, At, B1); PG8_BAR; PG8_SCHED;
	s_add_i32 s30, s44, s8
	v_lshl_add_u64 v[192:193], v[192:193], 0, s[6:7]
	s_mov_b32 m0, s30
	ds_read_b128 v[184:187], v153 offset:49152
	ds_read_b128 v[188:191], v153 offset:50176
	ds_read_b128 v[194:197], v153 offset:51200
	ds_read_b128 v[198:201], v153 offset:52224
	ds_read_b128 v[202:205], v153 offset:53248
	ds_read_b128 v[206:209], v153 offset:54272
	ds_read_b128 v[210:213], v153 offset:55296
	ds_read_b128 v[214:217], v153 offset:56320
	global_load_lds_dwordx4 v[192:193], off
	s_add_i32 m0, s30, 0x2000
	s_add_u32 s28, s28, 0x40080
	v_lshl_add_u64 v[192:193], v[218:219], 0, s[6:7]
	s_addc_u32 s29, s29, 0
	s_add_i32 s30, s45, s8
	global_load_lds_dwordx4 v[192:193], off
	s_mov_b32 m0, s30
	s_nop 0
	global_load_lds_dwordx4 v130, s[28:29]
	s_add_i32 m0, s30, 0x2000
	s_nop 0
	global_load_lds_dwordx4 v134, s[28:29]
	v_lshl_add_u64 v[192:193], v[220:221], 0, s[6:7]
	s_mov_b32 m0, s36
	s_nop 0
	global_load_lds_dwordx4 v[192:193], off
	v_lshl_add_u64 v[192:193], v[222:223], 0, s[6:7]
	s_mov_b32 m0, s37
	s_nop 0
	global_load_lds_dwordx4 v[192:193], off
	s_waitcnt vmcnt(8)
	s_waitcnt lgkmcnt(0)
	s_barrier
	s_setprio 1
	s_waitcnt lgkmcnt(0)
	v_mfma_f32_16x16x32_bf16 v[60:63], v[144:147], v[184:187], v[60:63]
	v_mfma_f32_16x16x32_bf16 v[56:59], v[160:163], v[184:187], v[56:59]
	v_mfma_f32_16x16x32_bf16 v[44:47], v[144:147], v[194:197], v[44:47]
	v_mfma_f32_16x16x32_bf16 v[40:43], v[160:163], v[194:197], v[40:43]
	v_mfma_f32_16x16x32_bf16 v[28:31], v[144:147], v[202:205], v[28:31]
	v_mfma_f32_16x16x32_bf16 v[24:27], v[160:163], v[202:205], v[24:27]
	v_mfma_f32_16x16x32_bf16 v[12:15], v[144:147], v[210:213], v[12:15]
	v_mfma_f32_16x16x32_bf16 v[8:11], v[160:163], v[210:213], v[8:11]
	v_mfma_f32_16x16x32_bf16 v[60:63], v[156:159], v[188:191], v[60:63]
	v_mfma_f32_16x16x32_bf16 v[56:59], v[164:167], v[188:191], v[56:59]
	v_mfma_f32_16x16x32_bf16 v[44:47], v[156:159], v[198:201], v[44:47]
	v_mfma_f32_16x16x32_bf16 v[40:43], v[164:167], v[198:201], v[40:43]
	v_mfma_f32_16x16x32_bf16 v[28:31], v[156:159], v[206:209], v[28:31]
	v_mfma_f32_16x16x32_bf16 v[24:27], v[164:167], v[206:209], v[24:27]
	v_mfma_f32_16x16x32_bf16 v[12:15], v[156:159], v[214:217], v[12:15]
	v_mfma_f32_16x16x32_bf16 v[8:11], v[164:167], v[214:217], v[8:11]
	s_setprio 0
	s_setprio 1
	v_mfma_f32_16x16x32_bf16 v[52:55], v[168:171], v[184:187], v[52:55]
	v_mfma_f32_16x16x32_bf16 v[48:51], v[176:179], v[184:187], v[48:51]
	v_mfma_f32_16x16x32_bf16 v[36:39], v[168:171], v[194:197], v[36:39]
	v_mfma_f32_16x16x32_bf16 v[32:35], v[176:179], v[194:197], v[32:35]
	v_mfma_f32_16x16x32_bf16 v[20:23], v[168:171], v[202:205], v[20:23]
	v_mfma_f32_16x16x32_bf16 v[16:19], v[176:179], v[202:205], v[16:19]
	v_mfma_f32_16x16x32_bf16 v[4:7], v[168:171], v[210:213], v[4:7]
	v_mfma_f32_16x16x32_bf16 v[0:3], v[176:179], v[210:213], v[0:3]
	v_mfma_f32_16x16x32_bf16 v[52:55], v[172:175], v[188:191], v[52:55]
	v_mfma_f32_16x16x32_bf16 v[48:51], v[180:183], v[188:191], v[48:51]
	v_mfma_f32_16x16x32_bf16 v[36:39], v[172:175], v[198:201], v[36:39]
	v_mfma_f32_16x16x32_bf16 v[32:35], v[180:183], v[198:201], v[32:35]
	v_mfma_f32_16x16x32_bf16 v[20:23], v[172:175], v[206:209], v[20:23]
	v_mfma_f32_16x16x32_bf16 v[16:19], v[180:183], v[206:209], v[16:19]
	v_mfma_f32_16x16x32_bf16 v[4:7], v[172:175], v[214:217], v[4:7]
	v_mfma_f32_16x16x32_bf16 v[0:3], v[180:183], v[214:217], v[0:3]
	s_setprio 0
	s_barrier
	s_add_i32 s50, s50, 2
	s_add_u32 s26, s26, 0x100
	s_addc_u32 s27, s27, 0
	s_add_u32 s48, s48, 0x100
	s_addc_u32 s49, s49, 0
	s_cmp_gt_u32 s50, 13
	s_cbranch_scc0 .LBB0_632
	s_and_b64 vcc, exec, s[12:13]
	s_cbranch_vccz .LBB0_635
	s_barrier
.LBB0_635:
	s_lshl_b32 s15, s24, 8
	s_add_i32 s15, s15, s34
	v_readlane_b32 s48, v255, 0
	v_readlane_b32 s49, v255, 1
	v_add_u32_e32 v144, s15, v148
	s_lshl_b32 s15, s22, 8
	s_or_b32 s15, s15, s35
	v_lshl_add_u32 v145, v149, 3, s15
	v_lshl_add_u32 v146, v144, 10, v145
	v_lshlrev_b32_e32 v147, 2, v146
	v_lshlrev_b32_e32 v155, 1, v146
	v_lshlrev_b32_e32 v156, 2, v144
	v_xor_b32_e32 v157, 16, v154
	v_xor_b32_e32 v158, 32, v154
	v_lshlrev_b32_e32 v157, 2, v157
	v_lshlrev_b32_e32 v158, 2, v158
	v_cmp_eq_u32_e64 s[54:55], 0, v149
	s_mov_b64 s[50:51], s[48:49]
	global_load_dwordx4 v[170:173], v147, s[50:51] nt
	global_load_dwordx4 v[174:177], v147, s[50:51] offset:16 nt
	global_load_dwordx4 v[178:181], v147, s[50:51] offset:512 nt
	global_load_dwordx4 v[182:185], v147, s[50:51] offset:528 nt
	s_add_u32 s50, s48, 0x10000
	s_addc_u32 s51, s49, 0
	global_load_dwordx4 v[186:189], v147, s[50:51] nt
	global_load_dwordx4 v[190:193], v147, s[50:51] offset:16 nt
	global_load_dwordx4 v[194:197], v147, s[50:51] offset:512 nt
	global_load_dwordx4 v[198:201], v147, s[50:51] offset:528 nt
	s_add_u32 s50, s48, 0x20000
	s_addc_u32 s51, s49, 0
	global_load_dwordx4 v[202:205], v147, s[50:51] nt
	global_load_dwordx4 v[206:209], v147, s[50:51] offset:16 nt
	global_load_dwordx4 v[210:213], v147, s[50:51] offset:512 nt
	global_load_dwordx4 v[214:217], v147, s[50:51] offset:528 nt
	s_add_u32 s50, s48, 0x30000
	s_addc_u32 s51, s49, 0
	global_load_dwordx4 v[218:221], v147, s[50:51] nt
	global_load_dwordx4 v[222:225], v147, s[50:51] offset:16 nt
	global_load_dwordx4 v[226:229], v147, s[50:51] offset:512 nt
	global_load_dwordx4 v[230:233], v147, s[50:51] offset:528 nt
	s_waitcnt vmcnt(12)
; __device__ __forceinline__ unsigned pk2(float a, float b) { f32x2_t v = {a, b}; bf16x2v_t r = __builtin_convertvector(v, bf16x2v_t); return __builtin_bit_cast(unsigned, r); }
;     __device__ __forceinline__ void operator()(const f32x4 (&acc)[2][2][4][2], const Unit& u, int wr, int wc, int fr, int fq) const {
;     ...
;         for (int ai = 0; ai < 2; ++ai)
; #pragma unroll
;             for (int m = 0; m < 4; ++m) { const int row = row0 + ai * HALF + m * 16; const size_t off = (size_t)row * ldc + col0; float s = 0.f;
; #pragma unroll
;                 for (int bj = 0; bj < 2; ++bj) { const size_t o2 = off + bj * HALF;
;                     const f32x4 v0 = *(const f32x4*)(base + o2) + acc[ai][bj][m][0], v1 = *(const f32x4*)(base + o2 + 4) + acc[ai][bj][m][1];
;                     u32x4 w; w.x = pk2(v0[0], v0[1]); w.y = pk2(v0[2], v0[3]); w.z = pk2(v1[0], v1[1]); w.w = pk2(v1[2], v1[3]); *(u32x4*)(xb + o2) = w;
;                     s += ((v0[0] * v0[0] + v0[1] * v0[1]) + (v0[2] * v0[2] + v0[3] * v0[3])) + ((v1[0] * v1[0] + v1[1] * v1[1]) + (v1[2] * v1[2] + v1[3] * v1[3])); }
;                 s += __shfl_xor(s, 16); s += __shfl_xor(s, 32);
;                 if (fq == 0) atomicAdd(rowsq + row, s);
	s_mov_b64 s[52:53], s[46:47]
	v_pk_add_f32 v[124:125], v[124:125], v[170:171]
	v_pk_add_f32 v[126:127], v[126:127], v[172:173]
	v_pk_add_f32 v[120:121], v[120:121], v[174:175]
	v_pk_add_f32 v[122:123], v[122:123], v[176:177]
	v_cvt_pk_bf16_f32 v160, v124, v125
	v_cvt_pk_bf16_f32 v161, v126, v127
	v_cvt_pk_bf16_f32 v162, v120, v121
	v_cvt_pk_bf16_f32 v163, v122, v123
	global_store_dwordx4 v155, v[160:163], s[52:53]
	v_mul_f32_e32 v164, v124, v124
	v_fmac_f32_e32 v164, v125, v125
	v_fmac_f32_e32 v164, v126, v126
	v_fmac_f32_e32 v164, v127, v127
	v_fmac_f32_e32 v164, v120, v120
	v_fmac_f32_e32 v164, v121, v121
	v_fmac_f32_e32 v164, v122, v122
	v_fmac_f32_e32 v164, v123, v123
	v_pk_add_f32 v[116:117], v[116:117], v[178:179]
	v_pk_add_f32 v[118:119], v[118:119], v[180:181]
	v_pk_add_f32 v[112:113], v[112:113], v[182:183]
	v_pk_add_f32 v[114:115], v[114:115], v[184:185]
	v_cvt_pk_bf16_f32 v160, v116, v117
	v_cvt_pk_bf16_f32 v161, v118, v119
	v_cvt_pk_bf16_f32 v162, v112, v113
	v_cvt_pk_bf16_f32 v163, v114, v115
	global_store_dwordx4 v155, v[160:163], s[52:53] offset:256
	v_fmac_f32_e32 v164, v116, v116
	v_fmac_f32_e32 v164, v117, v117
	v_fmac_f32_e32 v164, v118, v118
	v_fmac_f32_e32 v164, v119, v119
	v_fmac_f32_e32 v164, v112, v112
	v_fmac_f32_e32 v164, v113, v113
	v_fmac_f32_e32 v164, v114, v114
	v_fmac_f32_e32 v164, v115, v115
	ds_bpermute_b32 v165, v157, v164
	s_waitcnt lgkmcnt(0)
	v_add_f32_e32 v164, v164, v165
	ds_bpermute_b32 v165, v158, v164
	s_waitcnt lgkmcnt(0)
	v_add_f32_e32 v164, v164, v165
	s_and_saveexec_b64 s[22:23], s[54:55]
	global_atomic_add_f32 v156, v164, s[70:71]
	s_or_b64 exec, exec, s[22:23]
	s_add_u32 s50, s48, 0x80000
	s_addc_u32 s51, s49, 0
	global_load_dwordx4 v[170:173], v147, s[50:51] nt
	global_load_dwordx4 v[174:177], v147, s[50:51] offset:16 nt
	global_load_dwordx4 v[178:181], v147, s[50:51] offset:512 nt
	global_load_dwordx4 v[182:185], v147, s[50:51] offset:528 nt
	s_waitcnt vmcnt(15)
	s_add_u32 s52, s46, 0x8000
	s_addc_u32 s53, s47, 0
	v_pk_add_f32 v[108:109], v[108:109], v[186:187]
	v_pk_add_f32 v[110:111], v[110:111], v[188:189]
	v_pk_add_f32 v[104:105], v[104:105], v[190:191]
	v_pk_add_f32 v[106:107], v[106:107], v[192:193]
	v_cvt_pk_bf16_f32 v160, v108, v109
	v_cvt_pk_bf16_f32 v161, v110, v111
	v_cvt_pk_bf16_f32 v162, v104, v105
	v_cvt_pk_bf16_f32 v163, v106, v107
	global_store_dwordx4 v155, v[160:163], s[52:53]
	v_mul_f32_e32 v164, v108, v108
	v_fmac_f32_e32 v164, v109, v109
	v_fmac_f32_e32 v164, v110, v110
	v_fmac_f32_e32 v164, v111, v111
	v_fmac_f32_e32 v164, v104, v104
	v_fmac_f32_e32 v164, v105, v105
	v_fmac_f32_e32 v164, v106, v106
	v_fmac_f32_e32 v164, v107, v107
	v_pk_add_f32 v[100:101], v[100:101], v[194:195]
	v_pk_add_f32 v[102:103], v[102:103], v[196:197]
	v_pk_add_f32 v[96:97], v[96:97], v[198:199]
	v_pk_add_f32 v[98:99], v[98:99], v[200:201]
	v_cvt_pk_bf16_f32 v160, v100, v101
	v_cvt_pk_bf16_f32 v161, v102, v103
	v_cvt_pk_bf16_f32 v162, v96, v97
	v_cvt_pk_bf16_f32 v163, v98, v99
	global_store_dwordx4 v155, v[160:163], s[52:53] offset:256
	v_fmac_f32_e32 v164, v100, v100
	v_fmac_f32_e32 v164, v101, v101
	v_fmac_f32_e32 v164, v102, v102
	v_fmac_f32_e32 v164, v103, v103
	v_fmac_f32_e32 v164, v96, v96
	v_fmac_f32_e32 v164, v97, v97
	v_fmac_f32_e32 v164, v98, v98
	v_fmac_f32_e32 v164, v99, v99
	ds_bpermute_b32 v165, v157, v164
	s_waitcnt lgkmcnt(0)
	v_add_f32_e32 v164, v164, v165
	ds_bpermute_b32 v165, v158, v164
	s_waitcnt lgkmcnt(0)
	v_add_f32_e32 v164, v164, v165
	s_and_saveexec_b64 s[22:23], s[54:55]
	global_atomic_add_f32 v156, v164, s[70:71] offset:64
	s_or_b64 exec, exec, s[22:23]
	s_add_u32 s50, s48, 0x90000
	s_addc_u32 s51, s49, 0
	global_load_dwordx4 v[186:189], v147, s[50:51] nt
	global_load_dwordx4 v[190:193], v147, s[50:51] offset:16 nt
	global_load_dwordx4 v[194:197], v147, s[50:51] offset:512 nt
	global_load_dwordx4 v[198:201], v147, s[50:51] offset:528 nt
	s_waitcnt vmcnt(18)
	s_add_u32 s52, s46, 0x10000
	s_addc_u32 s53, s47, 0
	v_pk_add_f32 v[92:93], v[92:93], v[202:203]
	v_pk_add_f32 v[94:95], v[94:95], v[204:205]
	v_pk_add_f32 v[88:89], v[88:89], v[206:207]
	v_pk_add_f32 v[90:91], v[90:91], v[208:209]
	v_cvt_pk_bf16_f32 v160, v92, v93
	v_cvt_pk_bf16_f32 v161, v94, v95
	v_cvt_pk_bf16_f32 v162, v88, v89
	v_cvt_pk_bf16_f32 v163, v90, v91
	global_store_dwordx4 v155, v[160:163], s[52:53]
	v_mul_f32_e32 v164, v92, v92
	v_fmac_f32_e32 v164, v93, v93
	v_fmac_f32_e32 v164, v94, v94
	v_fmac_f32_e32 v164, v95, v95
	v_fmac_f32_e32 v164, v88, v88
	v_fmac_f32_e32 v164, v89, v89
	v_fmac_f32_e32 v164, v90, v90
	v_fmac_f32_e32 v164, v91, v91
	v_pk_add_f32 v[84:85], v[84:85], v[210:211]
	v_pk_add_f32 v[86:87], v[86:87], v[212:213]
	v_pk_add_f32 v[80:81], v[80:81], v[214:215]
	v_pk_add_f32 v[82:83], v[82:83], v[216:217]
	v_cvt_pk_bf16_f32 v160, v84, v85
	v_cvt_pk_bf16_f32 v161, v86, v87
	v_cvt_pk_bf16_f32 v162, v80, v81
	v_cvt_pk_bf16_f32 v163, v82, v83
	global_store_dwordx4 v155, v[160:163], s[52:53] offset:256
	v_fmac_f32_e32 v164, v84, v84
	v_fmac_f32_e32 v164, v85, v85
	v_fmac_f32_e32 v164, v86, v86
	v_fmac_f32_e32 v164, v87, v87
	v_fmac_f32_e32 v164, v80, v80
	v_fmac_f32_e32 v164, v81, v81
	v_fmac_f32_e32 v164, v82, v82
	v_fmac_f32_e32 v164, v83, v83
	ds_bpermute_b32 v165, v157, v164
	s_waitcnt lgkmcnt(0)
	v_add_f32_e32 v164, v164, v165
	ds_bpermute_b32 v165, v158, v164
	s_waitcnt lgkmcnt(0)
	v_add_f32_e32 v164, v164, v165
	s_and_saveexec_b64 s[22:23], s[54:55]
	global_atomic_add_f32 v156, v164, s[70:71] offset:128
	s_or_b64 exec, exec, s[22:23]
	s_add_u32 s50, s48, 0xa0000
	s_addc_u32 s51, s49, 0
	global_load_dwordx4 v[202:205], v147, s[50:51] nt
	global_load_dwordx4 v[206:209], v147, s[50:51] offset:16 nt
	global_load_dwordx4 v[210:213], v147, s[50:51] offset:512 nt
	global_load_dwordx4 v[214:217], v147, s[50:51] offset:528 nt
	s_waitcnt vmcnt(21)
; __device__ __forceinline__ unsigned pk2(float a, float b) { f32x2_t v = {a, b}; bf16x2v_t r = __builtin_convertvector(v, bf16x2v_t); return __builtin_bit_cast(unsigned, r); }
;     __device__ __forceinline__ void operator()(const f32x4 (&acc)[2][2][4][2], const Unit& u, int wr, int wc, int fr, int fq) const {
;     ...
;         for (int ai = 0; ai < 2; ++ai)
; #pragma unroll
;             for (int m = 0; m < 4; ++m) { const int row = row0 + ai * HALF + m * 16; const size_t off = (size_t)row * ldc + col0; float s = 0.f;
; #pragma unroll
;                 for (int bj = 0; bj < 2; ++bj) { const size_t o2 = off + bj * HALF;
;                     const f32x4 v0 = *(const f32x4*)(base + o2) + acc[ai][bj][m][0], v1 = *(const f32x4*)(base + o2 + 4) + acc[ai][bj][m][1];
;                     u32x4 w; w.x = pk2(v0[0], v0[1]); w.y = pk2(v0[2], v0[3]); w.z = pk2(v1[0], v1[1]); w.w = pk2(v1[2], v1[3]); *(u32x4*)(xb + o2) = w;
;                     s += ((v0[0] * v0[0] + v0[1] * v0[1]) + (v0[2] * v0[2] + v0[3] * v0[3])) + ((v1[0] * v1[0] + v1[1] * v1[1]) + (v1[2] * v1[2] + v1[3] * v1[3])); }
;                 s += __shfl_xor(s, 16); s += __shfl_xor(s, 32);
;                 if (fq == 0) atomicAdd(rowsq + row, s);
	s_add_u32 s52, s46, 0x18000
	s_addc_u32 s53, s47, 0
	v_pk_add_f32 v[76:77], v[76:77], v[218:219]
	v_pk_add_f32 v[78:79], v[78:79], v[220:221]
	v_pk_add_f32 v[72:73], v[72:73], v[222:223]
	v_pk_add_f32 v[74:75], v[74:75], v[224:225]
	v_cvt_pk_bf16_f32 v160, v76, v77
	v_cvt_pk_bf16_f32 v161, v78, v79
	v_cvt_pk_bf16_f32 v162, v72, v73
	v_cvt_pk_bf16_f32 v163, v74, v75
	global_store_dwordx4 v155, v[160:163], s[52:53]
	v_mul_f32_e32 v164, v76, v76
	v_fmac_f32_e32 v164, v77, v77
	v_fmac_f32_e32 v164, v78, v78
	v_fmac_f32_e32 v164, v79, v79
	v_fmac_f32_e32 v164, v72, v72
	v_fmac_f32_e32 v164, v73, v73
	v_fmac_f32_e32 v164, v74, v74
	v_fmac_f32_e32 v164, v75, v75
	v_pk_add_f32 v[68:69], v[68:69], v[226:227]
	v_pk_add_f32 v[70:71], v[70:71], v[228:229]
	v_pk_add_f32 v[64:65], v[64:65], v[230:231]
	v_pk_add_f32 v[66:67], v[66:67], v[232:233]
	v_cvt_pk_bf16_f32 v160, v68, v69
	v_cvt_pk_bf16_f32 v161, v70, v71
	v_cvt_pk_bf16_f32 v162, v64, v65
	v_cvt_pk_bf16_f32 v163, v66, v67
	global_store_dwordx4 v155, v[160:163], s[52:53] offset:256
	v_fmac_f32_e32 v164, v68, v68
	v_fmac_f32_e32 v164, v69, v69
	v_fmac_f32_e32 v164, v70, v70
	v_fmac_f32_e32 v164, v71, v71
	v_fmac_f32_e32 v164, v64, v64
	v_fmac_f32_e32 v164, v65, v65
	v_fmac_f32_e32 v164, v66, v66
	v_fmac_f32_e32 v164, v67, v67
	ds_bpermute_b32 v165, v157, v164
	s_waitcnt lgkmcnt(0)
	v_add_f32_e32 v164, v164, v165
	ds_bpermute_b32 v165, v158, v164
	s_waitcnt lgkmcnt(0)
	v_add_f32_e32 v164, v164, v165
	s_and_saveexec_b64 s[22:23], s[54:55]
	global_atomic_add_f32 v156, v164, s[70:71] offset:192
	s_or_b64 exec, exec, s[22:23]
	s_add_u32 s50, s48, 0xb0000
	s_addc_u32 s51, s49, 0
	global_load_dwordx4 v[218:221], v147, s[50:51] nt
	global_load_dwordx4 v[222:225], v147, s[50:51] offset:16 nt
	global_load_dwordx4 v[226:229], v147, s[50:51] offset:512 nt
	global_load_dwordx4 v[230:233], v147, s[50:51] offset:528 nt
	s_waitcnt vmcnt(21)
	s_add_u32 s52, s46, 0x40000
	s_addc_u32 s53, s47, 0
	v_pk_add_f32 v[60:61], v[60:61], v[170:171]
	v_pk_add_f32 v[62:63], v[62:63], v[172:173]
	v_pk_add_f32 v[56:57], v[56:57], v[174:175]
	v_pk_add_f32 v[58:59], v[58:59], v[176:177]
	v_cvt_pk_bf16_f32 v160, v60, v61
	v_cvt_pk_bf16_f32 v161, v62, v63
	v_cvt_pk_bf16_f32 v162, v56, v57
	v_cvt_pk_bf16_f32 v163, v58, v59
	global_store_dwordx4 v155, v[160:163], s[52:53]
	v_mul_f32_e32 v164, v60, v60
	v_fmac_f32_e32 v164, v61, v61
	v_fmac_f32_e32 v164, v62, v62
	v_fmac_f32_e32 v164, v63, v63
	v_fmac_f32_e32 v164, v56, v56
	v_fmac_f32_e32 v164, v57, v57
	v_fmac_f32_e32 v164, v58, v58
	v_fmac_f32_e32 v164, v59, v59
	v_pk_add_f32 v[52:53], v[52:53], v[178:179]
	v_pk_add_f32 v[54:55], v[54:55], v[180:181]
	v_pk_add_f32 v[48:49], v[48:49], v[182:183]
	v_pk_add_f32 v[50:51], v[50:51], v[184:185]
	v_cvt_pk_bf16_f32 v160, v52, v53
	v_cvt_pk_bf16_f32 v161, v54, v55
	v_cvt_pk_bf16_f32 v162, v48, v49
	v_cvt_pk_bf16_f32 v163, v50, v51
	global_store_dwordx4 v155, v[160:163], s[52:53] offset:256
	v_fmac_f32_e32 v164, v52, v52
	v_fmac_f32_e32 v164, v53, v53
	v_fmac_f32_e32 v164, v54, v54
	v_fmac_f32_e32 v164, v55, v55
	v_fmac_f32_e32 v164, v48, v48
	v_fmac_f32_e32 v164, v49, v49
	v_fmac_f32_e32 v164, v50, v50
	v_fmac_f32_e32 v164, v51, v51
	ds_bpermute_b32 v165, v157, v164
	s_waitcnt lgkmcnt(0)
	v_add_f32_e32 v164, v164, v165
	ds_bpermute_b32 v165, v158, v164
	s_waitcnt lgkmcnt(0)
	v_add_f32_e32 v164, v164, v165
	s_and_saveexec_b64 s[22:23], s[54:55]
	global_atomic_add_f32 v156, v164, s[70:71] offset:512
	s_or_b64 exec, exec, s[22:23]
	s_waitcnt vmcnt(17)
	s_add_u32 s52, s46, 0x48000
	s_addc_u32 s53, s47, 0
	v_pk_add_f32 v[44:45], v[44:45], v[186:187]
	v_pk_add_f32 v[46:47], v[46:47], v[188:189]
	v_pk_add_f32 v[40:41], v[40:41], v[190:191]
	v_pk_add_f32 v[42:43], v[42:43], v[192:193]
	v_cvt_pk_bf16_f32 v160, v44, v45
	v_cvt_pk_bf16_f32 v161, v46, v47
	v_cvt_pk_bf16_f32 v162, v40, v41
	v_cvt_pk_bf16_f32 v163, v42, v43
	global_store_dwordx4 v155, v[160:163], s[52:53]
	v_mul_f32_e32 v164, v44, v44
	v_fmac_f32_e32 v164, v45, v45
	v_fmac_f32_e32 v164, v46, v46
	v_fmac_f32_e32 v164, v47, v47
	v_fmac_f32_e32 v164, v40, v40
	v_fmac_f32_e32 v164, v41, v41
	v_fmac_f32_e32 v164, v42, v42
	v_fmac_f32_e32 v164, v43, v43
	v_pk_add_f32 v[36:37], v[36:37], v[194:195]
	v_pk_add_f32 v[38:39], v[38:39], v[196:197]
	v_pk_add_f32 v[32:33], v[32:33], v[198:199]
	v_pk_add_f32 v[34:35], v[34:35], v[200:201]
	v_cvt_pk_bf16_f32 v160, v36, v37
	v_cvt_pk_bf16_f32 v161, v38, v39
	v_cvt_pk_bf16_f32 v162, v32, v33
	v_cvt_pk_bf16_f32 v163, v34, v35
	global_store_dwordx4 v155, v[160:163], s[52:53] offset:256
	v_fmac_f32_e32 v164, v36, v36
	v_fmac_f32_e32 v164, v37, v37
	v_fmac_f32_e32 v164, v38, v38
	v_fmac_f32_e32 v164, v39, v39
	v_fmac_f32_e32 v164, v32, v32
	v_fmac_f32_e32 v164, v33, v33
	v_fmac_f32_e32 v164, v34, v34
	v_fmac_f32_e32 v164, v35, v35
	ds_bpermute_b32 v165, v157, v164
	s_waitcnt lgkmcnt(0)
; __device__ __forceinline__ unsigned pk2(float a, float b) { f32x2_t v = {a, b}; bf16x2v_t r = __builtin_convertvector(v, bf16x2v_t); return __builtin_bit_cast(unsigned, r); }
;     __device__ __forceinline__ void operator()(const f32x4 (&acc)[2][2][4][2], const Unit& u, int wr, int wc, int fr, int fq) const {
;     ...
;         for (int ai = 0; ai < 2; ++ai)
; #pragma unroll
;             for (int m = 0; m < 4; ++m) { const int row = row0 + ai * HALF + m * 16; const size_t off = (size_t)row * ldc + col0; float s = 0.f;
; #pragma unroll
;                 for (int bj = 0; bj < 2; ++bj) { const size_t o2 = off + bj * HALF;
;                     const f32x4 v0 = *(const f32x4*)(base + o2) + acc[ai][bj][m][0], v1 = *(const f32x4*)(base + o2 + 4) + acc[ai][bj][m][1];
;                     u32x4 w; w.x = pk2(v0[0], v0[1]); w.y = pk2(v0[2], v0[3]); w.z = pk2(v1[0], v1[1]); w.w = pk2(v1[2], v1[3]); *(u32x4*)(xb + o2) = w;
;                     s += ((v0[0] * v0[0] + v0[1] * v0[1]) + (v0[2] * v0[2] + v0[3] * v0[3])) + ((v1[0] * v1[0] + v1[1] * v1[1]) + (v1[2] * v1[2] + v1[3] * v1[3])); }
;                 s += __shfl_xor(s, 16); s += __shfl_xor(s, 32);
;                 if (fq == 0) atomicAdd(rowsq + row, s);
;                 if (m & 1) asm volatile("" ::: "memory"); }
	v_add_f32_e32 v164, v164, v165
	ds_bpermute_b32 v165, v158, v164
	s_waitcnt lgkmcnt(0)
	v_add_f32_e32 v164, v164, v165
	s_and_saveexec_b64 s[22:23], s[54:55]
	global_atomic_add_f32 v156, v164, s[70:71] offset:576
	s_or_b64 exec, exec, s[22:23]
	s_waitcnt vmcnt(13)
	s_add_u32 s52, s46, 0x50000
	s_addc_u32 s53, s47, 0
	v_pk_add_f32 v[28:29], v[28:29], v[202:203]
	v_pk_add_f32 v[30:31], v[30:31], v[204:205]
	v_pk_add_f32 v[24:25], v[24:25], v[206:207]
	v_pk_add_f32 v[26:27], v[26:27], v[208:209]
	v_cvt_pk_bf16_f32 v160, v28, v29
	v_cvt_pk_bf16_f32 v161, v30, v31
	v_cvt_pk_bf16_f32 v162, v24, v25
	v_cvt_pk_bf16_f32 v163, v26, v27
	global_store_dwordx4 v155, v[160:163], s[52:53]
	v_mul_f32_e32 v164, v28, v28
	v_fmac_f32_e32 v164, v29, v29
	v_fmac_f32_e32 v164, v30, v30
	v_fmac_f32_e32 v164, v31, v31
	v_fmac_f32_e32 v164, v24, v24
	v_fmac_f32_e32 v164, v25, v25
	v_fmac_f32_e32 v164, v26, v26
	v_fmac_f32_e32 v164, v27, v27
	v_pk_add_f32 v[20:21], v[20:21], v[210:211]
	v_pk_add_f32 v[22:23], v[22:23], v[212:213]
	v_pk_add_f32 v[16:17], v[16:17], v[214:215]
	v_pk_add_f32 v[18:19], v[18:19], v[216:217]
	v_cvt_pk_bf16_f32 v160, v20, v21
	v_cvt_pk_bf16_f32 v161, v22, v23
	v_cvt_pk_bf16_f32 v162, v16, v17
	v_cvt_pk_bf16_f32 v163, v18, v19
	global_store_dwordx4 v155, v[160:163], s[52:53] offset:256
	v_fmac_f32_e32 v164, v20, v20
	v_fmac_f32_e32 v164, v21, v21
	v_fmac_f32_e32 v164, v22, v22
	v_fmac_f32_e32 v164, v23, v23
	v_fmac_f32_e32 v164, v16, v16
	v_fmac_f32_e32 v164, v17, v17
	v_fmac_f32_e32 v164, v18, v18
	v_fmac_f32_e32 v164, v19, v19
	ds_bpermute_b32 v165, v157, v164
	s_waitcnt lgkmcnt(0)
	v_add_f32_e32 v164, v164, v165
	ds_bpermute_b32 v165, v158, v164
	s_waitcnt lgkmcnt(0)
	v_add_f32_e32 v164, v164, v165
	s_and_saveexec_b64 s[22:23], s[54:55]
	global_atomic_add_f32 v156, v164, s[70:71] offset:640
	s_or_b64 exec, exec, s[22:23]
	s_waitcnt vmcnt(9)
	s_add_u32 s52, s46, 0x58000
	s_addc_u32 s53, s47, 0
	v_pk_add_f32 v[12:13], v[12:13], v[218:219]
	v_pk_add_f32 v[14:15], v[14:15], v[220:221]
	v_pk_add_f32 v[8:9], v[8:9], v[222:223]
	v_pk_add_f32 v[10:11], v[10:11], v[224:225]
	v_cvt_pk_bf16_f32 v160, v12, v13
	v_cvt_pk_bf16_f32 v161, v14, v15
	v_cvt_pk_bf16_f32 v162, v8, v9
	v_cvt_pk_bf16_f32 v163, v10, v11
	global_store_dwordx4 v155, v[160:163], s[52:53]
	v_mul_f32_e32 v164, v12, v12
	v_fmac_f32_e32 v164, v13, v13
	v_fmac_f32_e32 v164, v14, v14
	v_fmac_f32_e32 v164, v15, v15
	v_fmac_f32_e32 v164, v8, v8
	v_fmac_f32_e32 v164, v9, v9
	v_fmac_f32_e32 v164, v10, v10
	v_fmac_f32_e32 v164, v11, v11
	v_pk_add_f32 v[4:5], v[4:5], v[226:227]
	v_pk_add_f32 v[6:7], v[6:7], v[228:229]
	v_pk_add_f32 v[0:1], v[0:1], v[230:231]
	v_pk_add_f32 v[2:3], v[2:3], v[232:233]
	v_cvt_pk_bf16_f32 v160, v4, v5
	v_cvt_pk_bf16_f32 v161, v6, v7
	v_cvt_pk_bf16_f32 v162, v0, v1
	v_cvt_pk_bf16_f32 v163, v2, v3
	global_store_dwordx4 v155, v[160:163], s[52:53] offset:256
	v_fmac_f32_e32 v164, v4, v4
	v_fmac_f32_e32 v164, v5, v5
	v_fmac_f32_e32 v164, v6, v6
	v_fmac_f32_e32 v164, v7, v7
	v_fmac_f32_e32 v164, v0, v0
	v_fmac_f32_e32 v164, v1, v1
	v_fmac_f32_e32 v164, v2, v2
	v_fmac_f32_e32 v164, v3, v3
	ds_bpermute_b32 v165, v157, v164
	s_waitcnt lgkmcnt(0)
	v_add_f32_e32 v164, v164, v165
	ds_bpermute_b32 v165, v158, v164
	s_waitcnt lgkmcnt(0)
	v_add_f32_e32 v164, v164, v165
	s_and_saveexec_b64 s[22:23], s[54:55]
	global_atomic_add_f32 v156, v164, s[70:71] offset:704
	s_or_b64 exec, exec, s[22:23]
	s_andn2_b64 vcc, exec, s[4:5]
	s_mov_b64 s[4:5], -1
	s_cbranch_vccnz .LBB0_624
	s_andn2_b64 vcc, exec, s[0:1]
	s_cbranch_vccnz .LBB0_623
	s_barrier
	s_branch .LBB0_623

; #define PG8_STAGE(bufoff, gbase, voff) do { _Pragma("unroll") for (int _i = 0; _i < 2; ++_i) \
;         __builtin_amdgcn_global_load_lds((const unsigned*)((const char*)(gbase) + (voff)[_i]), (PG8_LAS unsigned*)(lds + (bufoff) + ldsw + _i * 8192), 16, 0, 0); } while (0)
; #define PG8_WAIT_V(n) asm volatile("s_waitcnt vmcnt(" #n ")" ::: "memory")
; #define PG8_BAR __builtin_amdgcn_s_barrier()
; template <class Epi, class Sched, bool ALIGN_EPI = false, bool SP2 = false>
; __device__ __forceinline__ void gemm_phase(PG8_LAS unsigned char* lds, const Gemm g, const Sched& S, const Epi& E) {
;     ...
;         PG8_STAGE(PG8_SB(0, 0), cB, voffB); PG8_STAGE(PG8_SB(0, 1), cB + hstepB, voffB); PG8_STAGE(PG8_SA(0, 0), cA, voffA); PG8_STAGE(PG8_SA(0, 1), cA + hstepA, voffA);
;         if (wr == 1) PG8_BAR;
;         PG8_WAIT_V(2); PG8_BAR;
;         PG8_STAGE(PG8_SB(1, 0), cB + kstep, voffB); PG8_STAGE(PG8_SA(1, 0), cA + kstep, voffA); PG8_STAGE(PG8_SB(1, 1), cB + hstepB + kstep, voffB);
;         PG8_WAIT_V(6); PG8_BAR;
.LBB0_714:
	s_add_u32 s6, s82, 0x7800000
	s_addc_u32 s7, s83, 0
	s_lshl_b32 s2, s2, 5
	s_mov_b64 s[10:11], 0x80
	s_and_b32 s56, s2, 0x60
	s_add_i32 m0, s39, 0x18000
	v_lshl_add_u64 v[6:7], v[6:7], 0, s[10:11]
	s_lshl_b32 s55, s1, 6
	s_lshl_b32 s1, s1, 13
	s_lshl_b32 s9, s56, 7
	s_waitcnt vmcnt(2)
	s_barrier
	global_load_lds_dwordx4 v[6:7], off
	v_lshl_add_u64 v[4:5], v[4:5], 0, s[10:11]
	s_add_i32 m0, s39, 0x1a000
	s_add_i32 s57, s39, 0x8000
	s_add_i32 s58, s39, 0xa000
	global_load_lds_dwordx4 v[4:5], off
	v_lshl_add_u64 v[0:1], v[0:1], 0, s[10:11]
	s_mov_b32 m0, s57
	s_add_u32 s12, s44, 0x40080
	global_load_lds_dwordx4 v[0:1], off
	v_lshl_add_u64 v[0:1], v[2:3], 0, s[10:11]
	s_mov_b32 m0, s58
	s_addc_u32 s13, s45, 0
	global_load_lds_dwordx4 v[0:1], off
	s_add_i32 m0, s39, 0x1c000
	s_nop 0
	global_load_lds_dwordx4 v130, s[12:13]
	v_lshl_add_u64 v[0:1], s[12:13], 0, v[134:135]
	s_add_i32 m0, s39, 0x1e000
	v_bfe_u32 v149, v8, 4, 2
	global_load_lds_dwordx4 v[0:1], off
	v_and_b32_e32 v148, 15, v8
	v_lshlrev_b32_e32 v0, 4, v149
	v_lshlrev_b32_e32 v1, 2, v8
	v_lshl_or_b32 v0, v148, 6, v0
	v_and_b32_e32 v1, 32, v1
	v_bitop3_b32 v2, v0, s1, v1 bitop3:0xde
	v_bitop3_b32 v150, v0, s9, v1 bitop3:0xde
	v_lshlrev_b32_e32 v0, 14, v9
	v_and_b32_e32 v0, 0xffff8000, v0
	v_lshl_add_u32 v0, v10, 11, v0
	v_and_b32_e32 v1, 1, v9
	v_lshl_or_b32 v0, v1, 6, v0
	v_lshl_add_u32 v136, v11, 1, v0
	v_lshlrev_b32_e32 v0, 14, v12
	v_and_b32_e32 v0, 0xffff8000, v0
	s_waitcnt vmcnt(6)
	s_cmpk_lt_u32 s8, 0x100
	v_lshl_add_u32 v0, v13, 11, v0
	v_and_b32_e32 v1, 1, v12
	s_cselect_b64 s[12:13], -1, 0
	v_lshl_or_b32 v0, v1, 6, v0
	s_add_i32 s60, 0, 0x10000
	s_add_i32 s61, 0, 0x14000
	s_sext_i32_i8 s2, s0
	s_ashr_i32 s59, s88, 31
	v_mov_b32_e32 v137, v131
	v_lshl_add_u32 v138, v14, 1, v0
	v_mov_b32_e32 v139, v131
	v_mov_b64_e32 v[140:141], 0x100
	v_mov_b64_e32 v[142:143], 0xff
	v_add_u32_e32 v151, s60, v150
	v_add_u32_e32 v152, s61, v150
	v_add_u32_e32 v153, 0, v2
	v_mov_b32_e32 v154, 0x358637bd
	s_mov_b64 s[14:15], 0x4000
	s_mov_b64 s[16:17], 0x8000
	s_mov_b64 s[18:19], 0xc000
	s_mov_b64 s[20:21], 0x20000
	s_mov_b64 s[22:23], 0x24000
	s_mov_b64 s[24:25], 0x28000
	s_mov_b64 s[26:27], 0x2c000
	s_barrier
	s_branch .LBB0_717

; #define PG8_STAGE(bufoff, gbase, voff) do { _Pragma("unroll") for (int _i = 0; _i < 2; ++_i) \
;         __builtin_amdgcn_global_load_lds((const unsigned*)((const char*)(gbase) + (voff)[_i]), (PG8_LAS unsigned*)(lds + (bufoff) + ldsw + _i * 8192), 16, 0, 0); } while (0)
; #define PG8_LDA(dst, b, h) do { _Pragma("unroll") for (int m = 0; m < 4; ++m) _Pragma("unroll") for (int k = 0; k < 2; ++k) dst[m][k] = *(const PG8_LAS bf16x8*)(lds + PG8_SA(b, h) + aoff + m * 2048 + k * 1024); } while (0)
; #define PG8_LDB(dst, b, h) do { _Pragma("unroll") for (int n = 0; n < 2; ++n) _Pragma("unroll") for (int k = 0; k < 2; ++k) dst[n][k] = *(const PG8_LAS bf16x8*)(lds + PG8_SB(b, h) + boff + n * 2048 + k * 1024); } while (0)
; #define PG8_MMA(ai, bj, At, Bt) do { __builtin_amdgcn_s_setprio(1); _Pragma("unroll") for (int m = 0; m < 4; ++m) _Pragma("unroll") for (int n = 0; n < 2; ++n) _Pragma("unroll") for (int k = 0; k < 2; ++k) \
;         acc[ai][bj][m][n] = __builtin_amdgcn_mfma_f32_16x16x32_bf16(Bt[n][k], At[m][k], acc[ai][bj][m][n], 0, 0, 0); __builtin_amdgcn_s_setprio(0); } while (0)
; #define PG8_WAIT_V(n) asm volatile("s_waitcnt vmcnt(" #n ")" ::: "memory")
; #define PG8_WAIT_L(n) asm volatile("s_waitcnt lgkmcnt(" #n ")" ::: "memory")
; #define PG8_BAR __builtin_amdgcn_s_barrier()
; #define PG8_SCHED __builtin_amdgcn_sched_barrier(0)
; template <class Epi, class Sched, bool ALIGN_EPI = false, bool SP2 = false>
; __device__ __forceinline__ void gemm_phase(PG8_LAS unsigned char* lds, const Gemm g, const Sched& S, const Epi& E) {
;     ...
;             PG8_LDB(B0, 0, 0); PG8_LDB(B1, 0, 1); PG8_SCHED; PG8_LDA(At, 0, 0); PG8_STAGE(PG8_SA(1, 1), a1 + hstepA, voffA);
;             PG8_WAIT_V(8); PG8_WAIT_L(0); PG8_BAR; PG8_MMA(0, 0, At, B0); PG8_MMA(0, 1, At, B1); PG8_BAR; PG8_SCHED;
;             PG8_LDA(At, 0, 1); PG8_STAGE(PG8_SB(0, 0), b2, voffB); PG8_STAGE(PG8_SB(0, 1), b2 + hstepB, voffB); PG8_STAGE(PG8_SA(0, 0), a2, voffA);
;             PG8_WAIT_V(8); PG8_WAIT_L(0); PG8_BAR; PG8_MMA(1, 0, At, B0); PG8_MMA(1, 1, At, B1); PG8_BAR; PG8_SCHED;
.LBB0_724:
	ds_read_b128 v[144:147], v151
	ds_read_b128 v[156:159], v151 offset:1024
	ds_read_b128 v[160:163], v151 offset:2048
	ds_read_b128 v[164:167], v151 offset:3072
	ds_read_b128 v[168:171], v152
	ds_read_b128 v[172:175], v152 offset:1024
	ds_read_b128 v[176:179], v152 offset:2048
	ds_read_b128 v[180:183], v152 offset:3072
	s_add_u32 s44, s40, 0xfffc0080
	s_addc_u32 s45, s41, -1
	s_cmp_eq_u32 s63, 12
	s_cselect_b32 s49, s8, s45
	s_cselect_b32 s48, s9, s44
	s_cselect_b32 s45, s29, s62
	s_cselect_b32 s44, s31, s42
	s_add_i32 m0, s39, 0xc000
	ds_read_b128 v[184:187], v153
	ds_read_b128 v[188:191], v153 offset:1024
	ds_read_b128 v[194:197], v153 offset:2048
	ds_read_b128 v[198:201], v153 offset:3072
	ds_read_b128 v[202:205], v153 offset:4096
	ds_read_b128 v[206:209], v153 offset:5120
	ds_read_b128 v[210:213], v153 offset:6144
	ds_read_b128 v[214:217], v153 offset:7168
	global_load_lds_dwordx4 v136, s[40:41]
	s_add_i32 m0, s39, 0xe000
	s_nop 0
	global_load_lds_dwordx4 v138, s[40:41]
	s_waitcnt vmcnt(8)
	s_waitcnt lgkmcnt(0)
	s_barrier
	s_setprio 1
	s_waitcnt lgkmcnt(0)
	v_mfma_f32_16x16x32_bf16 v[124:127], v[144:147], v[184:187], v[124:127]
	v_mfma_f32_16x16x32_bf16 v[120:123], v[160:163], v[184:187], v[120:123]
	v_mfma_f32_16x16x32_bf16 v[108:111], v[144:147], v[194:197], v[108:111]
	v_mfma_f32_16x16x32_bf16 v[104:107], v[160:163], v[194:197], v[104:107]
	v_mfma_f32_16x16x32_bf16 v[92:95], v[144:147], v[202:205], v[92:95]
	v_mfma_f32_16x16x32_bf16 v[88:91], v[160:163], v[202:205], v[88:91]
	v_mfma_f32_16x16x32_bf16 v[76:79], v[144:147], v[210:213], v[76:79]
	v_mfma_f32_16x16x32_bf16 v[72:75], v[160:163], v[210:213], v[72:75]
	v_mfma_f32_16x16x32_bf16 v[124:127], v[156:159], v[188:191], v[124:127]
	v_mfma_f32_16x16x32_bf16 v[120:123], v[164:167], v[188:191], v[120:123]
	v_mfma_f32_16x16x32_bf16 v[108:111], v[156:159], v[198:201], v[108:111]
	v_mfma_f32_16x16x32_bf16 v[104:107], v[164:167], v[198:201], v[104:107]
	v_mfma_f32_16x16x32_bf16 v[92:95], v[156:159], v[206:209], v[92:95]
	v_mfma_f32_16x16x32_bf16 v[88:91], v[164:167], v[206:209], v[88:91]
	v_mfma_f32_16x16x32_bf16 v[76:79], v[156:159], v[214:217], v[76:79]
	v_mfma_f32_16x16x32_bf16 v[72:75], v[164:167], v[214:217], v[72:75]
	s_setprio 0
	s_setprio 1
	v_mfma_f32_16x16x32_bf16 v[116:119], v[168:171], v[184:187], v[116:119]
	v_mfma_f32_16x16x32_bf16 v[112:115], v[176:179], v[184:187], v[112:115]
	v_mfma_f32_16x16x32_bf16 v[100:103], v[168:171], v[194:197], v[100:103]
	v_mfma_f32_16x16x32_bf16 v[96:99], v[176:179], v[194:197], v[96:99]
	v_mfma_f32_16x16x32_bf16 v[84:87], v[168:171], v[202:205], v[84:87]
	v_mfma_f32_16x16x32_bf16 v[80:83], v[176:179], v[202:205], v[80:83]
	v_mfma_f32_16x16x32_bf16 v[68:71], v[168:171], v[210:213], v[68:71]
	v_mfma_f32_16x16x32_bf16 v[64:67], v[176:179], v[210:213], v[64:67]
	v_mfma_f32_16x16x32_bf16 v[116:119], v[172:175], v[188:191], v[116:119]
	v_mfma_f32_16x16x32_bf16 v[112:115], v[180:183], v[188:191], v[112:115]
	v_mfma_f32_16x16x32_bf16 v[100:103], v[172:175], v[198:201], v[100:103]
	v_mfma_f32_16x16x32_bf16 v[96:99], v[180:183], v[198:201], v[96:99]
	v_mfma_f32_16x16x32_bf16 v[84:87], v[172:175], v[206:209], v[84:87]
	v_mfma_f32_16x16x32_bf16 v[80:83], v[180:183], v[206:209], v[80:83]
	v_mfma_f32_16x16x32_bf16 v[68:71], v[172:175], v[214:217], v[68:71]
	v_mfma_f32_16x16x32_bf16 v[64:67], v[180:183], v[214:217], v[64:67]
	s_setprio 0
	s_barrier
	s_add_i32 s64, s60, s50
	v_lshl_add_u64 v[192:193], s[44:45], 0, v[130:131]
	s_mov_b32 m0, s64
	ds_read_b128 v[184:187], v153 offset:16384
	ds_read_b128 v[188:191], v153 offset:17408
	ds_read_b128 v[194:197], v153 offset:18432
	ds_read_b128 v[198:201], v153 offset:19456
	ds_read_b128 v[202:205], v153 offset:20480
	ds_read_b128 v[206:209], v153 offset:21504
	ds_read_b128 v[210:213], v153 offset:22528
	ds_read_b128 v[214:217], v153 offset:23552
	global_load_lds_dwordx4 v[192:193], off
	s_add_i32 m0, s64, 0x2000
	s_add_u32 s64, s44, 0x40000
	v_lshl_add_u64 v[218:219], s[44:45], 0, v[134:135]
	s_addc_u32 s65, s45, 0
	s_add_i32 s66, s61, s50
	global_load_lds_dwordx4 v[218:219], off
	s_mov_b32 m0, s66
	v_lshl_add_u64 v[222:223], s[48:49], 0, v[132:133]
	global_load_lds_dwordx4 v130, s[64:65]
	s_add_i32 m0, s66, 0x2000
	s_nop 0
	global_load_lds_dwordx4 v134, s[64:65]
	v_lshl_add_u64 v[220:221], s[48:49], 0, v[128:129]
	s_mov_b32 m0, s39
	s_nop 0
	global_load_lds_dwordx4 v[220:221], off
	s_mov_b32 m0, s51
	s_nop 0
	global_load_lds_dwordx4 v[222:223], off
	s_waitcnt vmcnt(8)
	s_waitcnt lgkmcnt(0)
	s_barrier
; #define PG8_STAGE(bufoff, gbase, voff) do { _Pragma("unroll") for (int _i = 0; _i < 2; ++_i) \
;         __builtin_amdgcn_global_load_lds((const unsigned*)((const char*)(gbase) + (voff)[_i]), (PG8_LAS unsigned*)(lds + (bufoff) + ldsw + _i * 8192), 16, 0, 0); } while (0)
; #define PG8_LDA(dst, b, h) do { _Pragma("unroll") for (int m = 0; m < 4; ++m) _Pragma("unroll") for (int k = 0; k < 2; ++k) dst[m][k] = *(const PG8_LAS bf16x8*)(lds + PG8_SA(b, h) + aoff + m * 2048 + k * 1024); } while (0)
; #define PG8_LDB(dst, b, h) do { _Pragma("unroll") for (int n = 0; n < 2; ++n) _Pragma("unroll") for (int k = 0; k < 2; ++k) dst[n][k] = *(const PG8_LAS bf16x8*)(lds + PG8_SB(b, h) + boff + n * 2048 + k * 1024); } while (0)
; #define PG8_MMA(ai, bj, At, Bt) do { __builtin_amdgcn_s_setprio(1); _Pragma("unroll") for (int m = 0; m < 4; ++m) _Pragma("unroll") for (int n = 0; n < 2; ++n) _Pragma("unroll") for (int k = 0; k < 2; ++k) \
;         acc[ai][bj][m][n] = __builtin_amdgcn_mfma_f32_16x16x32_bf16(Bt[n][k], At[m][k], acc[ai][bj][m][n], 0, 0, 0); __builtin_amdgcn_s_setprio(0); } while (0)
; #define PG8_WAIT_V(n) asm volatile("s_waitcnt vmcnt(" #n ")" ::: "memory")
; #define PG8_WAIT_L(n) asm volatile("s_waitcnt lgkmcnt(" #n ")" ::: "memory")
; #define PG8_BAR __builtin_amdgcn_s_barrier()
; #define PG8_SCHED __builtin_amdgcn_sched_barrier(0)
; template <class Epi, class Sched, bool ALIGN_EPI = false, bool SP2 = false>
; __device__ __forceinline__ void gemm_phase(PG8_LAS unsigned char* lds, const Gemm g, const Sched& S, const Epi& E) {
;     ...
;             PG8_WAIT_V(8); PG8_WAIT_L(0); PG8_BAR; PG8_MMA(1, 0, At, B0); PG8_MMA(1, 1, At, B1); PG8_BAR; PG8_SCHED;
;             PG8_LDB(B0, 1, 0); PG8_LDB(B1, 1, 1); PG8_SCHED; PG8_LDA(At, 1, 0); PG8_STAGE(PG8_SA(0, 1), a2 + hstepA, voffA);
;             PG8_WAIT_V(8); PG8_WAIT_L(0); PG8_BAR; PG8_MMA(0, 0, At, B0); PG8_MMA(0, 1, At, B1); PG8_BAR; PG8_SCHED;
;             PG8_LDA(At, 1, 1); PG8_STAGE(PG8_SB(1, 0), b3, voffB); PG8_STAGE(PG8_SB(1, 1), b3 + hstepB, voffB); PG8_STAGE(PG8_SA(1, 0), a3, voffA);
	s_setprio 1
	s_waitcnt lgkmcnt(0)
	v_mfma_f32_16x16x32_bf16 v[60:63], v[144:147], v[184:187], v[60:63]
	v_mfma_f32_16x16x32_bf16 v[56:59], v[160:163], v[184:187], v[56:59]
	v_mfma_f32_16x16x32_bf16 v[44:47], v[144:147], v[194:197], v[44:47]
	v_mfma_f32_16x16x32_bf16 v[40:43], v[160:163], v[194:197], v[40:43]
	v_mfma_f32_16x16x32_bf16 v[28:31], v[144:147], v[202:205], v[28:31]
	v_mfma_f32_16x16x32_bf16 v[24:27], v[160:163], v[202:205], v[24:27]
	v_mfma_f32_16x16x32_bf16 v[12:15], v[144:147], v[210:213], v[12:15]
	v_mfma_f32_16x16x32_bf16 v[8:11], v[160:163], v[210:213], v[8:11]
	v_mfma_f32_16x16x32_bf16 v[60:63], v[156:159], v[188:191], v[60:63]
	v_mfma_f32_16x16x32_bf16 v[56:59], v[164:167], v[188:191], v[56:59]
	v_mfma_f32_16x16x32_bf16 v[44:47], v[156:159], v[198:201], v[44:47]
	v_mfma_f32_16x16x32_bf16 v[40:43], v[164:167], v[198:201], v[40:43]
	v_mfma_f32_16x16x32_bf16 v[28:31], v[156:159], v[206:209], v[28:31]
	v_mfma_f32_16x16x32_bf16 v[24:27], v[164:167], v[206:209], v[24:27]
	v_mfma_f32_16x16x32_bf16 v[12:15], v[156:159], v[214:217], v[12:15]
	v_mfma_f32_16x16x32_bf16 v[8:11], v[164:167], v[214:217], v[8:11]
	s_setprio 0
	s_setprio 1
	v_mfma_f32_16x16x32_bf16 v[52:55], v[168:171], v[184:187], v[52:55]
	v_mfma_f32_16x16x32_bf16 v[48:51], v[176:179], v[184:187], v[48:51]
	v_mfma_f32_16x16x32_bf16 v[36:39], v[168:171], v[194:197], v[36:39]
	v_mfma_f32_16x16x32_bf16 v[32:35], v[176:179], v[194:197], v[32:35]
	v_mfma_f32_16x16x32_bf16 v[20:23], v[168:171], v[202:205], v[20:23]
	v_mfma_f32_16x16x32_bf16 v[16:19], v[176:179], v[202:205], v[16:19]
	v_mfma_f32_16x16x32_bf16 v[4:7], v[168:171], v[210:213], v[4:7]
	v_mfma_f32_16x16x32_bf16 v[0:3], v[176:179], v[210:213], v[0:3]
	v_mfma_f32_16x16x32_bf16 v[52:55], v[172:175], v[188:191], v[52:55]
	v_mfma_f32_16x16x32_bf16 v[48:51], v[180:183], v[188:191], v[48:51]
	v_mfma_f32_16x16x32_bf16 v[36:39], v[172:175], v[198:201], v[36:39]
	v_mfma_f32_16x16x32_bf16 v[32:35], v[180:183], v[198:201], v[32:35]
	v_mfma_f32_16x16x32_bf16 v[20:23], v[172:175], v[206:209], v[20:23]
	v_mfma_f32_16x16x32_bf16 v[16:19], v[180:183], v[206:209], v[16:19]
	v_mfma_f32_16x16x32_bf16 v[4:7], v[172:175], v[214:217], v[4:7]
	v_mfma_f32_16x16x32_bf16 v[0:3], v[180:183], v[214:217], v[0:3]
	s_setprio 0
	s_barrier
	s_add_i32 s64, 0, 0x18000
	v_add_u32_e32 v155, s64, v150
	s_add_i32 s65, 0, 0x1c000
	ds_read_b128 v[144:147], v155
	ds_read_b128 v[156:159], v155 offset:1024
	ds_read_b128 v[160:163], v155 offset:2048
	ds_read_b128 v[164:167], v155 offset:3072
	v_add_u32_e32 v155, s65, v150
	ds_read_b128 v[168:171], v155
	ds_read_b128 v[172:175], v155 offset:1024
	ds_read_b128 v[176:179], v155 offset:2048
	ds_read_b128 v[180:183], v155 offset:3072
	s_add_u32 s48, s48, 0x40000
	s_addc_u32 s49, s49, 0
	s_mov_b32 m0, s52
	ds_read_b128 v[184:187], v153 offset:32768
	ds_read_b128 v[188:191], v153 offset:33792
	ds_read_b128 v[194:197], v153 offset:34816
	ds_read_b128 v[198:201], v153 offset:35840
	ds_read_b128 v[202:205], v153 offset:36864
	ds_read_b128 v[206:209], v153 offset:37888
	ds_read_b128 v[210:213], v153 offset:38912
	ds_read_b128 v[214:217], v153 offset:39936
	global_load_lds_dwordx4 v128, s[48:49]
	s_mov_b32 m0, s53
	s_nop 0
	global_load_lds_dwordx4 v132, s[48:49]
	s_waitcnt vmcnt(8)
	s_waitcnt lgkmcnt(0)
	s_barrier
	s_setprio 1
	s_waitcnt lgkmcnt(0)
	v_mfma_f32_16x16x32_bf16 v[124:127], v[144:147], v[184:187], v[124:127]
	v_mfma_f32_16x16x32_bf16 v[120:123], v[160:163], v[184:187], v[120:123]
	v_mfma_f32_16x16x32_bf16 v[108:111], v[144:147], v[194:197], v[108:111]
	v_mfma_f32_16x16x32_bf16 v[104:107], v[160:163], v[194:197], v[104:107]
	v_mfma_f32_16x16x32_bf16 v[92:95], v[144:147], v[202:205], v[92:95]
	v_mfma_f32_16x16x32_bf16 v[88:91], v[160:163], v[202:205], v[88:91]
	v_mfma_f32_16x16x32_bf16 v[76:79], v[144:147], v[210:213], v[76:79]
	v_mfma_f32_16x16x32_bf16 v[72:75], v[160:163], v[210:213], v[72:75]
	v_mfma_f32_16x16x32_bf16 v[124:127], v[156:159], v[188:191], v[124:127]
	v_mfma_f32_16x16x32_bf16 v[120:123], v[164:167], v[188:191], v[120:123]
	v_mfma_f32_16x16x32_bf16 v[108:111], v[156:159], v[198:201], v[108:111]
	v_mfma_f32_16x16x32_bf16 v[104:107], v[164:167], v[198:201], v[104:107]
	v_mfma_f32_16x16x32_bf16 v[92:95], v[156:159], v[206:209], v[92:95]
	v_mfma_f32_16x16x32_bf16 v[88:91], v[164:167], v[206:209], v[88:91]
	v_mfma_f32_16x16x32_bf16 v[76:79], v[156:159], v[214:217], v[76:79]
	v_mfma_f32_16x16x32_bf16 v[72:75], v[164:167], v[214:217], v[72:75]
	s_setprio 0
	s_setprio 1
	v_mfma_f32_16x16x32_bf16 v[116:119], v[168:171], v[184:187], v[116:119]
	v_mfma_f32_16x16x32_bf16 v[112:115], v[176:179], v[184:187], v[112:115]
	v_mfma_f32_16x16x32_bf16 v[100:103], v[168:171], v[194:197], v[100:103]
	v_mfma_f32_16x16x32_bf16 v[96:99], v[176:179], v[194:197], v[96:99]
	v_mfma_f32_16x16x32_bf16 v[84:87], v[168:171], v[202:205], v[84:87]
	v_mfma_f32_16x16x32_bf16 v[80:83], v[176:179], v[202:205], v[80:83]
	v_mfma_f32_16x16x32_bf16 v[68:71], v[168:171], v[210:213], v[68:71]
	v_mfma_f32_16x16x32_bf16 v[64:67], v[176:179], v[210:213], v[64:67]
	v_mfma_f32_16x16x32_bf16 v[116:119], v[172:175], v[188:191], v[116:119]
	v_mfma_f32_16x16x32_bf16 v[112:115], v[180:183], v[188:191], v[112:115]
	v_mfma_f32_16x16x32_bf16 v[100:103], v[172:175], v[198:201], v[100:103]
	v_mfma_f32_16x16x32_bf16 v[96:99], v[180:183], v[198:201], v[96:99]
	v_mfma_f32_16x16x32_bf16 v[84:87], v[172:175], v[206:209], v[84:87]
	v_mfma_f32_16x16x32_bf16 v[80:83], v[180:183], v[206:209], v[80:83]
	v_mfma_f32_16x16x32_bf16 v[68:71], v[172:175], v[214:217], v[68:71]
	v_mfma_f32_16x16x32_bf16 v[64:67], v[180:183], v[214:217], v[64:67]
	s_setprio 0
	s_barrier
; #define PG8_STAGE(bufoff, gbase, voff) do { _Pragma("unroll") for (int _i = 0; _i < 2; ++_i) \
;         __builtin_amdgcn_global_load_lds((const unsigned*)((const char*)(gbase) + (voff)[_i]), (PG8_LAS unsigned*)(lds + (bufoff) + ldsw + _i * 8192), 16, 0, 0); } while (0)
; #define PG8_LDA(dst, b, h) do { _Pragma("unroll") for (int m = 0; m < 4; ++m) _Pragma("unroll") for (int k = 0; k < 2; ++k) dst[m][k] = *(const PG8_LAS bf16x8*)(lds + PG8_SA(b, h) + aoff + m * 2048 + k * 1024); } while (0)
; #define PG8_MMA(ai, bj, At, Bt) do { __builtin_amdgcn_s_setprio(1); _Pragma("unroll") for (int m = 0; m < 4; ++m) _Pragma("unroll") for (int n = 0; n < 2; ++n) _Pragma("unroll") for (int k = 0; k < 2; ++k) \
;         acc[ai][bj][m][n] = __builtin_amdgcn_mfma_f32_16x16x32_bf16(Bt[n][k], At[m][k], acc[ai][bj][m][n], 0, 0, 0); __builtin_amdgcn_s_setprio(0); } while (0)
; #define PG8_WAIT_V(n) asm volatile("s_waitcnt vmcnt(" #n ")" ::: "memory")
; #define PG8_WAIT_L(n) asm volatile("s_waitcnt lgkmcnt(" #n ")" ::: "memory")
; #define PG8_BAR __builtin_amdgcn_s_barrier()
; #define PG8_SCHED __builtin_amdgcn_sched_barrier(0)
; template <class Epi, class Sched, bool ALIGN_EPI = false, bool SP2 = false>
; __device__ __forceinline__ void gemm_phase(PG8_LAS unsigned char* lds, const Gemm g, const Sched& S, const Epi& E) {
;     ...
;             PG8_WAIT_V(8); PG8_WAIT_L(0); PG8_BAR; PG8_MMA(0, 0, At, B0); PG8_MMA(0, 1, At, B1); PG8_BAR; PG8_SCHED;
;             PG8_LDA(At, 1, 1); PG8_STAGE(PG8_SB(1, 0), b3, voffB); PG8_STAGE(PG8_SB(1, 1), b3 + hstepB, voffB); PG8_STAGE(PG8_SA(1, 0), a3, voffA);
;             PG8_WAIT_V(8); PG8_WAIT_L(0); PG8_BAR; PG8_MMA(1, 0, At, B0); PG8_MMA(1, 1, At, B1); PG8_BAR; PG8_SCHED;
	s_add_i32 s48, s64, s50
	v_lshl_add_u64 v[192:193], v[192:193], 0, s[10:11]
	s_mov_b32 m0, s48
	ds_read_b128 v[184:187], v153 offset:49152
	ds_read_b128 v[188:191], v153 offset:50176
	ds_read_b128 v[194:197], v153 offset:51200
	ds_read_b128 v[198:201], v153 offset:52224
	ds_read_b128 v[202:205], v153 offset:53248
	ds_read_b128 v[206:209], v153 offset:54272
	ds_read_b128 v[210:213], v153 offset:55296
	ds_read_b128 v[214:217], v153 offset:56320
	global_load_lds_dwordx4 v[192:193], off
	s_add_i32 m0, s48, 0x2000
	s_add_u32 s44, s44, 0x40080
	v_lshl_add_u64 v[192:193], v[218:219], 0, s[10:11]
	s_addc_u32 s45, s45, 0
	s_add_i32 s48, s65, s50
	global_load_lds_dwordx4 v[192:193], off
	s_mov_b32 m0, s48
	s_nop 0
	global_load_lds_dwordx4 v130, s[44:45]
	s_add_i32 m0, s48, 0x2000
	s_nop 0
	global_load_lds_dwordx4 v134, s[44:45]
	v_lshl_add_u64 v[192:193], v[220:221], 0, s[10:11]
	s_mov_b32 m0, s57
	s_nop 0
	global_load_lds_dwordx4 v[192:193], off
	v_lshl_add_u64 v[192:193], v[222:223], 0, s[10:11]
	s_mov_b32 m0, s58
	s_nop 0
	global_load_lds_dwordx4 v[192:193], off
	s_waitcnt vmcnt(8)
	s_waitcnt lgkmcnt(0)
	s_barrier
	s_setprio 1
	s_waitcnt lgkmcnt(0)
	v_mfma_f32_16x16x32_bf16 v[60:63], v[144:147], v[184:187], v[60:63]
	v_mfma_f32_16x16x32_bf16 v[56:59], v[160:163], v[184:187], v[56:59]
	v_mfma_f32_16x16x32_bf16 v[44:47], v[144:147], v[194:197], v[44:47]
	v_mfma_f32_16x16x32_bf16 v[40:43], v[160:163], v[194:197], v[40:43]
	v_mfma_f32_16x16x32_bf16 v[28:31], v[144:147], v[202:205], v[28:31]
	v_mfma_f32_16x16x32_bf16 v[24:27], v[160:163], v[202:205], v[24:27]
	v_mfma_f32_16x16x32_bf16 v[12:15], v[144:147], v[210:213], v[12:15]
	v_mfma_f32_16x16x32_bf16 v[8:11], v[160:163], v[210:213], v[8:11]
	v_mfma_f32_16x16x32_bf16 v[60:63], v[156:159], v[188:191], v[60:63]
	v_mfma_f32_16x16x32_bf16 v[56:59], v[164:167], v[188:191], v[56:59]
	v_mfma_f32_16x16x32_bf16 v[44:47], v[156:159], v[198:201], v[44:47]
	v_mfma_f32_16x16x32_bf16 v[40:43], v[164:167], v[198:201], v[40:43]
	v_mfma_f32_16x16x32_bf16 v[28:31], v[156:159], v[206:209], v[28:31]
	v_mfma_f32_16x16x32_bf16 v[24:27], v[164:167], v[206:209], v[24:27]
	v_mfma_f32_16x16x32_bf16 v[12:15], v[156:159], v[214:217], v[12:15]
	v_mfma_f32_16x16x32_bf16 v[8:11], v[164:167], v[214:217], v[8:11]
	s_setprio 0
	s_setprio 1
	v_mfma_f32_16x16x32_bf16 v[52:55], v[168:171], v[184:187], v[52:55]
	v_mfma_f32_16x16x32_bf16 v[48:51], v[176:179], v[184:187], v[48:51]
	v_mfma_f32_16x16x32_bf16 v[36:39], v[168:171], v[194:197], v[36:39]
	v_mfma_f32_16x16x32_bf16 v[32:35], v[176:179], v[194:197], v[32:35]
	v_mfma_f32_16x16x32_bf16 v[20:23], v[168:171], v[202:205], v[20:23]
	v_mfma_f32_16x16x32_bf16 v[16:19], v[176:179], v[202:205], v[16:19]
	v_mfma_f32_16x16x32_bf16 v[4:7], v[168:171], v[210:213], v[4:7]
	v_mfma_f32_16x16x32_bf16 v[0:3], v[176:179], v[210:213], v[0:3]
	v_mfma_f32_16x16x32_bf16 v[52:55], v[172:175], v[188:191], v[52:55]
	v_mfma_f32_16x16x32_bf16 v[48:51], v[180:183], v[188:191], v[48:51]
	v_mfma_f32_16x16x32_bf16 v[36:39], v[172:175], v[198:201], v[36:39]
	v_mfma_f32_16x16x32_bf16 v[32:35], v[180:183], v[198:201], v[32:35]
	v_mfma_f32_16x16x32_bf16 v[20:23], v[172:175], v[206:209], v[20:23]
	v_mfma_f32_16x16x32_bf16 v[16:19], v[180:183], v[206:209], v[16:19]
	v_mfma_f32_16x16x32_bf16 v[4:7], v[172:175], v[214:217], v[4:7]
	v_mfma_f32_16x16x32_bf16 v[0:3], v[180:183], v[214:217], v[0:3]
	s_setprio 0
	s_barrier
	s_add_i32 s63, s63, 2
	s_add_u32 s40, s40, 0x100
	s_addc_u32 s41, s41, 0
	s_add_u32 s42, s42, 0x100
	s_addc_u32 s62, s62, 0
	s_cmp_gt_u32 s63, 13
	s_cbranch_scc0 .LBB0_724
	s_and_b64 vcc, exec, s[12:13]
	s_cbranch_vccz .LBB0_727
	s_barrier
